# v17 recipe + radix-16 butterflies with multiplications folded into the first adds (a = u0 + u2 W as two fmas, c = 2 u0 - a as one; s100 = 2.0)
# speedup vs baseline: 1.0174x; 1.0003x over previous
; #define GAS __attribute__((address_space(1)))
;     __device__ __forceinline__ bool next(int i, Unit& u) const {
;         const long L = (long)i * G + c; if (L >= nsub) return false;
;         const int j = (int)L / ksplit; u.type = (int)L % ksplit; u.pm = pm0 + j / nN; u.pn = j % nN; return true;
;     }
; __global__ void __launch_bounds__(NTHR, 2) fwd_kernel(Args args) {
;     ...
;             { TP_BEGIN(40) { STAGGER(STAG_P4); pg8::SchedRound S{0, (int)blockIdx.x, Ab, Bb, (size_t)256 * DM * 2}; pg8::gemm_phase<EpiResNorm<0>, pg8::SchedRound, true, true>(ring, DM, DM, S, E, opaque_int(wave0)); __syncthreads(); } TP_END(40) }
;     ...
;             if (uc) {
;                 pg8::SchedK SK; SK.nsub = 16 * 4; SK.nN = 8; SK.ksplit = 4; SK.pm0 = PML; SK.G = F.G; SK.c = (int)blockIdx.x; SK.A = Ab; SK.B = Bb; SK.tstep = (size_t)256 * DM * 2; SK.kbytes = 512 * 2;
;                 EpiSlab EA{WSP(float, WS_SLAB), MODL + 2 * DM};
;     ...
;                 { TP_BEGIN(41) pg8::gemm_phase<EpiSlab, pg8::SchedK, true, true>(ring, DM, 512, SK, EA, opaque_int(wave0)); TP_END(41) }
;     ...
;             }
;         }
;         GRID_BAR();
;         TP_END(4) }
;         { TP_BEGIN(5)
;         if (uc) {
;     ...
;             REFRESH(F); norm_phase(F, l, 1, true, 4, ML);
;     ...
;             GRID_BAR();
;         }
;         TP_END(5) }
;         { TP_BEGIN(6)
;         {
;             pg8::Sched2 S; S.n1 = npm * 44; S.nM1 = npm; S.nN1 = 44; S.n2 = 0; S.nM2 = 1; S.nN2 = 1; S.G = F.G; S.c = (int)blockIdx.x;
;             S.A1 = (const char*)WSP(bf16, WS_H); S.B1 = (const char*)(WSP(bf16, WS_WUP) + (size_t)l * 2 * DFF * DM); S.A2 = S.A1; S.B2 = S.B1; S.tstep = (size_t)256 * DM * 2;
;             GAS float* EG = WSP(float, WS_EDGE);
;             EpiUp E{WSP(bf16, WS_HID), EG, EG + EDGE_ELEMS, EG + 2 * EDGE_ELEMS, IN(ffn_conv_w) + (size_t)l * 3 * DFF, IN(ffn_conv_b) + (size_t)l * DFF};
;     ...
;             for (int rep = 0, nrep = opaque_int(REP_P6); rep < nrep; ++rep) { pg8::gemm_phase<EpiUp, pg8::Sched2, true, true>(ring, DM, DM, S, E, opaque_int(wave0)); __syncthreads();
;     ...
;                 if (rep + 1 < nrep) GRID_BAR();
;     ...
;             }
;     ...
;         }
;         GRID_BAR();
;         TP_END(6) }
;         { TP_BEGIN(7)
;     ...
;         for (int rep = 0, nrep = opaque_int(REP_EDGE); rep < nrep; ++rep) { REFRESH(F); edge_fix_phase(F, l, uc); }
;     ...
;         GRID_BAR();
;         TP_END(7) }
;         { TP_BEGIN(8)
;         {
.LBB0_140:
	v_writelane_b32 v254, s86, 11
	s_andn2_b32 s0, s0, 63
	s_lshl_b32 s2, s88, 3
	v_writelane_b32 v254, s87, 12
	v_writelane_b32 v254, s0, 13
	s_lshl_b32 s4, s93, 3
	s_add_i32 s0, s2, 0x8000
	s_cmpk_lt_i32 s92, 0x410
	v_writelane_b32 v254, s0, 14
	s_cselect_b64 s[0:1], -1, 0
	v_writelane_b32 v254, s0, 15
	s_cmpk_gt_i32 s92, 0x40f
	v_mov_b32_e32 v177, 0
	v_writelane_b32 v254, s1, 16
	s_cselect_b64 s[0:1], -1, 0
	v_writelane_b32 v254, s0, 17
	s_cmpk_lt_u32 s92, 0xa28
	v_mov_b32_e32 v212, 0x358637bd
	v_writelane_b32 v254, s1, 18
	s_cselect_b64 s[0:1], -1, 0
	v_writelane_b32 v254, s0, 19
	s_ashr_i32 s3, s92, 31
	s_ashr_i32 s57, s93, 31
	v_writelane_b32 v254, s1, 20
	s_and_b32 s0, s92, 7
	s_mulk_i32 s0, 0xc3
	v_writelane_b32 v254, s0, 21
	s_lshr_b32 s0, s3, 29
	s_add_i32 s0, s92, s0
	s_ashr_i32 s1, s0, 3
	s_and_b32 s0, s0, -8
	s_sub_i32 s5, s92, s0
	s_cmpk_lt_i32 s88, 0x100
	v_writelane_b32 v254, s1, 22
	s_cselect_b64 s[0:1], -1, 0
	v_writelane_b32 v254, s0, 23
	s_cmpk_lt_i32 s88, 0x200
	v_mov_b32_e32 v213, 0x260
	v_writelane_b32 v254, s1, 24
	s_cselect_b64 s[0:1], -1, 0
	v_writelane_b32 v254, s0, 25
	s_ashr_i32 s89, s88, 31
	s_bfe_u32 s9, s92, 0x30003
	v_writelane_b32 v254, s1, 26
	s_lshl_b64 s[0:1], s[88:89], 18
	v_writelane_b32 v254, s0, 27
	v_mov_b32_e32 v214, 0x3c0881c4
	v_mov_b32_e32 v215, 0xbab64f3b
	v_writelane_b32 v254, s1, 28
	s_lshl_b32 s0, s92, 2
	s_and_b32 s0, s0, 28
	s_ashr_i32 s1, s92, 6
	s_add_i32 s6, s0, s1
	s_mov_b32 s0, s6
	s_ashr_i32 s7, s6, 31
	v_writelane_b32 v254, s0, 29
	s_sub_i32 s8, 0x7f, s6
	v_mov_b32_e32 v216, 0xc0447cbd
	v_writelane_b32 v254, s1, 30
	s_lshl_b64 s[0:1], s[6:7], 20
	v_writelane_b32 v254, s0, 31
	v_mov_b32_e32 v217, 1
	v_mov_b32_e32 v236, 0xbf1f24be
	v_writelane_b32 v254, s1, 32
	s_lshl_b32 s0, s9, 20
	s_cmp_lt_i32 s92, 64
	v_writelane_b32 v254, s0, 33
	s_cselect_b64 s[0:1], -1, 0
	v_writelane_b32 v254, s0, 34
	v_mov_b32_e32 v237, 0x3e642e9d
	v_not_b32_e32 v238, 63
	v_writelane_b32 v254, s1, 35
	s_lshr_b32 s0, s3, 30
	s_add_i32 s0, s92, s0
	s_ashr_i32 s1, s0, 2
	s_and_b32 s0, s0, -4
	s_sub_i32 s6, s92, s0
	s_lshr_b32 s0, s3, 27
	s_add_i32 s0, s92, s0
	s_ashr_i32 s0, s0, 5
	s_add_i32 s10, s0, 0x80
	s_lshr_b32 s0, s1, 29
	s_add_i32 s0, s1, s0
	s_and_b32 s0, s0, -8
	v_writelane_b32 v254, s3, 36
	s_sub_i32 s12, s1, s0
	s_mov_b32 s0, s10
	s_ashr_i32 s11, s10, 31
	v_writelane_b32 v254, s0, 37
	s_ashr_i32 s7, s6, 31
	s_ashr_i32 s13, s12, 31
	v_writelane_b32 v254, s1, 38
	s_lshl_b64 s[0:1], s[10:11], 20
	v_writelane_b32 v254, s0, 39
	s_mul_hi_i32 s3, s8, 0x2c0000
	v_not_b32_e32 v221, 31
	v_writelane_b32 v254, s1, 40
	s_lshl_b64 s[0:1], s[6:7], 10
	v_writelane_b32 v254, s0, 41
	v_mov_b32_e32 v220, 0x7fc00000
	v_mov_b32_e32 v239, 0xffc00000
	v_writelane_b32 v254, s1, 42
	s_lshl_b64 s[0:1], s[12:13], 20
	v_writelane_b32 v254, s0, 43
	v_mov_b32_e32 v224, 0x800
	v_mov_b32_e32 v225, 0x1000
	v_writelane_b32 v254, s1, 44
	s_lshl_b32 s0, s88, 9
	v_writelane_b32 v254, s0, 45
	s_lshl_b32 s0, s93, 9
	v_writelane_b32 v254, s0, 46
	s_mov_b32 s0, s6
	v_writelane_b32 v254, s0, 47
	v_mov_b32_e32 v226, 0x1800
	v_mov_b32_e32 v227, 0x2000
	v_writelane_b32 v254, s1, 48
	s_mul_i32 s0, s6, 0xb00
	v_writelane_b32 v254, s0, 49
	s_ashr_i32 s0, s0, 31
	v_writelane_b32 v254, s0, 50
	s_mov_b32 s0, s12
	v_writelane_b32 v254, s0, 51
	v_mov_b32_e32 v228, 0x2800
	v_mov_b32_e32 v229, 0x3000
	v_writelane_b32 v254, s1, 52
	s_mul_i32 s0, s12, 0x2c0000
	v_writelane_b32 v254, s0, 53
	s_ashr_i32 s0, s0, 31
	v_writelane_b32 v254, s0, 54
	s_add_i32 s0, s92, 0xfbf0
	s_bfe_u32 s0, s0, 0xd0003
	v_writelane_b32 v254, s0, 55
	s_cmp_lt_i32 s5, 0
	s_movk_i32 s0, 0x83
	s_cselect_b32 s0, s0, 0x82
	s_abs_i32 s1, s93
	v_cvt_f32_u32_e32 v0, s1
	v_writelane_b32 v254, s3, 56
	v_writelane_b32 v254, s8, 57
	s_mul_i32 s3, s8, 0x2c0000
	v_rcp_iflag_f32_e32 v0, v0
	v_writelane_b32 v254, s3, 58
	v_writelane_b32 v254, s9, 59
	s_mul_i32 s3, s9, 0x2c0000
	v_mul_f32_e32 v0, 0x4f7ffffe, v0
	v_cvt_u32_f32_e32 v0, v0
	v_writelane_b32 v254, s3, 60
	s_mul_i32 s0, s5, s0
	v_writelane_b32 v254, s0, 61
	v_writelane_b32 v254, s5, 62
	s_lshr_b32 s0, s5, 31
	v_writelane_b32 v254, s0, 63
	v_writelane_b32 v255, s1, 0
	s_sub_i32 s0, 0, s1
	v_readfirstlane_b32 s1, v0
	s_mul_i32 s0, s0, s1
	s_mul_hi_u32 s0, s1, s0
	s_add_i32 s0, s1, s0
	v_writelane_b32 v255, s0, 1
	v_writelane_b32 v255, s2, 2
	s_add_i32 s0, s2, s4
	v_writelane_b32 v255, s0, 3
	s_add_i32 s0, s0, 0x8000
	v_writelane_b32 v255, s0, 4
	s_mov_b32 s0, s88
	v_writelane_b32 v255, s0, 5
	s_ashr_i32 s5, s4, 31
	v_mov_b32_e32 v230, 0x3800
	v_writelane_b32 v255, s1, 6
	s_lshl_b32 s0, s88, 4
	v_writelane_b32 v255, s0, 7
	s_lshl_b32 s0, s93, 4
	v_writelane_b32 v255, s0, 8
	s_add_i32 s0, 0, 0x10800
	v_writelane_b32 v255, s0, 9
	s_add_i32 s0, 0, 0x12900
	v_writelane_b32 v255, s0, 10
	s_add_i32 s0, 0, 0x12100
	v_writelane_b32 v255, s0, 11
	s_add_i32 s0, 0, 0x27020
	v_writelane_b32 v255, s0, 12
	s_add_i32 s0, 0, 0x27024
	v_writelane_b32 v255, s0, 13
	s_add_i32 s0, 0, 0x22000
	v_writelane_b32 v255, s0, 14
	s_add_i32 s0, 0, 0x21800
	v_writelane_b32 v255, s0, 15
	s_add_i32 s0, 0, 0x11000
	v_writelane_b32 v255, s0, 16
	s_add_i32 s0, 0, 0x21b24
	v_writelane_b32 v255, s0, 17
	s_add_i32 s0, 0, 0x2200
	v_writelane_b32 v255, s0, 18
	s_add_i32 s0, 0, 0x26000
	v_writelane_b32 v255, s0, 19
	s_add_i32 s0, 0, 0x26400
	v_writelane_b32 v255, s0, 20
	s_add_i32 s0, 0, 0x22800
	v_writelane_b32 v255, s0, 21
	v_writelane_b32 v255, s4, 22
	s_lshl_b64 s[2:3], s[4:5], 12
	v_mov_b32_e32 v240, 0x7fc
	v_writelane_b32 v255, s5, 23
	v_writelane_b32 v255, s2, 24
	v_mov_b32_e32 v241, 0xffc
	v_mov_b32_e32 v242, 0x7f8
	v_writelane_b32 v255, s3, 25
	s_mov_b64 s[2:3], 0
	v_writelane_b32 v255, s2, 26
	v_mov_b32_e32 v243, 0xff8
	v_mov_b32_e32 v244, 0x7f4
	v_writelane_b32 v255, s3, 27
	s_mov_b64 s[2:3], 0
	v_writelane_b32 v255, s2, 28
	v_mov_b32_e32 v245, 0xff4
	v_mov_b32_e32 v246, 0x7f0
	v_writelane_b32 v255, s3, 29
	s_mov_b64 s[2:3], 0
	v_writelane_b32 v255, s2, 30
	v_mov_b32_e32 v247, 0xff0
	s_mov_b32 s60, 0xf800000
	v_writelane_b32 v255, s3, 31
	s_movk_i32 s61, 0x7fff
	s_mov_b32 s86, 0xffff0000
	s_movk_i32 s74, 0x1ff
	s_add_i32 s90, 0, 0x10000
	s_movk_i32 s91, 0x104
	s_movk_i32 s48, 0x4000
	s_brev_b32 s87, 18
	s_mov_b32 s68, 0xfe5163ab
	s_mov_b32 s84, 0x3c439041
	s_mov_b32 s85, 0xdb629599
	s_mov_b32 s88, 0xf534ddc0
	s_mov_b32 s89, 0xfc2757d1
	s_mov_b32 s54, 0x4e441529
	s_mov_b32 s55, 0xa2f9836e
	s_mov_b32 s47, 0x3fc90fda
	s_mov_b32 s46, 0x3f22f983
	s_mov_b32 s66, 0xbfc90fda
	s_brev_b32 s75, 1
	s_movk_i32 s53, 0x1f8
	s_mov_b32 s40, 0xc3ff8000
	s_mov_b32 s42, 0x10400
	s_movk_i32 s56, 0xfff
	s_movk_i32 s45, 0x110
	s_movk_i32 s81, 0x210
	s_movk_i32 s77, 0x2200
	s_mov_b32 s1, 0x20000
	s_movk_i32 s43, 0x220
	s_movk_i32 s69, 0x3ffc
	s_mov_b64 s[96:97], 0x80
	s_mov_b32 s82, 0x3ec3ef15
	s_mov_b32 s44, 0x3f6c835e
	s_mov_b32 s76, 0x3f3504f3
	s_mov_b32 s72, 0xbf3504f3
	s_mov_b32 s64, 0xbf6c835e
	s_mov_b32 s70, 0xbec3ef15
	s_mov_b32 s100, 2.0
	s_brev_b32 s80, 28
	s_mov_b32 s8, s51
	v_writelane_b32 v255, s95, 32
	s_waitcnt lgkmcnt(0)
	s_barrier
; __global__ void __launch_bounds__(NTHR, 2) fwd_kernel(Args args) {
;     ...
;     for (int l = 0; l < DEPTH; ++l) {
;         const bool uc = l < DEPTH - 1;
	s_branch .LBB0_145

; #define LAS __attribute__((address_space(3)))
; __device__ __forceinline__ f32x2 cmul(f32x2 a, f32x2 b) { return (f32x2){a.x * b.x - a.y * b.y, a.x * b.y + a.y * b.x}; }
; __device__ __forceinline__ f32x2 tw32k(const LAS f32x2* TH, const LAS f32x2* TL, int n) { return cmul(TH[n >> 7], TL[n & 127]); }
; template <bool INV> __device__ __forceinline__ void dft16(f32x2 (&x)[16]) {
; #pragma unroll
;     for (int b = 0; b < 4; ++b) r4<INV>(x[b], x[4 + b], x[8 + b], x[12 + b]);
;     const float sg = INV ? -1.f : 1.f;
;     const f32x2 W1 = {0.92387953251f, -0.38268343236f * sg}, W2 = {0.70710678118f, -0.70710678118f * sg}, W3 = {0.38268343236f, -0.92387953251f * sg},
;                 W4 = {0.f, -1.f * sg}, W6 = {-0.70710678118f, -0.70710678118f * sg}, W9 = {-0.92387953251f, 0.38268343236f * sg};
;     x[5] = cmul(x[5], W1); x[9] = cmul(x[9], W2); x[13] = cmul(x[13], W3);
;     x[6] = cmul(x[6], W2); x[10] = cmul(x[10], W4); x[14] = cmul(x[14], W6);
;     x[7] = cmul(x[7], W3); x[11] = cmul(x[11], W6); x[15] = cmul(x[15], W9);
; #pragma unroll
;     for (int c = 0; c < 4; ++c) r4<INV>(x[4 * c], x[4 * c + 1], x[4 * c + 2], x[4 * c + 3]);
; }
; template <bool INV> __device__ __forceinline__ void bfly16(f32x2 (&x)[16], const LAS f32x2* TH, const LAS f32x2* TL, int tw) {
;     f32x2 W = tw32k(TH, TL, tw); if (INV) W.y = -W.y;
;     if (INV) { f32x2 p = W;
; #pragma unroll
;         for (int q = 1; q < 16; ++q) { x[q] = cmul(x[q], p); if (q < 15) p = cmul(p, W); } }
;     dft16<INV>(x);
;     if (!INV) { f32x2 p = W;
; #pragma unroll
;         for (int r = 1; r < 16; ++r) { x[4 * (r & 3) + (r >> 2)] = cmul(x[4 * (r & 3) + (r >> 2)], p); if (r < 15) p = cmul(p, W); } }
; }
; template <bool INV> __device__ __forceinline__ void pass16(LAS f32x2* X, const LAS f32x2* TH, const LAS f32x2* TL, int base, int stride, int tw) {
;     f32x2 x[16];
; #pragma unroll
;     for (int q = 0; q < 16; ++q) x[q] = X[base + q * stride];
;     bfly16<INV>(x, TH, TL, tw);
; #pragma unroll
;     for (int c = 0; c < 4; ++c)
; #pragma unroll
;         for (int d = 0; d < 4; ++d) X[base + (c + 4 * d) * stride] = x[4 * c + d];
; }
.LBB0_696:
	v_add_u32_e32 v128, s0, v140
	v_lshrrev_b32_e32 v147, 6, v128
	v_and_b32_e32 v157, 63, v128
	v_lshlrev_b32_e32 v151, 5, v147
	v_lshlrev_b32_e32 v155, 3, v147
	v_lshlrev_b32_e32 v157, 4, v157
	v_lshl_add_u32 v151, v128, 3, v151
	v_add_u32_e32 v155, 0x26000, v155
	v_add_u32_e32 v157, 0x26400, v157
	v_add_u32_e32 v176, 0x11000, v151
	ds_read_b64 v[0:1], v155
	ds_read_b64 v[2:3], v157
	ds_read_b64 v[4:5], v151 offset:0
	ds_read_b64 v[6:7], v176 offset:0
	ds_read_b64 v[8:9], v151 offset:8704
	ds_read_b64 v[10:11], v176 offset:8704
	ds_read_b64 v[12:13], v151 offset:17408
	ds_read_b64 v[14:15], v176 offset:17408
	ds_read_b64 v[16:17], v151 offset:26112
	ds_read_b64 v[18:19], v176 offset:26112
	ds_read_b64 v[20:21], v151 offset:34816
	ds_read_b64 v[22:23], v176 offset:34816
	ds_read_b64 v[24:25], v151 offset:43520
	ds_read_b64 v[26:27], v176 offset:43520
	ds_read_b64 v[28:29], v151 offset:52224
	ds_read_b64 v[30:31], v176 offset:52224
	ds_read_b64 v[32:33], v151 offset:60928
	ds_read_b64 v[34:35], v176 offset:60928
	s_cmp_eq_u32 s0, 0
	s_movk_i32 s0, 0x200
	s_mov_b64 s[36:37], 0
	s_waitcnt lgkmcnt(15)
	v_pk_mul_f32 v[36:37], v[0:1], v[2:3] op_sel:[0,1] op_sel_hi:[1,1]
	s_nop 0
	v_pk_fma_f32 v[0:1], v[0:1], v[2:3], v[36:37] op_sel:[0,0,1] op_sel_hi:[1,0,0] neg_lo:[0,0,1]
	s_nop 0
	v_pk_mul_f32 v[36:37], v[0:1], v[0:1] op_sel:[0,1] op_sel_hi:[1,1]
	s_nop 0
	v_pk_fma_f32 v[36:37], v[0:1], v[0:1], v[36:37] op_sel:[0,0,1] op_sel_hi:[1,0,0] neg_lo:[0,0,1]
	s_nop 0
	v_pk_mul_f32 v[2:3], v[36:37], v[0:1] op_sel:[0,1] op_sel_hi:[1,1]
	v_pk_mul_f32 v[38:39], v[36:37], v[36:37] op_sel:[0,1] op_sel_hi:[1,1]
	v_pk_fma_f32 v[2:3], v[36:37], v[0:1], v[2:3] op_sel:[0,0,1] op_sel_hi:[1,0,0] neg_lo:[0,0,1]
	v_pk_fma_f32 v[38:39], v[36:37], v[36:37], v[38:39] op_sel:[0,0,1] op_sel_hi:[1,0,0] neg_lo:[0,0,1]
	s_nop 0
	v_pk_mul_f32 v[40:41], v[38:39], v[0:1] op_sel:[0,1] op_sel_hi:[1,1]
	v_pk_mul_f32 v[42:43], v[38:39], v[36:37] op_sel:[0,1] op_sel_hi:[1,1]
	v_pk_mul_f32 v[44:45], v[38:39], v[2:3] op_sel:[0,1] op_sel_hi:[1,1]
	v_pk_fma_f32 v[40:41], v[38:39], v[0:1], v[40:41] op_sel:[0,0,1] op_sel_hi:[1,0,0] neg_lo:[0,0,1]
	v_pk_fma_f32 v[42:43], v[38:39], v[36:37], v[42:43] op_sel:[0,0,1] op_sel_hi:[1,0,0] neg_lo:[0,0,1]
	v_pk_fma_f32 v[44:45], v[38:39], v[2:3], v[44:45] op_sel:[0,0,1] op_sel_hi:[1,0,0] neg_lo:[0,0,1]
	v_pk_mul_f32 v[46:47], v[38:39], v[38:39] op_sel:[0,1] op_sel_hi:[1,1]
	s_nop 0
	v_pk_fma_f32 v[46:47], v[38:39], v[38:39], v[46:47] op_sel:[0,0,1] op_sel_hi:[1,0,0] neg_lo:[0,0,1]
	s_nop 0
	v_pk_mul_f32 v[48:49], v[46:47], v[0:1] op_sel:[0,1] op_sel_hi:[1,1]
	v_pk_mul_f32 v[50:51], v[46:47], v[36:37] op_sel:[0,1] op_sel_hi:[1,1]
	v_pk_mul_f32 v[52:53], v[46:47], v[2:3] op_sel:[0,1] op_sel_hi:[1,1]
	v_pk_fma_f32 v[48:49], v[46:47], v[0:1], v[48:49] op_sel:[0,0,1] op_sel_hi:[1,0,0] neg_lo:[0,0,1]
	v_pk_fma_f32 v[50:51], v[46:47], v[36:37], v[50:51] op_sel:[0,0,1] op_sel_hi:[1,0,0] neg_lo:[0,0,1]
	v_pk_fma_f32 v[52:53], v[46:47], v[2:3], v[52:53] op_sel:[0,0,1] op_sel_hi:[1,0,0] neg_lo:[0,0,1]
	v_pk_mul_f32 v[54:55], v[46:47], v[38:39] op_sel:[0,1] op_sel_hi:[1,1]
	v_pk_mul_f32 v[56:57], v[46:47], v[40:41] op_sel:[0,1] op_sel_hi:[1,1]
	v_pk_mul_f32 v[58:59], v[46:47], v[42:43] op_sel:[0,1] op_sel_hi:[1,1]
	v_pk_fma_f32 v[54:55], v[46:47], v[38:39], v[54:55] op_sel:[0,0,1] op_sel_hi:[1,0,0] neg_lo:[0,0,1]
	v_pk_fma_f32 v[56:57], v[46:47], v[40:41], v[56:57] op_sel:[0,0,1] op_sel_hi:[1,0,0] neg_lo:[0,0,1]
	v_pk_fma_f32 v[58:59], v[46:47], v[42:43], v[58:59] op_sel:[0,0,1] op_sel_hi:[1,0,0] neg_lo:[0,0,1]
	v_pk_mul_f32 v[60:61], v[46:47], v[44:45] op_sel:[0,1] op_sel_hi:[1,1]
	s_nop 0
	v_pk_fma_f32 v[60:61], v[46:47], v[44:45], v[60:61] op_sel:[0,0,1] op_sel_hi:[1,0,0] neg_lo:[0,0,1]
	s_waitcnt lgkmcnt(14)
	v_pk_add_f32 v[62:63], v[4:5], v[6:7]
	s_waitcnt lgkmcnt(12)
	v_pk_add_f32 v[170:171], v[8:9], v[10:11]
	s_waitcnt lgkmcnt(10)
	v_pk_add_f32 v[172:173], v[12:13], v[14:15]
	s_waitcnt lgkmcnt(8)
	v_pk_add_f32 v[174:175], v[16:17], v[18:19]
	v_pk_add_f32 v[4:5], v[4:5], v[6:7] neg_lo:[0,1] neg_hi:[0,1]
	v_pk_add_f32 v[8:9], v[8:9], v[10:11] neg_lo:[0,1] neg_hi:[0,1]
	v_pk_add_f32 v[12:13], v[12:13], v[14:15] neg_lo:[0,1] neg_hi:[0,1]
	v_pk_add_f32 v[16:17], v[16:17], v[18:19] neg_lo:[0,1] neg_hi:[0,1]
	s_waitcnt lgkmcnt(6)
	v_pk_add_f32 v[18:19], v[20:21], v[22:23]
	s_waitcnt lgkmcnt(4)
	v_pk_add_f32 v[14:15], v[24:25], v[26:27]
	s_waitcnt lgkmcnt(2)
	v_pk_add_f32 v[10:11], v[28:29], v[30:31]
	s_waitcnt lgkmcnt(0)
; __device__ __forceinline__ f32x2 cmul(f32x2 a, f32x2 b) { return (f32x2){a.x * b.x - a.y * b.y, a.x * b.y + a.y * b.x}; }
; template <bool INV> __device__ __forceinline__ void dft16(f32x2 (&x)[16]) {
; #pragma unroll
;     for (int b = 0; b < 4; ++b) r4<INV>(x[b], x[4 + b], x[8 + b], x[12 + b]);
;     const float sg = INV ? -1.f : 1.f;
;     const f32x2 W1 = {0.92387953251f, -0.38268343236f * sg}, W2 = {0.70710678118f, -0.70710678118f * sg}, W3 = {0.38268343236f, -0.92387953251f * sg},
;                 W4 = {0.f, -1.f * sg}, W6 = {-0.70710678118f, -0.70710678118f * sg}, W9 = {-0.92387953251f, 0.38268343236f * sg};
;     x[5] = cmul(x[5], W1); x[9] = cmul(x[9], W2); x[13] = cmul(x[13], W3);
;     x[6] = cmul(x[6], W2); x[10] = cmul(x[10], W4); x[14] = cmul(x[14], W6);
;     x[7] = cmul(x[7], W3); x[11] = cmul(x[11], W6); x[15] = cmul(x[15], W9);
; #pragma unroll
;     for (int c = 0; c < 4; ++c) r4<INV>(x[4 * c], x[4 * c + 1], x[4 * c + 2], x[4 * c + 3]);
; }
	v_pk_add_f32 v[6:7], v[32:33], v[34:35]
	v_pk_add_f32 v[20:21], v[20:21], v[22:23] neg_lo:[0,1] neg_hi:[0,1]
	v_pk_add_f32 v[24:25], v[24:25], v[26:27] neg_lo:[0,1] neg_hi:[0,1]
	v_pk_add_f32 v[30:31], v[28:29], v[30:31] neg_lo:[0,1] neg_hi:[0,1]
	v_pk_add_f32 v[34:35], v[32:33], v[34:35] neg_lo:[0,1] neg_hi:[0,1]
	v_pk_add_f32 v[32:33], v[62:63], v[18:19]
	v_pk_add_f32 v[28:29], v[170:171], v[14:15]
	v_pk_add_f32 v[26:27], v[172:173], v[10:11]
	v_pk_add_f32 v[22:23], v[174:175], v[6:7]
	v_pk_add_f32 v[18:19], v[62:63], v[18:19] neg_lo:[0,1] neg_hi:[0,1]
	v_pk_add_f32 v[14:15], v[170:171], v[14:15] neg_lo:[0,1] neg_hi:[0,1]
	v_pk_add_f32 v[172:173], v[172:173], v[10:11] neg_lo:[0,1] neg_hi:[0,1]
	v_pk_add_f32 v[6:7], v[174:175], v[6:7] neg_lo:[0,1] neg_hi:[0,1]
	v_pk_add_f32 v[174:175], v[4:5], v[20:21] op_sel:[0,1] op_sel_hi:[1,0] neg_hi:[0,1]
	v_pk_add_f32 v[10:11], v[8:9], v[24:25] op_sel:[0,1] op_sel_hi:[1,0] neg_hi:[0,1]
	v_pk_add_f32 v[170:171], v[12:13], v[30:31] op_sel:[0,1] op_sel_hi:[1,0] neg_hi:[0,1]
	v_pk_add_f32 v[62:63], v[16:17], v[34:35] op_sel:[0,1] op_sel_hi:[1,0] neg_hi:[0,1]
	v_pk_add_f32 v[4:5], v[4:5], v[20:21] op_sel:[0,1] op_sel_hi:[1,0] neg_lo:[0,1]
	v_pk_add_f32 v[24:25], v[8:9], v[24:25] op_sel:[0,1] op_sel_hi:[1,0] neg_lo:[0,1]
	v_pk_add_f32 v[12:13], v[12:13], v[30:31] op_sel:[0,1] op_sel_hi:[1,0] neg_lo:[0,1]
	v_pk_add_f32 v[34:35], v[16:17], v[34:35] op_sel:[0,1] op_sel_hi:[1,0] neg_lo:[0,1]
	v_pk_add_f32 v[16:17], v[32:33], v[26:27]
	v_pk_mul_f32 v[30:31], v[10:11], s[70:71] op_sel_hi:[1,0]
	v_pk_mul_f32 v[8:9], v[14:15], s[72:73] op_sel_hi:[1,0]
	v_pk_mul_f32 v[20:21], v[24:25], s[64:65] op_sel_hi:[1,0]
	v_pk_add_f32 v[32:33], v[32:33], v[26:27] neg_lo:[0,1] neg_hi:[0,1]
	v_pk_fma_f32 v[30:31], v[10:11], s[44:45], v[30:31] op_sel:[0,0,1] op_sel_hi:[1,0,0] neg_lo:[0,0,1]
	v_pk_fma_f32 v[8:9], v[14:15], s[76:77], v[8:9] op_sel:[0,0,1] op_sel_hi:[1,0,0] neg_lo:[0,0,1]
	v_pk_fma_f32 v[20:21], v[24:25], s[82:83], v[20:21] op_sel:[0,0,1] op_sel_hi:[1,0,0] neg_lo:[0,0,1]
	v_pk_add_f32 v[24:25], v[28:29], v[22:23]
	v_pk_fma_f32 v[14:15], v[170:171], s[72:73], v[174:175] op_sel:[0,0,1] op_sel_hi:[1,0,0] neg_hi:[0,0,1]
	v_pk_add_f32 v[10:11], v[18:19], v[172:173] op_sel:[0,1] op_sel_hi:[1,0] neg_hi:[0,1]
	v_pk_fma_f32 v[26:27], v[12:13], s[72:73], v[4:5] op_sel:[0,0,1] op_sel_hi:[1,0,0] neg_hi:[0,0,1]
	v_pk_add_f32 v[28:29], v[28:29], v[22:23] neg_lo:[0,1] neg_hi:[0,1]
	v_pk_fma_f32 v[170:171], v[170:171], s[76:77], v[14:15] op_sel:[0,0,1] op_sel_hi:[1,0,0] neg_lo:[0,0,1]
	v_pk_add_f32 v[18:19], v[18:19], v[172:173] op_sel:[0,1] op_sel_hi:[1,0] neg_lo:[0,1]
	v_pk_fma_f32 v[12:13], v[12:13], s[72:73], v[26:27] op_sel:[0,0,1] op_sel_hi:[1,0,0] neg_lo:[0,0,1]
	v_pk_add_f32 v[26:27], v[16:17], v[24:25]
	v_pk_fma_f32 v[174:175], v[174:175], s[100:101], v[170:171] op_sel_hi:[1,0,1] neg_lo:[0,0,1] neg_hi:[0,0,1]
	v_pk_fma_f32 v[172:173], v[6:7], s[72:73], v[8:9] op_sel:[0,0,1] op_sel_hi:[1,0,0] neg_hi:[0,0,1]
	v_pk_fma_f32 v[4:5], v[4:5], s[100:101], v[12:13] op_sel_hi:[1,0,1] neg_lo:[0,0,1] neg_hi:[0,0,1]
	v_pk_add_f32 v[24:25], v[16:17], v[24:25] neg_lo:[0,1] neg_hi:[0,1]
	v_pk_fma_f32 v[16:17], v[62:63], s[64:65], v[30:31] op_sel:[0,0,1] op_sel_hi:[1,0,0] neg_hi:[0,0,1]
	v_pk_fma_f32 v[172:173], v[6:7], s[72:73], v[172:173] op_sel:[0,0,1] op_sel_hi:[1,0,0] neg_lo:[0,0,1]
	v_pk_fma_f32 v[6:7], v[34:35], s[82:83], v[20:21] op_sel:[0,0,1] op_sel_hi:[1,0,0] neg_hi:[0,0,1]
	v_pk_add_f32 v[14:15], v[32:33], v[28:29] op_sel:[0,1] op_sel_hi:[1,0] neg_hi:[0,1]
	v_pk_fma_f32 v[62:63], v[62:63], s[82:83], v[16:17] op_sel:[0,0,1] op_sel_hi:[1,0,0] neg_lo:[0,0,1]
	v_pk_fma_f32 v[8:9], v[8:9], s[100:101], v[172:173] op_sel_hi:[1,0,1] neg_lo:[0,0,1] neg_hi:[0,0,1]
	v_pk_fma_f32 v[34:35], v[34:35], s[64:65], v[6:7] op_sel:[0,0,1] op_sel_hi:[1,0,0] neg_lo:[0,0,1]
	v_pk_add_f32 v[28:29], v[32:33], v[28:29] op_sel:[0,1] op_sel_hi:[1,0] neg_lo:[0,1]
	v_pk_fma_f32 v[30:31], v[30:31], s[100:101], v[62:63] op_sel_hi:[1,0,1] neg_lo:[0,0,1] neg_hi:[0,0,1]
	v_pk_add_f32 v[32:33], v[10:11], v[172:173]
	v_pk_fma_f32 v[20:21], v[20:21], s[100:101], v[34:35] op_sel_hi:[1,0,1] neg_lo:[0,0,1] neg_hi:[0,0,1]
	v_pk_add_f32 v[6:7], v[170:171], v[62:63]
	v_pk_add_f32 v[172:173], v[10:11], v[172:173] neg_lo:[0,1] neg_hi:[0,1]
	v_pk_add_f32 v[10:11], v[12:13], v[34:35]
	v_pk_add_f32 v[62:63], v[170:171], v[62:63] neg_lo:[0,1] neg_hi:[0,1]
	v_pk_add_f32 v[170:171], v[18:19], v[8:9] op_sel:[0,1] op_sel_hi:[1,0] neg_hi:[0,1]
	v_pk_add_f32 v[12:13], v[12:13], v[34:35] neg_lo:[0,1] neg_hi:[0,1]
	v_pk_add_f32 v[34:35], v[174:175], v[30:31] op_sel:[0,1] op_sel_hi:[1,0] neg_hi:[0,1]
	v_pk_add_f32 v[8:9], v[18:19], v[8:9] op_sel:[0,1] op_sel_hi:[1,0] neg_lo:[0,1]
	v_pk_add_f32 v[18:19], v[4:5], v[20:21] op_sel:[0,1] op_sel_hi:[1,0] neg_hi:[0,1]
	v_pk_add_f32 v[174:175], v[174:175], v[30:31] op_sel:[0,1] op_sel_hi:[1,0] neg_lo:[0,1]
	v_pk_add_f32 v[20:21], v[4:5], v[20:21] op_sel:[0,1] op_sel_hi:[1,0] neg_lo:[0,1]
	v_pk_mul_f32 v[4:5], v[6:7], v[0:1] op_sel:[0,1] op_sel_hi:[1,1]
	v_pk_mul_f32 v[30:31], v[32:33], v[36:37] op_sel:[0,1] op_sel_hi:[1,1]
	v_pk_fma_f32 v[6:7], v[6:7], v[0:1], v[4:5] op_sel:[0,0,1] op_sel_hi:[1,0,0] neg_lo:[0,0,1]
	v_pk_mul_f32 v[4:5], v[10:11], v[2:3] op_sel:[0,1] op_sel_hi:[1,1]
	v_pk_fma_f32 v[36:37], v[32:33], v[36:37], v[30:31] op_sel:[0,0,1] op_sel_hi:[1,0,0] neg_lo:[0,0,1]
	v_pk_mul_f32 v[32:33], v[14:15], v[38:39] op_sel:[0,1] op_sel_hi:[1,1]
	v_pk_fma_f32 v[4:5], v[10:11], v[2:3], v[4:5] op_sel:[0,0,1] op_sel_hi:[1,0,0] neg_lo:[0,0,1]
	v_pk_mul_f32 v[10:11], v[34:35], v[40:41] op_sel:[0,1] op_sel_hi:[1,1]
; #define LAS __attribute__((address_space(3)))
; __device__ __forceinline__ f32x2 cmul(f32x2 a, f32x2 b) { return (f32x2){a.x * b.x - a.y * b.y, a.x * b.y + a.y * b.x}; }
; template <bool INV> __device__ __forceinline__ void bfly16(f32x2 (&x)[16], const LAS f32x2* TH, const LAS f32x2* TL, int tw) {
;     ...
;     if (!INV) { f32x2 p = W;
; #pragma unroll
;         for (int r = 1; r < 16; ++r) { x[4 * (r & 3) + (r >> 2)] = cmul(x[4 * (r & 3) + (r >> 2)], p); if (r < 15) p = cmul(p, W); } }
; template <bool INV> __device__ __forceinline__ void pass16_s64(LAS f32x2* X, const LAS f32x2* TH, int base, int j) {
;     f32x2 x[16];
; #pragma unroll
;     for (int q = 0; q < 16; ++q) x[q] = X[base + q * 68];
;     bfly16_tab<INV>(x, TH - 2048, 64, j);
; #pragma unroll
;     for (int c = 0; c < 4; ++c)
; #pragma unroll
;         for (int d = 0; d < 4; ++d) X[base + (c + 4 * d) * 68] = x[4 * c + d];
; }
; template <bool INV> __device__ __forceinline__ void pass16(LAS f32x2* X, const LAS f32x2* TH, const LAS f32x2* TL, int base, int stride, int tw) {
;     f32x2 x[16];
; #pragma unroll
;     for (int q = 0; q < 16; ++q) x[q] = X[base + q * stride];
;     bfly16<INV>(x, TH, TL, tw);
; #pragma unroll
;     for (int c = 0; c < 4; ++c)
; #pragma unroll
;         for (int d = 0; d < 4; ++d) X[base + (c + 4 * d) * stride] = x[4 * c + d];
; }
	v_pk_fma_f32 v[14:15], v[14:15], v[38:39], v[32:33] op_sel:[0,0,1] op_sel_hi:[1,0,0] neg_lo:[0,0,1]
	v_pk_mul_f32 v[38:39], v[170:171], v[42:43] op_sel:[0,1] op_sel_hi:[1,1]
	v_pk_fma_f32 v[40:41], v[34:35], v[40:41], v[10:11] op_sel:[0,0,1] op_sel_hi:[1,0,0] neg_lo:[0,0,1]
	v_pk_mul_f32 v[10:11], v[18:19], v[44:45] op_sel:[0,1] op_sel_hi:[1,1]
	v_pk_fma_f32 v[42:43], v[170:171], v[42:43], v[38:39] op_sel:[0,0,1] op_sel_hi:[1,0,0] neg_lo:[0,0,1]
	v_pk_mul_f32 v[38:39], v[24:25], v[46:47] op_sel:[0,1] op_sel_hi:[1,1]
	v_pk_fma_f32 v[10:11], v[18:19], v[44:45], v[10:11] op_sel:[0,0,1] op_sel_hi:[1,0,0] neg_lo:[0,0,1]
	v_pk_mul_f32 v[44:45], v[62:63], v[48:49] op_sel:[0,1] op_sel_hi:[1,1]
	v_pk_fma_f32 v[46:47], v[24:25], v[46:47], v[38:39] op_sel:[0,0,1] op_sel_hi:[1,0,0] neg_lo:[0,0,1]
	v_pk_mul_f32 v[38:39], v[172:173], v[50:51] op_sel:[0,1] op_sel_hi:[1,1]
	v_pk_fma_f32 v[48:49], v[62:63], v[48:49], v[44:45] op_sel:[0,0,1] op_sel_hi:[1,0,0] neg_lo:[0,0,1]
	v_pk_mul_f32 v[44:45], v[12:13], v[52:53] op_sel:[0,1] op_sel_hi:[1,1]
	v_pk_fma_f32 v[50:51], v[172:173], v[50:51], v[38:39] op_sel:[0,0,1] op_sel_hi:[1,0,0] neg_lo:[0,0,1]
	v_pk_mul_f32 v[172:173], v[28:29], v[54:55] op_sel:[0,1] op_sel_hi:[1,1]
	v_pk_fma_f32 v[44:45], v[12:13], v[52:53], v[44:45] op_sel:[0,0,1] op_sel_hi:[1,0,0] neg_lo:[0,0,1]
	v_pk_mul_f32 v[52:53], v[174:175], v[56:57] op_sel:[0,1] op_sel_hi:[1,1]
	v_pk_fma_f32 v[28:29], v[28:29], v[54:55], v[172:173] op_sel:[0,0,1] op_sel_hi:[1,0,0] neg_lo:[0,0,1]
	v_pk_mul_f32 v[54:55], v[8:9], v[58:59] op_sel:[0,1] op_sel_hi:[1,1]
	v_pk_fma_f32 v[52:53], v[174:175], v[56:57], v[52:53] op_sel:[0,0,1] op_sel_hi:[1,0,0] neg_lo:[0,0,1]
	v_pk_mul_f32 v[56:57], v[20:21], v[60:61] op_sel:[0,1] op_sel_hi:[1,1]
	v_pk_fma_f32 v[58:59], v[8:9], v[58:59], v[54:55] op_sel:[0,0,1] op_sel_hi:[1,0,0] neg_lo:[0,0,1]
	v_pk_fma_f32 v[20:21], v[20:21], v[60:61], v[56:57] op_sel:[0,0,1] op_sel_hi:[1,0,0] neg_lo:[0,0,1]
	ds_write_b64 v151, v[26:27] offset:0
	ds_write_b64 v151, v[6:7] offset:8704
	ds_write_b64 v151, v[36:37] offset:17408
	ds_write_b64 v151, v[4:5] offset:26112
	ds_write_b64 v151, v[14:15] offset:34816
	ds_write_b64 v151, v[40:41] offset:43520
	ds_write_b64 v151, v[42:43] offset:52224
	ds_write_b64 v151, v[10:11] offset:60928
	ds_write_b64 v176, v[46:47] offset:0
	ds_write_b64 v176, v[48:49] offset:8704
	ds_write_b64 v176, v[50:51] offset:17408
	ds_write_b64 v176, v[44:45] offset:26112
	ds_write_b64 v176, v[28:29] offset:34816
	ds_write_b64 v176, v[52:53] offset:43520
	ds_write_b64 v176, v[58:59] offset:52224
	ds_write_b64 v176, v[20:21] offset:60928
	s_cbranch_scc1 .LBB0_696
	s_waitcnt lgkmcnt(0)
	s_barrier
	s_mov_b32 s0, 0
	s_mov_b64 s[36:37], -1
	ds_read2st64_b64 v[232:235], v139 offset0:1 offset1:2
	ds_read2st64_b64 v[208:211], v139 offset0:3 offset1:4
	ds_read2st64_b64 v[204:207], v139 offset0:5 offset1:6
	ds_read2st64_b64 v[200:203], v139 offset0:7 offset1:8
	ds_read2st64_b64 v[196:199], v139 offset0:9 offset1:10
	ds_read2st64_b64 v[192:195], v139 offset0:11 offset1:12
	ds_read2st64_b64 v[188:191], v139 offset0:13 offset1:14
	ds_read_b64 v[186:187], v139 offset:7680
.LBB0_698:
	v_add_u32_e32 v128, s0, v140
	v_lshrrev_b32_e32 v147, 6, v128
	v_mad_u32_u24 v151, v147, s77, v142
	ds_read_b64 v[0:1], v151 offset:0
	ds_read_b64 v[2:3], v151 offset:4352
	ds_read_b64 v[4:5], v151 offset:544
	ds_read_b64 v[6:7], v151 offset:4896
	ds_read_b64 v[8:9], v151 offset:1088
	ds_read_b64 v[10:11], v151 offset:5440
	ds_read_b64 v[12:13], v151 offset:1632
	ds_read_b64 v[14:15], v151 offset:5984
	ds_read_b64 v[16:17], v151 offset:2176
	ds_read_b64 v[18:19], v151 offset:6528
	ds_read_b64 v[20:21], v151 offset:2720
	ds_read_b64 v[22:23], v151 offset:7072
	ds_read_b64 v[24:25], v151 offset:3264
	ds_read_b64 v[26:27], v151 offset:7616
	ds_read_b64 v[28:29], v151 offset:3808
	ds_read_b64 v[30:31], v151 offset:8160
	s_cmp_eq_u32 s0, 0
	s_movk_i32 s0, 0x200
	s_mov_b64 s[36:37], 0
	s_waitcnt lgkmcnt(14)
	v_pk_add_f32 v[32:33], v[0:1], v[2:3]
	s_waitcnt lgkmcnt(12)
	v_pk_add_f32 v[34:35], v[4:5], v[6:7]
	s_waitcnt lgkmcnt(10)
	v_pk_add_f32 v[36:37], v[8:9], v[10:11]
	s_waitcnt lgkmcnt(8)
	v_pk_add_f32 v[38:39], v[12:13], v[14:15]
	v_pk_add_f32 v[2:3], v[0:1], v[2:3] neg_lo:[0,1] neg_hi:[0,1]
	v_pk_add_f32 v[6:7], v[4:5], v[6:7] neg_lo:[0,1] neg_hi:[0,1]
	v_pk_add_f32 v[8:9], v[8:9], v[10:11] neg_lo:[0,1] neg_hi:[0,1]
	v_pk_add_f32 v[12:13], v[12:13], v[14:15] neg_lo:[0,1] neg_hi:[0,1]
	s_waitcnt lgkmcnt(6)
	v_pk_add_f32 v[14:15], v[16:17], v[18:19]
	s_waitcnt lgkmcnt(4)
	v_pk_add_f32 v[10:11], v[20:21], v[22:23]
	s_waitcnt lgkmcnt(2)
	v_pk_add_f32 v[4:5], v[24:25], v[26:27]
	s_waitcnt lgkmcnt(0)
; #define LAS __attribute__((address_space(3)))
; __device__ __forceinline__ f32x2 cmul(f32x2 a, f32x2 b) { return (f32x2){a.x * b.x - a.y * b.y, a.x * b.y + a.y * b.x}; }
; template <bool INV> __device__ __forceinline__ void dft16(f32x2 (&x)[16]) {
; #pragma unroll
;     for (int b = 0; b < 4; ++b) r4<INV>(x[b], x[4 + b], x[8 + b], x[12 + b]);
;     const float sg = INV ? -1.f : 1.f;
;     const f32x2 W1 = {0.92387953251f, -0.38268343236f * sg}, W2 = {0.70710678118f, -0.70710678118f * sg}, W3 = {0.38268343236f, -0.92387953251f * sg},
;                 W4 = {0.f, -1.f * sg}, W6 = {-0.70710678118f, -0.70710678118f * sg}, W9 = {-0.92387953251f, 0.38268343236f * sg};
;     x[5] = cmul(x[5], W1); x[9] = cmul(x[9], W2); x[13] = cmul(x[13], W3);
;     x[6] = cmul(x[6], W2); x[10] = cmul(x[10], W4); x[14] = cmul(x[14], W6);
;     x[7] = cmul(x[7], W3); x[11] = cmul(x[11], W6); x[15] = cmul(x[15], W9);
; #pragma unroll
;     for (int c = 0; c < 4; ++c) r4<INV>(x[4 * c], x[4 * c + 1], x[4 * c + 2], x[4 * c + 3]);
; }
; template <bool INV> __device__ __forceinline__ void bfly16_tab(f32x2 (&x)[16], const LAS f32x2* T, int tstride, int j) {
;     if (INV) {
; #pragma unroll
;         for (int q = 1; q < 16; ++q) { f32x2 p = T[q * tstride + j]; p.y = -p.y; x[q] = cmul(x[q], p); } }
;     dft16<INV>(x);
;     if (!INV) {
; #pragma unroll
;         for (int r = 1; r < 16; ++r) { const f32x2 p = T[r * tstride + j]; x[4 * (r & 3) + (r >> 2)] = cmul(x[4 * (r & 3) + (r >> 2)], p); } }
; }
	v_pk_add_f32 v[0:1], v[28:29], v[30:31]
	v_pk_add_f32 v[16:17], v[16:17], v[18:19] neg_lo:[0,1] neg_hi:[0,1]
	v_pk_add_f32 v[20:21], v[20:21], v[22:23] neg_lo:[0,1] neg_hi:[0,1]
	v_pk_add_f32 v[26:27], v[24:25], v[26:27] neg_lo:[0,1] neg_hi:[0,1]
	v_pk_add_f32 v[30:31], v[28:29], v[30:31] neg_lo:[0,1] neg_hi:[0,1]
	v_pk_add_f32 v[28:29], v[32:33], v[14:15]
	v_pk_add_f32 v[24:25], v[34:35], v[10:11]
	v_pk_add_f32 v[22:23], v[36:37], v[4:5]
	v_pk_add_f32 v[18:19], v[38:39], v[0:1]
	v_pk_add_f32 v[14:15], v[32:33], v[14:15] neg_lo:[0,1] neg_hi:[0,1]
	v_pk_add_f32 v[34:35], v[34:35], v[10:11] neg_lo:[0,1] neg_hi:[0,1]
	v_pk_add_f32 v[36:37], v[36:37], v[4:5] neg_lo:[0,1] neg_hi:[0,1]
	v_pk_add_f32 v[38:39], v[38:39], v[0:1] neg_lo:[0,1] neg_hi:[0,1]
	v_pk_add_f32 v[0:1], v[2:3], v[16:17] op_sel:[0,1] op_sel_hi:[1,0] neg_hi:[0,1]
	v_pk_add_f32 v[4:5], v[6:7], v[20:21] op_sel:[0,1] op_sel_hi:[1,0] neg_hi:[0,1]
	v_pk_add_f32 v[10:11], v[8:9], v[26:27] op_sel:[0,1] op_sel_hi:[1,0] neg_hi:[0,1]
	v_pk_add_f32 v[32:33], v[12:13], v[30:31] op_sel:[0,1] op_sel_hi:[1,0] neg_hi:[0,1]
	v_pk_add_f32 v[2:3], v[2:3], v[16:17] op_sel:[0,1] op_sel_hi:[1,0] neg_lo:[0,1]
	v_pk_add_f32 v[20:21], v[6:7], v[20:21] op_sel:[0,1] op_sel_hi:[1,0] neg_lo:[0,1]
	v_pk_add_f32 v[26:27], v[8:9], v[26:27] op_sel:[0,1] op_sel_hi:[1,0] neg_lo:[0,1]
	v_pk_add_f32 v[30:31], v[12:13], v[30:31] op_sel:[0,1] op_sel_hi:[1,0] neg_lo:[0,1]
	v_pk_add_f32 v[12:13], v[28:29], v[22:23]
	v_pk_mul_f32 v[8:9], v[4:5], s[70:71] op_sel_hi:[1,0]
	v_pk_mul_f32 v[6:7], v[34:35], s[72:73] op_sel_hi:[1,0]
	v_pk_mul_f32 v[16:17], v[20:21], s[64:65] op_sel_hi:[1,0]
	v_pk_add_f32 v[22:23], v[28:29], v[22:23] neg_lo:[0,1] neg_hi:[0,1]
	v_pk_fma_f32 v[8:9], v[4:5], s[44:45], v[8:9] op_sel:[0,0,1] op_sel_hi:[1,0,0] neg_lo:[0,0,1]
	v_pk_fma_f32 v[6:7], v[34:35], s[76:77], v[6:7] op_sel:[0,0,1] op_sel_hi:[1,0,0] neg_lo:[0,0,1]
	v_pk_fma_f32 v[20:21], v[20:21], s[82:83], v[16:17] op_sel:[0,0,1] op_sel_hi:[1,0,0] neg_lo:[0,0,1]
	v_pk_add_f32 v[16:17], v[24:25], v[18:19]
	v_pk_fma_f32 v[34:35], v[10:11], s[72:73], v[0:1] op_sel:[0,0,1] op_sel_hi:[1,0,0] neg_hi:[0,0,1]
	v_pk_add_f32 v[4:5], v[14:15], v[36:37] op_sel:[0,1] op_sel_hi:[1,0] neg_hi:[0,1]
	v_pk_fma_f32 v[28:29], v[26:27], s[72:73], v[2:3] op_sel:[0,0,1] op_sel_hi:[1,0,0] neg_hi:[0,0,1]
	v_pk_add_f32 v[24:25], v[24:25], v[18:19] neg_lo:[0,1] neg_hi:[0,1]
	v_pk_fma_f32 v[34:35], v[10:11], s[76:77], v[34:35] op_sel:[0,0,1] op_sel_hi:[1,0,0] neg_lo:[0,0,1]
	v_pk_add_f32 v[14:15], v[14:15], v[36:37] op_sel:[0,1] op_sel_hi:[1,0] neg_lo:[0,1]
	v_pk_fma_f32 v[26:27], v[26:27], s[72:73], v[28:29] op_sel:[0,0,1] op_sel_hi:[1,0,0] neg_lo:[0,0,1]
	v_pk_add_f32 v[28:29], v[12:13], v[16:17]
	v_pk_fma_f32 v[0:1], v[0:1], s[100:101], v[34:35] op_sel_hi:[1,0,1] neg_lo:[0,0,1] neg_hi:[0,0,1]
	v_pk_fma_f32 v[36:37], v[38:39], s[72:73], v[6:7] op_sel:[0,0,1] op_sel_hi:[1,0,0] neg_hi:[0,0,1]
	v_pk_fma_f32 v[2:3], v[2:3], s[100:101], v[26:27] op_sel_hi:[1,0,1] neg_lo:[0,0,1] neg_hi:[0,0,1]
	v_pk_add_f32 v[16:17], v[12:13], v[16:17] neg_lo:[0,1] neg_hi:[0,1]
	v_pk_fma_f32 v[12:13], v[32:33], s[64:65], v[8:9] op_sel:[0,0,1] op_sel_hi:[1,0,0] neg_hi:[0,0,1]
	v_pk_fma_f32 v[36:37], v[38:39], s[72:73], v[36:37] op_sel:[0,0,1] op_sel_hi:[1,0,0] neg_lo:[0,0,1]
	v_pk_fma_f32 v[38:39], v[30:31], s[82:83], v[20:21] op_sel:[0,0,1] op_sel_hi:[1,0,0] neg_hi:[0,0,1]
	v_pk_add_f32 v[10:11], v[22:23], v[24:25] op_sel:[0,1] op_sel_hi:[1,0] neg_hi:[0,1]
	v_pk_fma_f32 v[12:13], v[32:33], s[82:83], v[12:13] op_sel:[0,0,1] op_sel_hi:[1,0,0] neg_lo:[0,0,1]
	v_pk_fma_f32 v[6:7], v[6:7], s[100:101], v[36:37] op_sel_hi:[1,0,1] neg_lo:[0,0,1] neg_hi:[0,0,1]
	v_pk_fma_f32 v[30:31], v[30:31], s[64:65], v[38:39] op_sel:[0,0,1] op_sel_hi:[1,0,0] neg_lo:[0,0,1]
	v_pk_add_f32 v[24:25], v[22:23], v[24:25] op_sel:[0,1] op_sel_hi:[1,0] neg_lo:[0,1]
	v_pk_fma_f32 v[8:9], v[8:9], s[100:101], v[12:13] op_sel_hi:[1,0,1] neg_lo:[0,0,1] neg_hi:[0,0,1]
	v_pk_add_f32 v[22:23], v[4:5], v[36:37]
	v_pk_fma_f32 v[20:21], v[20:21], s[100:101], v[30:31] op_sel_hi:[1,0,1] neg_lo:[0,0,1] neg_hi:[0,0,1]
	v_pk_add_f32 v[38:39], v[34:35], v[12:13]
	v_pk_add_f32 v[4:5], v[4:5], v[36:37] neg_lo:[0,1] neg_hi:[0,1]
	v_pk_add_f32 v[36:37], v[26:27], v[30:31]
	v_pk_add_f32 v[12:13], v[34:35], v[12:13] neg_lo:[0,1] neg_hi:[0,1]
	v_pk_add_f32 v[34:35], v[14:15], v[6:7] op_sel:[0,1] op_sel_hi:[1,0] neg_hi:[0,1]
	v_pk_add_f32 v[26:27], v[26:27], v[30:31] neg_lo:[0,1] neg_hi:[0,1]
	v_pk_add_f32 v[30:31], v[0:1], v[8:9] op_sel:[0,1] op_sel_hi:[1,0] neg_hi:[0,1]
	v_pk_add_f32 v[6:7], v[14:15], v[6:7] op_sel:[0,1] op_sel_hi:[1,0] neg_lo:[0,1]
	v_pk_add_f32 v[14:15], v[2:3], v[20:21] op_sel:[0,1] op_sel_hi:[1,0] neg_hi:[0,1]
	v_pk_add_f32 v[8:9], v[0:1], v[8:9] op_sel:[0,1] op_sel_hi:[1,0] neg_lo:[0,1]
	v_pk_add_f32 v[20:21], v[2:3], v[20:21] op_sel:[0,1] op_sel_hi:[1,0] neg_lo:[0,1]
	v_pk_mul_f32 v[2:3], v[38:39], v[232:233] op_sel:[0,1] op_sel_hi:[1,1]
	v_pk_mul_f32 v[0:1], v[22:23], v[234:235] op_sel:[0,1] op_sel_hi:[1,1]
	v_pk_fma_f32 v[2:3], v[38:39], v[232:233], v[2:3] op_sel:[0,0,1] op_sel_hi:[1,0,0] neg_lo:[0,0,1]
	v_pk_mul_f32 v[38:39], v[36:37], v[208:209] op_sel:[0,1] op_sel_hi:[1,1]
	v_pk_fma_f32 v[22:23], v[22:23], v[234:235], v[0:1] op_sel:[0,0,1] op_sel_hi:[1,0,0] neg_lo:[0,0,1]
	v_pk_mul_f32 v[0:1], v[10:11], v[210:211] op_sel:[0,1] op_sel_hi:[1,1]
	v_pk_fma_f32 v[36:37], v[36:37], v[208:209], v[38:39] op_sel:[0,0,1] op_sel_hi:[1,0,0] neg_lo:[0,0,1]
	v_pk_mul_f32 v[38:39], v[30:31], v[204:205] op_sel:[0,1] op_sel_hi:[1,1]
	v_pk_fma_f32 v[0:1], v[10:11], v[210:211], v[0:1] op_sel:[0,0,1] op_sel_hi:[1,0,0] neg_lo:[0,0,1]
; #define LAS __attribute__((address_space(3)))
; __device__ __forceinline__ f32x2 cmul(f32x2 a, f32x2 b) { return (f32x2){a.x * b.x - a.y * b.y, a.x * b.y + a.y * b.x}; }
; template <bool INV> __device__ __forceinline__ void bfly16_tab(f32x2 (&x)[16], const LAS f32x2* T, int tstride, int j) {
;     if (INV) {
; #pragma unroll
;         for (int q = 1; q < 16; ++q) { f32x2 p = T[q * tstride + j]; p.y = -p.y; x[q] = cmul(x[q], p); } }
;     dft16<INV>(x);
;     if (!INV) {
; #pragma unroll
;         for (int r = 1; r < 16; ++r) { const f32x2 p = T[r * tstride + j]; x[4 * (r & 3) + (r >> 2)] = cmul(x[4 * (r & 3) + (r >> 2)], p); } }
; }
; template <bool INV> __device__ __forceinline__ void pass16_s64(LAS f32x2* X, const LAS f32x2* TH, int base, int j) {
;     f32x2 x[16];
; #pragma unroll
;     for (int q = 0; q < 16; ++q) x[q] = X[base + q * 68];
;     bfly16_tab<INV>(x, TH - 2048, 64, j);
; #pragma unroll
;     for (int c = 0; c < 4; ++c)
; #pragma unroll
;         for (int d = 0; d < 4; ++d) X[base + (c + 4 * d) * 68] = x[4 * c + d];
; }
; template <bool INV> __device__ __forceinline__ void pass16_s4(LAS f32x2* X, const LAS f32x2* TH, const LAS f32x2* TL, int tid) {
; #pragma unroll 1
;     for (int s = 0; s < 2; ++s) {
;         const int b = tid + NTHR * s, blk = b >> 2, jj = b & 3;
;         LAS f32x2* P = X + blk * 68 + jj;
;         f32x2 x[16];
; #pragma unroll
;         for (int q = 0; q < 16; ++q) x[q] = P[4 * q];
;         bfly16_tab<INV>(x, TH - 1024, 4, jj);
	v_pk_mul_f32 v[10:11], v[34:35], v[206:207] op_sel:[0,1] op_sel_hi:[1,1]
	v_pk_fma_f32 v[30:31], v[30:31], v[204:205], v[38:39] op_sel:[0,0,1] op_sel_hi:[1,0,0] neg_lo:[0,0,1]
	v_pk_mul_f32 v[38:39], v[14:15], v[200:201] op_sel:[0,1] op_sel_hi:[1,1]
	v_pk_fma_f32 v[10:11], v[34:35], v[206:207], v[10:11] op_sel:[0,0,1] op_sel_hi:[1,0,0] neg_lo:[0,0,1]
	v_pk_mul_f32 v[34:35], v[16:17], v[202:203] op_sel:[0,1] op_sel_hi:[1,1]
	v_pk_fma_f32 v[38:39], v[14:15], v[200:201], v[38:39] op_sel:[0,0,1] op_sel_hi:[1,0,0] neg_lo:[0,0,1]
	v_pk_mul_f32 v[14:15], v[12:13], v[196:197] op_sel:[0,1] op_sel_hi:[1,1]
	v_pk_fma_f32 v[34:35], v[16:17], v[202:203], v[34:35] op_sel:[0,0,1] op_sel_hi:[1,0,0] neg_lo:[0,0,1]
	v_pk_mul_f32 v[16:17], v[4:5], v[198:199] op_sel:[0,1] op_sel_hi:[1,1]
	v_pk_fma_f32 v[14:15], v[12:13], v[196:197], v[14:15] op_sel:[0,0,1] op_sel_hi:[1,0,0] neg_lo:[0,0,1]
	v_pk_mul_f32 v[12:13], v[26:27], v[192:193] op_sel:[0,1] op_sel_hi:[1,1]
	v_pk_fma_f32 v[16:17], v[4:5], v[198:199], v[16:17] op_sel:[0,0,1] op_sel_hi:[1,0,0] neg_lo:[0,0,1]
	v_pk_mul_f32 v[4:5], v[24:25], v[194:195] op_sel:[0,1] op_sel_hi:[1,1]
	v_pk_fma_f32 v[26:27], v[26:27], v[192:193], v[12:13] op_sel:[0,0,1] op_sel_hi:[1,0,0] neg_lo:[0,0,1]
	v_pk_mul_f32 v[12:13], v[8:9], v[188:189] op_sel:[0,1] op_sel_hi:[1,1]
	v_pk_fma_f32 v[4:5], v[24:25], v[194:195], v[4:5] op_sel:[0,0,1] op_sel_hi:[1,0,0] neg_lo:[0,0,1]
	v_pk_mul_f32 v[24:25], v[6:7], v[190:191] op_sel:[0,1] op_sel_hi:[1,1]
	v_pk_fma_f32 v[12:13], v[8:9], v[188:189], v[12:13] op_sel:[0,0,1] op_sel_hi:[1,0,0] neg_lo:[0,0,1]
	v_pk_mul_f32 v[8:9], v[20:21], v[186:187] op_sel:[0,1] op_sel_hi:[1,1]
	v_pk_fma_f32 v[6:7], v[6:7], v[190:191], v[24:25] op_sel:[0,0,1] op_sel_hi:[1,0,0] neg_lo:[0,0,1]
	v_pk_fma_f32 v[20:21], v[20:21], v[186:187], v[8:9] op_sel:[0,0,1] op_sel_hi:[1,0,0] neg_lo:[0,0,1]
	ds_write_b64 v151, v[28:29] offset:0
	ds_write_b64 v151, v[2:3] offset:544
	ds_write_b64 v151, v[22:23] offset:1088
	ds_write_b64 v151, v[36:37] offset:1632
	ds_write_b64 v151, v[0:1] offset:2176
	ds_write_b64 v151, v[30:31] offset:2720
	ds_write_b64 v151, v[10:11] offset:3264
	ds_write_b64 v151, v[38:39] offset:3808
	ds_write_b64 v151, v[34:35] offset:4352
	ds_write_b64 v151, v[14:15] offset:4896
	ds_write_b64 v151, v[16:17] offset:5440
	ds_write_b64 v151, v[26:27] offset:5984
	ds_write_b64 v151, v[4:5] offset:6528
	ds_write_b64 v151, v[12:13] offset:7072
	ds_write_b64 v151, v[6:7] offset:7616
	ds_write_b64 v151, v[20:21] offset:8160
	s_cbranch_scc1 .LBB0_698
	s_waitcnt lgkmcnt(0)
	s_barrier
	s_mov_b32 s0, 0
	s_mov_b64 s[36:37], -1
	ds_read2_b64 v[232:235], v141 offset0:4 offset1:8
	ds_read2_b64 v[208:211], v141 offset0:12 offset1:16
	ds_read2_b64 v[204:207], v141 offset0:20 offset1:24
	ds_read2_b64 v[200:203], v141 offset0:28 offset1:32
	ds_read2_b64 v[196:199], v141 offset0:36 offset1:40
	ds_read2_b64 v[192:195], v141 offset0:44 offset1:48
	ds_read2_b64 v[188:191], v141 offset0:52 offset1:56
	ds_read_b64 v[186:187], v141 offset:480
.LBB0_700:
	v_add_u32_e32 v128, s0, v140
	v_lshrrev_b32_e32 v147, 2, v128
	v_mad_u32_u24 v151, v147, s43, v144
	ds_read_b64 v[0:1], v151 offset:0
	ds_read_b64 v[2:3], v151 offset:256
	ds_read_b64 v[4:5], v151 offset:32
	ds_read_b64 v[6:7], v151 offset:288
	ds_read_b64 v[8:9], v151 offset:64
	ds_read_b64 v[10:11], v151 offset:320
	ds_read_b64 v[12:13], v151 offset:96
	ds_read_b64 v[14:15], v151 offset:352
	ds_read_b64 v[16:17], v151 offset:128
	ds_read_b64 v[18:19], v151 offset:384
	ds_read_b64 v[20:21], v151 offset:160
	ds_read_b64 v[22:23], v151 offset:416
	ds_read_b64 v[24:25], v151 offset:192
	ds_read_b64 v[26:27], v151 offset:448
	ds_read_b64 v[28:29], v151 offset:224
	ds_read_b64 v[30:31], v151 offset:480
	s_cmp_eq_u32 s0, 0
	s_movk_i32 s0, 0x200
	s_mov_b64 s[36:37], 0
	s_waitcnt lgkmcnt(14)
	v_pk_add_f32 v[32:33], v[0:1], v[2:3]
	s_waitcnt lgkmcnt(12)
	v_pk_add_f32 v[34:35], v[4:5], v[6:7]
	s_waitcnt lgkmcnt(10)
	v_pk_add_f32 v[36:37], v[8:9], v[10:11]
	s_waitcnt lgkmcnt(8)
	v_pk_add_f32 v[38:39], v[12:13], v[14:15]
	v_pk_add_f32 v[0:1], v[0:1], v[2:3] neg_lo:[0,1] neg_hi:[0,1]
	v_pk_add_f32 v[6:7], v[4:5], v[6:7] neg_lo:[0,1] neg_hi:[0,1]
	v_pk_add_f32 v[8:9], v[8:9], v[10:11] neg_lo:[0,1] neg_hi:[0,1]
	v_pk_add_f32 v[12:13], v[12:13], v[14:15] neg_lo:[0,1] neg_hi:[0,1]
	s_waitcnt lgkmcnt(6)
	v_pk_add_f32 v[14:15], v[16:17], v[18:19]
	s_waitcnt lgkmcnt(4)
	v_pk_add_f32 v[10:11], v[20:21], v[22:23]
	s_waitcnt lgkmcnt(2)
	v_pk_add_f32 v[4:5], v[24:25], v[26:27]
	s_waitcnt lgkmcnt(0)
; #define LAS __attribute__((address_space(3)))
; __device__ __forceinline__ f32x2 cmul(f32x2 a, f32x2 b) { return (f32x2){a.x * b.x - a.y * b.y, a.x * b.y + a.y * b.x}; }
; template <bool INV> __device__ __forceinline__ void dft16(f32x2 (&x)[16]) {
; #pragma unroll
;     for (int b = 0; b < 4; ++b) r4<INV>(x[b], x[4 + b], x[8 + b], x[12 + b]);
;     const float sg = INV ? -1.f : 1.f;
;     const f32x2 W1 = {0.92387953251f, -0.38268343236f * sg}, W2 = {0.70710678118f, -0.70710678118f * sg}, W3 = {0.38268343236f, -0.92387953251f * sg},
;                 W4 = {0.f, -1.f * sg}, W6 = {-0.70710678118f, -0.70710678118f * sg}, W9 = {-0.92387953251f, 0.38268343236f * sg};
;     x[5] = cmul(x[5], W1); x[9] = cmul(x[9], W2); x[13] = cmul(x[13], W3);
;     x[6] = cmul(x[6], W2); x[10] = cmul(x[10], W4); x[14] = cmul(x[14], W6);
;     x[7] = cmul(x[7], W3); x[11] = cmul(x[11], W6); x[15] = cmul(x[15], W9);
; #pragma unroll
;     for (int c = 0; c < 4; ++c) r4<INV>(x[4 * c], x[4 * c + 1], x[4 * c + 2], x[4 * c + 3]);
; }
; template <bool INV> __device__ __forceinline__ void pass16_s4(LAS f32x2* X, const LAS f32x2* TH, const LAS f32x2* TL, int tid) {
; #pragma unroll 1
;     for (int s = 0; s < 2; ++s) {
;         const int b = tid + NTHR * s, blk = b >> 2, jj = b & 3;
;         LAS f32x2* P = X + blk * 68 + jj;
;         f32x2 x[16];
; #pragma unroll
;         for (int q = 0; q < 16; ++q) x[q] = P[4 * q];
;         bfly16_tab<INV>(x, TH - 1024, 4, jj);
; #pragma unroll
;         for (int c = 0; c < 4; ++c)
; #pragma unroll
;             for (int d = 0; d < 4; ++d) P[4 * (c + 4 * d)] = x[4 * c + d];
;     }
; }
	v_pk_add_f32 v[2:3], v[28:29], v[30:31]
	v_pk_add_f32 v[18:19], v[16:17], v[18:19] neg_lo:[0,1] neg_hi:[0,1]
	v_pk_add_f32 v[22:23], v[20:21], v[22:23] neg_lo:[0,1] neg_hi:[0,1]
	v_pk_add_f32 v[26:27], v[24:25], v[26:27] neg_lo:[0,1] neg_hi:[0,1]
	v_pk_add_f32 v[30:31], v[28:29], v[30:31] neg_lo:[0,1] neg_hi:[0,1]
	v_pk_add_f32 v[28:29], v[32:33], v[14:15]
	v_pk_add_f32 v[24:25], v[34:35], v[10:11]
	v_pk_add_f32 v[20:21], v[36:37], v[4:5]
	v_pk_add_f32 v[16:17], v[38:39], v[2:3]
	v_pk_add_f32 v[14:15], v[32:33], v[14:15] neg_lo:[0,1] neg_hi:[0,1]
	v_pk_add_f32 v[34:35], v[34:35], v[10:11] neg_lo:[0,1] neg_hi:[0,1]
	v_pk_add_f32 v[36:37], v[36:37], v[4:5] neg_lo:[0,1] neg_hi:[0,1]
	v_pk_add_f32 v[2:3], v[38:39], v[2:3] neg_lo:[0,1] neg_hi:[0,1]
	v_pk_add_f32 v[38:39], v[0:1], v[18:19] op_sel:[0,1] op_sel_hi:[1,0] neg_hi:[0,1]
	v_pk_add_f32 v[4:5], v[6:7], v[22:23] op_sel:[0,1] op_sel_hi:[1,0] neg_hi:[0,1]
	v_pk_add_f32 v[10:11], v[8:9], v[26:27] op_sel:[0,1] op_sel_hi:[1,0] neg_hi:[0,1]
	v_pk_add_f32 v[32:33], v[12:13], v[30:31] op_sel:[0,1] op_sel_hi:[1,0] neg_hi:[0,1]
	v_pk_add_f32 v[0:1], v[0:1], v[18:19] op_sel:[0,1] op_sel_hi:[1,0] neg_lo:[0,1]
	v_pk_add_f32 v[6:7], v[6:7], v[22:23] op_sel:[0,1] op_sel_hi:[1,0] neg_lo:[0,1]
	v_pk_add_f32 v[26:27], v[8:9], v[26:27] op_sel:[0,1] op_sel_hi:[1,0] neg_lo:[0,1]
	v_pk_add_f32 v[12:13], v[12:13], v[30:31] op_sel:[0,1] op_sel_hi:[1,0] neg_lo:[0,1]
	v_pk_add_f32 v[30:31], v[28:29], v[20:21]
	v_pk_mul_f32 v[8:9], v[4:5], s[70:71] op_sel_hi:[1,0]
	v_pk_mul_f32 v[22:23], v[34:35], s[72:73] op_sel_hi:[1,0]
	v_pk_mul_f32 v[18:19], v[6:7], s[64:65] op_sel_hi:[1,0]
	v_pk_add_f32 v[28:29], v[28:29], v[20:21] neg_lo:[0,1] neg_hi:[0,1]
	v_pk_fma_f32 v[4:5], v[4:5], s[44:45], v[8:9] op_sel:[0,0,1] op_sel_hi:[1,0,0] neg_lo:[0,0,1]
	v_pk_fma_f32 v[34:35], v[34:35], s[76:77], v[22:23] op_sel:[0,0,1] op_sel_hi:[1,0,0] neg_lo:[0,0,1]
	v_pk_fma_f32 v[18:19], v[6:7], s[82:83], v[18:19] op_sel:[0,0,1] op_sel_hi:[1,0,0] neg_lo:[0,0,1]
	v_pk_add_f32 v[6:7], v[24:25], v[16:17]
	v_pk_fma_f32 v[22:23], v[10:11], s[72:73], v[38:39] op_sel:[0,0,1] op_sel_hi:[1,0,0] neg_hi:[0,0,1]
	v_pk_add_f32 v[8:9], v[14:15], v[36:37] op_sel:[0,1] op_sel_hi:[1,0] neg_hi:[0,1]
	v_pk_fma_f32 v[20:21], v[26:27], s[72:73], v[0:1] op_sel:[0,0,1] op_sel_hi:[1,0,0] neg_hi:[0,0,1]
	v_pk_add_f32 v[16:17], v[24:25], v[16:17] neg_lo:[0,1] neg_hi:[0,1]
	v_pk_fma_f32 v[10:11], v[10:11], s[76:77], v[22:23] op_sel:[0,0,1] op_sel_hi:[1,0,0] neg_lo:[0,0,1]
	v_pk_add_f32 v[14:15], v[14:15], v[36:37] op_sel:[0,1] op_sel_hi:[1,0] neg_lo:[0,1]
	v_pk_fma_f32 v[26:27], v[26:27], s[72:73], v[20:21] op_sel:[0,0,1] op_sel_hi:[1,0,0] neg_lo:[0,0,1]
	v_pk_add_f32 v[20:21], v[30:31], v[6:7]
	v_pk_fma_f32 v[38:39], v[38:39], s[100:101], v[10:11] op_sel_hi:[1,0,1] neg_lo:[0,0,1] neg_hi:[0,0,1]
	v_pk_fma_f32 v[36:37], v[2:3], s[72:73], v[34:35] op_sel:[0,0,1] op_sel_hi:[1,0,0] neg_hi:[0,0,1]
	v_pk_fma_f32 v[0:1], v[0:1], s[100:101], v[26:27] op_sel_hi:[1,0,1] neg_lo:[0,0,1] neg_hi:[0,0,1]
	v_pk_add_f32 v[30:31], v[30:31], v[6:7] neg_lo:[0,1] neg_hi:[0,1]
	v_pk_fma_f32 v[6:7], v[32:33], s[64:65], v[4:5] op_sel:[0,0,1] op_sel_hi:[1,0,0] neg_hi:[0,0,1]
	v_pk_fma_f32 v[2:3], v[2:3], s[72:73], v[36:37] op_sel:[0,0,1] op_sel_hi:[1,0,0] neg_lo:[0,0,1]
	v_pk_fma_f32 v[36:37], v[12:13], s[82:83], v[18:19] op_sel:[0,0,1] op_sel_hi:[1,0,0] neg_hi:[0,0,1]
	v_pk_add_f32 v[22:23], v[28:29], v[16:17] op_sel:[0,1] op_sel_hi:[1,0] neg_hi:[0,1]
	v_pk_fma_f32 v[6:7], v[32:33], s[82:83], v[6:7] op_sel:[0,0,1] op_sel_hi:[1,0,0] neg_lo:[0,0,1]
	v_pk_fma_f32 v[34:35], v[34:35], s[100:101], v[2:3] op_sel_hi:[1,0,1] neg_lo:[0,0,1] neg_hi:[0,0,1]
	v_pk_fma_f32 v[36:37], v[12:13], s[64:65], v[36:37] op_sel:[0,0,1] op_sel_hi:[1,0,0] neg_lo:[0,0,1]
	v_pk_add_f32 v[16:17], v[28:29], v[16:17] op_sel:[0,1] op_sel_hi:[1,0] neg_lo:[0,1]
	v_pk_fma_f32 v[4:5], v[4:5], s[100:101], v[6:7] op_sel_hi:[1,0,1] neg_lo:[0,0,1] neg_hi:[0,0,1]
	v_pk_add_f32 v[28:29], v[8:9], v[2:3]
	v_pk_fma_f32 v[18:19], v[18:19], s[100:101], v[36:37] op_sel_hi:[1,0,1] neg_lo:[0,0,1] neg_hi:[0,0,1]
	v_pk_add_f32 v[12:13], v[10:11], v[6:7]
	v_pk_add_f32 v[8:9], v[8:9], v[2:3] neg_lo:[0,1] neg_hi:[0,1]
	v_pk_add_f32 v[2:3], v[26:27], v[36:37]
	v_pk_add_f32 v[6:7], v[10:11], v[6:7] neg_lo:[0,1] neg_hi:[0,1]
	v_pk_add_f32 v[10:11], v[14:15], v[34:35] op_sel:[0,1] op_sel_hi:[1,0] neg_hi:[0,1]
	v_pk_add_f32 v[26:27], v[26:27], v[36:37] neg_lo:[0,1] neg_hi:[0,1]
	v_pk_add_f32 v[36:37], v[38:39], v[4:5] op_sel:[0,1] op_sel_hi:[1,0] neg_hi:[0,1]
	v_pk_add_f32 v[34:35], v[14:15], v[34:35] op_sel:[0,1] op_sel_hi:[1,0] neg_lo:[0,1]
	v_pk_add_f32 v[14:15], v[0:1], v[18:19] op_sel:[0,1] op_sel_hi:[1,0] neg_hi:[0,1]
	v_pk_add_f32 v[38:39], v[38:39], v[4:5] op_sel:[0,1] op_sel_hi:[1,0] neg_lo:[0,1]
	v_pk_add_f32 v[18:19], v[0:1], v[18:19] op_sel:[0,1] op_sel_hi:[1,0] neg_lo:[0,1]
	v_pk_mul_f32 v[0:1], v[12:13], v[232:233] op_sel:[0,1] op_sel_hi:[1,1]
	v_pk_mul_f32 v[4:5], v[28:29], v[234:235] op_sel:[0,1] op_sel_hi:[1,1]
	v_pk_fma_f32 v[0:1], v[12:13], v[232:233], v[0:1] op_sel:[0,0,1] op_sel_hi:[1,0,0] neg_lo:[0,0,1]
	v_pk_mul_f32 v[12:13], v[2:3], v[208:209] op_sel:[0,1] op_sel_hi:[1,1]
	v_pk_fma_f32 v[28:29], v[28:29], v[234:235], v[4:5] op_sel:[0,0,1] op_sel_hi:[1,0,0] neg_lo:[0,0,1]
	v_pk_mul_f32 v[4:5], v[22:23], v[210:211] op_sel:[0,1] op_sel_hi:[1,1]
; #define LAS __attribute__((address_space(3)))
; __device__ __forceinline__ float lane_read(float v, int src_lane) { return __builtin_bit_cast(float, __builtin_amdgcn_ds_bpermute(src_lane << 2, __builtin_bit_cast(int, v))); }
; #define LDS_BARRIER() do { asm volatile("s_waitcnt lgkmcnt(0)" ::: "memory"); __builtin_amdgcn_s_barrier(); asm volatile("" ::: "memory"); } while (0)
; #define HP_BEGIN(id) unsigned long long hp0_ = 0; if ((id) == PROBE_TIME_PHASE) { __syncthreads(); hp0_ = __builtin_amdgcn_s_memrealtime(); }
; #define LT() ({ int lt_ = tid; asm volatile("" : "+v"(lt_)); lt_; })
; template <bool INV> __device__ __forceinline__ void pass16_s4(LAS f32x2* X, const LAS f32x2* TH, const LAS f32x2* TL, int tid) {
;     ...
; #pragma unroll
;         for (int c = 0; c < 4; ++c)
; #pragma unroll
;             for (int d = 0; d < 4; ++d) P[4 * (c + 4 * d)] = x[4 * c + d];
;     }
; }
; __device__ __forceinline__ void hyena_latent(Frame& F, int l, int ch, LAS f32x2* X, const LAS f32x2* TH, const LAS f32x2* TL, GAS f32x2* KS, const LAS float* CT  , bool wr = true) {
;     ...
;             fft_fwd_head(X, TH, TL, tid);
; #pragma unroll
;             for (int i = 0; i < 8; ++i) { const int b = LT() + NTHR * i; const LAS f32x4* P = (const LAS f32x4*)(X + 4 * b + ((b >> 4) << 2)); const f32x4 u = P[0], v = P[1];
;                 f32x2 x0 = {u.x, u.y}, x1 = {u.z, u.w}, x2 = {v.x, v.y}, x3 = {v.z, v.w}; r4<false>(x0, x1, x2, x3);
;                 kreg[2 * i] = (f32x4){x0.x, x0.y, x1.x, x1.y}; kreg[2 * i + 1] = (f32x4){x2.x, x2.y, x3.x, x3.y}; }
;             LDS_BARRIER();
;             HP_END(31) }
;             { HP_BEGIN(32)
; #pragma unroll
;             for (int i = 0; i < 8; ++i) { const int g = LT() + NTHR * i, n0 = 4 * g;
;                 f32x4 z0 = pc0[i], z1 = pc1[i];
;                 if (o == 0) { const f32x4 c = pc0[i], d = pc1[i]; const int ln = F.lane;
;                     float l0 = lane_read(c.w, ln - 1), r0 = lane_read(c.x, ln + 1), l1 = lane_read(d.w, ln - 1), r1 = lane_read(d.x, ln + 1);
;                     if (ln == 0) { l0 = n0 > 0 ? hv[n0 - 1] : 0.f; l1 = n0 > 0 ? hv[SEQ + n0 - 1] : 0.f; }
;                     if (ln == 63) { r0 = n0 + 4 < SEQ ? hv[n0 + 4] : 0.f; r1 = n0 + 4 < SEQ ? hv[SEQ + n0 + 4] : 0.f; }
	v_pk_fma_f32 v[12:13], v[2:3], v[208:209], v[12:13] op_sel:[0,0,1] op_sel_hi:[1,0,0] neg_lo:[0,0,1]
	v_pk_mul_f32 v[2:3], v[36:37], v[204:205] op_sel:[0,1] op_sel_hi:[1,1]
	v_pk_fma_f32 v[4:5], v[22:23], v[210:211], v[4:5] op_sel:[0,0,1] op_sel_hi:[1,0,0] neg_lo:[0,0,1]
	v_pk_mul_f32 v[22:23], v[10:11], v[206:207] op_sel:[0,1] op_sel_hi:[1,1]
	v_pk_fma_f32 v[2:3], v[36:37], v[204:205], v[2:3] op_sel:[0,0,1] op_sel_hi:[1,0,0] neg_lo:[0,0,1]
	v_pk_mul_f32 v[36:37], v[14:15], v[200:201] op_sel:[0,1] op_sel_hi:[1,1]
	v_pk_fma_f32 v[22:23], v[10:11], v[206:207], v[22:23] op_sel:[0,0,1] op_sel_hi:[1,0,0] neg_lo:[0,0,1]
	v_pk_mul_f32 v[10:11], v[30:31], v[202:203] op_sel:[0,1] op_sel_hi:[1,1]
	v_pk_fma_f32 v[36:37], v[14:15], v[200:201], v[36:37] op_sel:[0,0,1] op_sel_hi:[1,0,0] neg_lo:[0,0,1]
	v_pk_mul_f32 v[14:15], v[6:7], v[196:197] op_sel:[0,1] op_sel_hi:[1,1]
	v_pk_fma_f32 v[30:31], v[30:31], v[202:203], v[10:11] op_sel:[0,0,1] op_sel_hi:[1,0,0] neg_lo:[0,0,1]
	v_pk_mul_f32 v[10:11], v[8:9], v[198:199] op_sel:[0,1] op_sel_hi:[1,1]
	v_pk_fma_f32 v[14:15], v[6:7], v[196:197], v[14:15] op_sel:[0,0,1] op_sel_hi:[1,0,0] neg_lo:[0,0,1]
	v_pk_mul_f32 v[6:7], v[26:27], v[192:193] op_sel:[0,1] op_sel_hi:[1,1]
	v_pk_fma_f32 v[10:11], v[8:9], v[198:199], v[10:11] op_sel:[0,0,1] op_sel_hi:[1,0,0] neg_lo:[0,0,1]
	v_pk_mul_f32 v[8:9], v[16:17], v[194:195] op_sel:[0,1] op_sel_hi:[1,1]
	v_pk_fma_f32 v[6:7], v[26:27], v[192:193], v[6:7] op_sel:[0,0,1] op_sel_hi:[1,0,0] neg_lo:[0,0,1]
	v_pk_mul_f32 v[26:27], v[38:39], v[188:189] op_sel:[0,1] op_sel_hi:[1,1]
	v_pk_fma_f32 v[16:17], v[16:17], v[194:195], v[8:9] op_sel:[0,0,1] op_sel_hi:[1,0,0] neg_lo:[0,0,1]
	v_pk_mul_f32 v[8:9], v[34:35], v[190:191] op_sel:[0,1] op_sel_hi:[1,1]
	v_pk_fma_f32 v[38:39], v[38:39], v[188:189], v[26:27] op_sel:[0,0,1] op_sel_hi:[1,0,0] neg_lo:[0,0,1]
	v_pk_mul_f32 v[26:27], v[18:19], v[186:187] op_sel:[0,1] op_sel_hi:[1,1]
	v_pk_fma_f32 v[8:9], v[34:35], v[190:191], v[8:9] op_sel:[0,0,1] op_sel_hi:[1,0,0] neg_lo:[0,0,1]
	v_pk_fma_f32 v[18:19], v[18:19], v[186:187], v[26:27] op_sel:[0,0,1] op_sel_hi:[1,0,0] neg_lo:[0,0,1]
	ds_write_b64 v151, v[20:21] offset:0
	ds_write_b64 v151, v[0:1] offset:32
	ds_write_b64 v151, v[28:29] offset:64
	ds_write_b64 v151, v[12:13] offset:96
	ds_write_b64 v151, v[4:5] offset:128
	ds_write_b64 v151, v[2:3] offset:160
	ds_write_b64 v151, v[22:23] offset:192
	ds_write_b64 v151, v[36:37] offset:224
	ds_write_b64 v151, v[30:31] offset:256
	ds_write_b64 v151, v[14:15] offset:288
	ds_write_b64 v151, v[10:11] offset:320
	ds_write_b64 v151, v[6:7] offset:352
	ds_write_b64 v151, v[16:17] offset:384
	ds_write_b64 v151, v[38:39] offset:416
	ds_write_b64 v151, v[8:9] offset:448
	ds_write_b64 v151, v[18:19] offset:480
	s_cbranch_scc1 .LBB0_700
	v_mov_b32_e32 v0, v140
	s_waitcnt lgkmcnt(0)
	s_barrier
	v_mov_b32_e32 v128, v140
	v_lshlrev_b32_e32 v1, 5, v0
	v_lshlrev_b32_e32 v0, 1, v0
	v_and_b32_e32 v0, 0xffffffe0, v0
	v_add3_u32 v0, 0, v1, v0
	ds_read_b128 v[56:59], v0
	ds_read_b128 v[60:63], v0 offset:16
	v_mov_b32_e32 v0, v140
	s_and_b64 vcc, s[26:27], exec
	v_add_u32_e32 v0, 0x200, v0
	v_lshlrev_b32_e32 v1, 5, v0
	v_lshlrev_b32_e32 v0, 1, v0
	v_and_b32_e32 v0, 0xffffffe0, v0
	v_add3_u32 v0, 0, v1, v0
	ds_read_b128 v[48:51], v0
	ds_read_b128 v[52:55], v0 offset:16
	v_mov_b32_e32 v0, v140
	s_nop 0
	v_add_u32_e32 v0, 0x400, v0
	v_lshlrev_b32_e32 v1, 5, v0
	v_lshlrev_b32_e32 v0, 1, v0
	v_and_b32_e32 v0, 0xffffffe0, v0
	v_add3_u32 v0, 0, v1, v0
	ds_read_b128 v[40:43], v0
	ds_read_b128 v[44:47], v0 offset:16
	v_mov_b32_e32 v0, v140
	s_nop 0
	v_add_u32_e32 v0, 0x600, v0
	v_lshlrev_b32_e32 v1, 5, v0
	v_lshlrev_b32_e32 v0, 1, v0
	v_and_b32_e32 v0, 0xffffffe0, v0
	v_add3_u32 v0, 0, v1, v0
	ds_read_b128 v[32:35], v0
	ds_read_b128 v[36:39], v0 offset:16
	v_mov_b32_e32 v0, v140
	s_nop 0
	v_add_u32_e32 v0, 0x800, v0
	v_lshlrev_b32_e32 v1, 5, v0
	v_lshlrev_b32_e32 v0, 1, v0
	v_and_b32_e32 v0, 0xffffffe0, v0
	v_add3_u32 v0, 0, v1, v0
	ds_read_b128 v[24:27], v0
	ds_read_b128 v[28:31], v0 offset:16
	v_mov_b32_e32 v0, v140
	s_nop 0
	v_add_u32_e32 v0, 0xa00, v0
	v_lshlrev_b32_e32 v1, 5, v0
	v_lshlrev_b32_e32 v0, 1, v0
	v_and_b32_e32 v0, 0xffffffe0, v0
	v_add3_u32 v0, 0, v1, v0
	ds_read_b128 v[12:15], v0
	ds_read_b128 v[20:23], v0 offset:16
	v_mov_b32_e32 v0, v140
	s_nop 0
	v_add_u32_e32 v0, 0xc00, v0
	v_lshlrev_b32_e32 v1, 5, v0
	v_lshlrev_b32_e32 v0, 1, v0
	v_and_b32_e32 v0, 0xffffffe0, v0
	v_add3_u32 v0, 0, v1, v0
	ds_read_b128 v[4:7], v0
	ds_read_b128 v[16:19], v0 offset:16
	v_mov_b32_e32 v0, v140
	s_nop 0
	v_add_u32_e32 v0, 0xe00, v0
	v_lshlrev_b32_e32 v1, 5, v0
	v_lshlrev_b32_e32 v0, 1, v0
	v_and_b32_e32 v0, 0xffffffe0, v0
	v_add3_u32 v8, 0, v1, v0
	ds_read_b128 v[0:3], v8
	ds_read_b128 v[8:11], v8 offset:16
	s_waitcnt lgkmcnt(0)
	s_barrier
	s_nop 0
	v_lshlrev_b32_e32 v176, 2, v128
	s_cbranch_vccz .LBB0_715
	s_waitcnt vmcnt(15)
	ds_bpermute_b32 v134, v143, v127
	ds_bpermute_b32 v133, v145, v124
	s_waitcnt vmcnt(14)
	ds_bpermute_b32 v130, v143, v123
	ds_bpermute_b32 v129, v145, v120
	s_and_saveexec_b64 s[36:37], s[8:9]
	s_cbranch_execz .LBB0_708
	v_cmp_lt_i32_e32 vcc, 0, v176
	s_waitcnt lgkmcnt(1)
	v_mov_b32_e32 v130, 0
	v_mov_b32_e32 v134, 0
	s_and_saveexec_b64 s[38:39], vcc
	s_cbranch_execz .LBB0_705
	v_lshl_add_u64 v[134:135], v[176:177], 2, s[20:21]
	global_load_dword v134, v[134:135], off offset:-4

; #define LAS __attribute__((address_space(3)))
; __device__ __forceinline__ f32x2 cmul(f32x2 a, f32x2 b) { return (f32x2){a.x * b.x - a.y * b.y, a.x * b.y + a.y * b.x}; }
; __device__ __forceinline__ f32x2 tw32k(const LAS f32x2* TH, const LAS f32x2* TL, int n) { return cmul(TH[n >> 7], TL[n & 127]); }
; template <bool INV> __device__ __forceinline__ void bfly16(f32x2 (&x)[16], const LAS f32x2* TH, const LAS f32x2* TL, int tw) {
;     f32x2 W = tw32k(TH, TL, tw); if (INV) W.y = -W.y;
;     if (INV) { f32x2 p = W;
; #pragma unroll
;         for (int q = 1; q < 16; ++q) { x[q] = cmul(x[q], p); if (q < 15) p = cmul(p, W); } }
;     dft16<INV>(x);
;     if (!INV) { f32x2 p = W;
; #pragma unroll
;         for (int r = 1; r < 16; ++r) { x[4 * (r & 3) + (r >> 2)] = cmul(x[4 * (r & 3) + (r >> 2)], p); if (r < 15) p = cmul(p, W); } }
; }
; template <bool INV> __device__ __forceinline__ void pass16(LAS f32x2* X, const LAS f32x2* TH, const LAS f32x2* TL, int base, int stride, int tw) {
;     f32x2 x[16];
; #pragma unroll
;     for (int q = 0; q < 16; ++q) x[q] = X[base + q * stride];
;     bfly16<INV>(x, TH, TL, tw);
; #pragma unroll
;     for (int c = 0; c < 4; ++c)
; #pragma unroll
;         for (int d = 0; d < 4; ++d) X[base + (c + 4 * d) * stride] = x[4 * c + d];
; }
.LBB0_846:
	v_add_u32_e32 v128, s0, v140
	v_lshrrev_b32_e32 v147, 6, v128
	v_and_b32_e32 v157, 63, v128
	v_lshlrev_b32_e32 v151, 5, v147
	v_lshlrev_b32_e32 v155, 3, v147
	v_lshlrev_b32_e32 v157, 4, v157
	v_lshl_add_u32 v151, v128, 3, v151
	v_add_u32_e32 v155, 0x26000, v155
	v_add_u32_e32 v157, 0x26400, v157
	v_add_u32_e32 v176, 0x11000, v151
	ds_read_b64 v[64:65], v155
	ds_read_b64 v[66:67], v157
	ds_read_b64 v[68:69], v151 offset:0
	ds_read_b64 v[70:71], v176 offset:0
	ds_read_b64 v[72:73], v151 offset:8704
	ds_read_b64 v[74:75], v176 offset:8704
	ds_read_b64 v[76:77], v151 offset:17408
	ds_read_b64 v[78:79], v176 offset:17408
	ds_read_b64 v[80:81], v151 offset:26112
	ds_read_b64 v[82:83], v176 offset:26112
	ds_read_b64 v[84:85], v151 offset:34816
	ds_read_b64 v[86:87], v176 offset:34816
	ds_read_b64 v[88:89], v151 offset:43520
	ds_read_b64 v[90:91], v176 offset:43520
	ds_read_b64 v[92:93], v151 offset:52224
	ds_read_b64 v[94:95], v176 offset:52224
	ds_read_b64 v[96:97], v151 offset:60928
	ds_read_b64 v[98:99], v176 offset:60928
	s_cmp_eq_u32 s0, 0
	s_movk_i32 s0, 0x200
	s_mov_b64 s[12:13], 0
	s_waitcnt lgkmcnt(15)
	v_pk_mul_f32 v[100:101], v[64:65], v[66:67] op_sel:[0,1] op_sel_hi:[1,1]
	s_nop 0
	v_pk_fma_f32 v[100:101], v[64:65], v[66:67], v[100:101] op_sel:[0,0,1] op_sel_hi:[1,0,0] neg_lo:[0,0,1]
	s_nop 0
	v_pk_mul_f32 v[66:67], v[100:101], v[100:101] op_sel:[0,1] op_sel_hi:[1,1]
	s_nop 0
	v_pk_fma_f32 v[66:67], v[100:101], v[100:101], v[66:67] op_sel:[0,0,1] op_sel_hi:[1,0,0] neg_lo:[0,0,1]
	s_nop 0
	v_pk_mul_f32 v[64:65], v[66:67], v[100:101] op_sel:[0,1] op_sel_hi:[1,1]
	v_pk_mul_f32 v[102:103], v[66:67], v[66:67] op_sel:[0,1] op_sel_hi:[1,1]
	v_pk_fma_f32 v[64:65], v[66:67], v[100:101], v[64:65] op_sel:[0,0,1] op_sel_hi:[1,0,0] neg_lo:[0,0,1]
	v_pk_fma_f32 v[102:103], v[66:67], v[66:67], v[102:103] op_sel:[0,0,1] op_sel_hi:[1,0,0] neg_lo:[0,0,1]
	s_nop 0
	v_pk_mul_f32 v[104:105], v[102:103], v[100:101] op_sel:[0,1] op_sel_hi:[1,1]
	v_pk_mul_f32 v[106:107], v[102:103], v[66:67] op_sel:[0,1] op_sel_hi:[1,1]
	v_pk_mul_f32 v[108:109], v[102:103], v[64:65] op_sel:[0,1] op_sel_hi:[1,1]
	v_pk_fma_f32 v[104:105], v[102:103], v[100:101], v[104:105] op_sel:[0,0,1] op_sel_hi:[1,0,0] neg_lo:[0,0,1]
	v_pk_fma_f32 v[106:107], v[102:103], v[66:67], v[106:107] op_sel:[0,0,1] op_sel_hi:[1,0,0] neg_lo:[0,0,1]
	v_pk_fma_f32 v[108:109], v[102:103], v[64:65], v[108:109] op_sel:[0,0,1] op_sel_hi:[1,0,0] neg_lo:[0,0,1]
	v_pk_mul_f32 v[110:111], v[102:103], v[102:103] op_sel:[0,1] op_sel_hi:[1,1]
	s_nop 0
	v_pk_fma_f32 v[110:111], v[102:103], v[102:103], v[110:111] op_sel:[0,0,1] op_sel_hi:[1,0,0] neg_lo:[0,0,1]
	s_nop 0
	v_pk_mul_f32 v[112:113], v[110:111], v[100:101] op_sel:[0,1] op_sel_hi:[1,1]
	v_pk_mul_f32 v[114:115], v[110:111], v[66:67] op_sel:[0,1] op_sel_hi:[1,1]
	v_pk_mul_f32 v[116:117], v[110:111], v[64:65] op_sel:[0,1] op_sel_hi:[1,1]
	v_pk_fma_f32 v[112:113], v[110:111], v[100:101], v[112:113] op_sel:[0,0,1] op_sel_hi:[1,0,0] neg_lo:[0,0,1]
	v_pk_fma_f32 v[114:115], v[110:111], v[66:67], v[114:115] op_sel:[0,0,1] op_sel_hi:[1,0,0] neg_lo:[0,0,1]
	v_pk_fma_f32 v[116:117], v[110:111], v[64:65], v[116:117] op_sel:[0,0,1] op_sel_hi:[1,0,0] neg_lo:[0,0,1]
	v_pk_mul_f32 v[118:119], v[110:111], v[102:103] op_sel:[0,1] op_sel_hi:[1,1]
	v_pk_mul_f32 v[120:121], v[110:111], v[104:105] op_sel:[0,1] op_sel_hi:[1,1]
	v_pk_mul_f32 v[122:123], v[110:111], v[106:107] op_sel:[0,1] op_sel_hi:[1,1]
	v_pk_fma_f32 v[118:119], v[110:111], v[102:103], v[118:119] op_sel:[0,0,1] op_sel_hi:[1,0,0] neg_lo:[0,0,1]
	v_pk_fma_f32 v[120:121], v[110:111], v[104:105], v[120:121] op_sel:[0,0,1] op_sel_hi:[1,0,0] neg_lo:[0,0,1]
	v_pk_fma_f32 v[122:123], v[110:111], v[106:107], v[122:123] op_sel:[0,0,1] op_sel_hi:[1,0,0] neg_lo:[0,0,1]
	v_pk_mul_f32 v[124:125], v[110:111], v[108:109] op_sel:[0,1] op_sel_hi:[1,1]
	s_nop 0
	v_pk_fma_f32 v[124:125], v[110:111], v[108:109], v[124:125] op_sel:[0,0,1] op_sel_hi:[1,0,0] neg_lo:[0,0,1]
	s_waitcnt lgkmcnt(14)
	v_pk_add_f32 v[126:127], v[68:69], v[70:71]
	s_waitcnt lgkmcnt(12)
	v_pk_add_f32 v[170:171], v[72:73], v[74:75]
	s_waitcnt lgkmcnt(10)
	v_pk_add_f32 v[172:173], v[76:77], v[78:79]
	s_waitcnt lgkmcnt(8)
	v_pk_add_f32 v[174:175], v[80:81], v[82:83]
	v_pk_add_f32 v[68:69], v[68:69], v[70:71] neg_lo:[0,1] neg_hi:[0,1]
	v_pk_add_f32 v[72:73], v[72:73], v[74:75] neg_lo:[0,1] neg_hi:[0,1]
	v_pk_add_f32 v[76:77], v[76:77], v[78:79] neg_lo:[0,1] neg_hi:[0,1]
	v_pk_add_f32 v[80:81], v[80:81], v[82:83] neg_lo:[0,1] neg_hi:[0,1]
	s_waitcnt lgkmcnt(6)
	v_pk_add_f32 v[82:83], v[84:85], v[86:87]
	s_waitcnt lgkmcnt(4)
	v_pk_add_f32 v[78:79], v[88:89], v[90:91]
	s_waitcnt lgkmcnt(2)
	v_pk_add_f32 v[74:75], v[92:93], v[94:95]
	s_waitcnt lgkmcnt(0)
; __device__ __forceinline__ f32x2 cmul(f32x2 a, f32x2 b) { return (f32x2){a.x * b.x - a.y * b.y, a.x * b.y + a.y * b.x}; }
; template <bool INV> __device__ __forceinline__ void dft16(f32x2 (&x)[16]) {
; #pragma unroll
;     for (int b = 0; b < 4; ++b) r4<INV>(x[b], x[4 + b], x[8 + b], x[12 + b]);
;     const float sg = INV ? -1.f : 1.f;
;     const f32x2 W1 = {0.92387953251f, -0.38268343236f * sg}, W2 = {0.70710678118f, -0.70710678118f * sg}, W3 = {0.38268343236f, -0.92387953251f * sg},
;                 W4 = {0.f, -1.f * sg}, W6 = {-0.70710678118f, -0.70710678118f * sg}, W9 = {-0.92387953251f, 0.38268343236f * sg};
;     x[5] = cmul(x[5], W1); x[9] = cmul(x[9], W2); x[13] = cmul(x[13], W3);
;     x[6] = cmul(x[6], W2); x[10] = cmul(x[10], W4); x[14] = cmul(x[14], W6);
;     x[7] = cmul(x[7], W3); x[11] = cmul(x[11], W6); x[15] = cmul(x[15], W9);
; #pragma unroll
;     for (int c = 0; c < 4; ++c) r4<INV>(x[4 * c], x[4 * c + 1], x[4 * c + 2], x[4 * c + 3]);
; }
	v_pk_add_f32 v[70:71], v[96:97], v[98:99]
	v_pk_add_f32 v[86:87], v[84:85], v[86:87] neg_lo:[0,1] neg_hi:[0,1]
	v_pk_add_f32 v[90:91], v[88:89], v[90:91] neg_lo:[0,1] neg_hi:[0,1]
	v_pk_add_f32 v[94:95], v[92:93], v[94:95] neg_lo:[0,1] neg_hi:[0,1]
	v_pk_add_f32 v[98:99], v[96:97], v[98:99] neg_lo:[0,1] neg_hi:[0,1]
	v_pk_add_f32 v[96:97], v[126:127], v[82:83]
	v_pk_add_f32 v[92:93], v[170:171], v[78:79]
	v_pk_add_f32 v[88:89], v[172:173], v[74:75]
	v_pk_add_f32 v[84:85], v[174:175], v[70:71]
	v_pk_add_f32 v[126:127], v[126:127], v[82:83] neg_lo:[0,1] neg_hi:[0,1]
	v_pk_add_f32 v[78:79], v[170:171], v[78:79] neg_lo:[0,1] neg_hi:[0,1]
	v_pk_add_f32 v[172:173], v[172:173], v[74:75] neg_lo:[0,1] neg_hi:[0,1]
	v_pk_add_f32 v[70:71], v[174:175], v[70:71] neg_lo:[0,1] neg_hi:[0,1]
	v_pk_add_f32 v[174:175], v[68:69], v[86:87] op_sel:[0,1] op_sel_hi:[1,0] neg_hi:[0,1]
	v_pk_add_f32 v[74:75], v[72:73], v[90:91] op_sel:[0,1] op_sel_hi:[1,0] neg_hi:[0,1]
	v_pk_add_f32 v[170:171], v[76:77], v[94:95] op_sel:[0,1] op_sel_hi:[1,0] neg_hi:[0,1]
	v_pk_add_f32 v[82:83], v[80:81], v[98:99] op_sel:[0,1] op_sel_hi:[1,0] neg_hi:[0,1]
	v_pk_add_f32 v[68:69], v[68:69], v[86:87] op_sel:[0,1] op_sel_hi:[1,0] neg_lo:[0,1]
	v_pk_add_f32 v[90:91], v[72:73], v[90:91] op_sel:[0,1] op_sel_hi:[1,0] neg_lo:[0,1]
	v_pk_add_f32 v[94:95], v[76:77], v[94:95] op_sel:[0,1] op_sel_hi:[1,0] neg_lo:[0,1]
	v_pk_add_f32 v[98:99], v[80:81], v[98:99] op_sel:[0,1] op_sel_hi:[1,0] neg_lo:[0,1]
	v_pk_add_f32 v[80:81], v[96:97], v[88:89]
	v_pk_mul_f32 v[76:77], v[74:75], s[70:71] op_sel_hi:[1,0]
	v_pk_mul_f32 v[72:73], v[78:79], s[72:73] op_sel_hi:[1,0]
	v_pk_mul_f32 v[86:87], v[90:91], s[64:65] op_sel_hi:[1,0]
	v_pk_add_f32 v[88:89], v[96:97], v[88:89] neg_lo:[0,1] neg_hi:[0,1]
	v_pk_fma_f32 v[76:77], v[74:75], s[44:45], v[76:77] op_sel:[0,0,1] op_sel_hi:[1,0,0] neg_lo:[0,0,1]
	v_pk_fma_f32 v[72:73], v[78:79], s[76:77], v[72:73] op_sel:[0,0,1] op_sel_hi:[1,0,0] neg_lo:[0,0,1]
	v_pk_fma_f32 v[90:91], v[90:91], s[82:83], v[86:87] op_sel:[0,0,1] op_sel_hi:[1,0,0] neg_lo:[0,0,1]
	v_pk_add_f32 v[86:87], v[92:93], v[84:85]
	v_pk_fma_f32 v[78:79], v[170:171], s[72:73], v[174:175] op_sel:[0,0,1] op_sel_hi:[1,0,0] neg_hi:[0,0,1]
	v_pk_add_f32 v[74:75], v[126:127], v[172:173] op_sel:[0,1] op_sel_hi:[1,0] neg_hi:[0,1]
	v_pk_fma_f32 v[96:97], v[94:95], s[72:73], v[68:69] op_sel:[0,0,1] op_sel_hi:[1,0,0] neg_hi:[0,0,1]
	v_pk_add_f32 v[92:93], v[92:93], v[84:85] neg_lo:[0,1] neg_hi:[0,1]
	v_pk_fma_f32 v[170:171], v[170:171], s[76:77], v[78:79] op_sel:[0,0,1] op_sel_hi:[1,0,0] neg_lo:[0,0,1]
	v_pk_add_f32 v[172:173], v[126:127], v[172:173] op_sel:[0,1] op_sel_hi:[1,0] neg_lo:[0,1]
	v_pk_fma_f32 v[94:95], v[94:95], s[72:73], v[96:97] op_sel:[0,0,1] op_sel_hi:[1,0,0] neg_lo:[0,0,1]
	v_pk_add_f32 v[96:97], v[80:81], v[86:87]
	v_pk_fma_f32 v[174:175], v[174:175], s[100:101], v[170:171] op_sel_hi:[1,0,1] neg_lo:[0,0,1] neg_hi:[0,0,1]
	v_pk_fma_f32 v[126:127], v[70:71], s[72:73], v[72:73] op_sel:[0,0,1] op_sel_hi:[1,0,0] neg_hi:[0,0,1]
	v_pk_fma_f32 v[68:69], v[68:69], s[100:101], v[94:95] op_sel_hi:[1,0,1] neg_lo:[0,0,1] neg_hi:[0,0,1]
	v_pk_add_f32 v[86:87], v[80:81], v[86:87] neg_lo:[0,1] neg_hi:[0,1]
	v_pk_fma_f32 v[80:81], v[82:83], s[64:65], v[76:77] op_sel:[0,0,1] op_sel_hi:[1,0,0] neg_hi:[0,0,1]
	v_pk_fma_f32 v[126:127], v[70:71], s[72:73], v[126:127] op_sel:[0,0,1] op_sel_hi:[1,0,0] neg_lo:[0,0,1]
	v_pk_fma_f32 v[70:71], v[98:99], s[82:83], v[90:91] op_sel:[0,0,1] op_sel_hi:[1,0,0] neg_hi:[0,0,1]
	v_pk_add_f32 v[78:79], v[88:89], v[92:93] op_sel:[0,1] op_sel_hi:[1,0] neg_hi:[0,1]
	v_pk_fma_f32 v[82:83], v[82:83], s[82:83], v[80:81] op_sel:[0,0,1] op_sel_hi:[1,0,0] neg_lo:[0,0,1]
	v_pk_fma_f32 v[72:73], v[72:73], s[100:101], v[126:127] op_sel_hi:[1,0,1] neg_lo:[0,0,1] neg_hi:[0,0,1]
	v_pk_fma_f32 v[98:99], v[98:99], s[64:65], v[70:71] op_sel:[0,0,1] op_sel_hi:[1,0,0] neg_lo:[0,0,1]
	v_pk_add_f32 v[92:93], v[88:89], v[92:93] op_sel:[0,1] op_sel_hi:[1,0] neg_lo:[0,1]
	v_pk_fma_f32 v[76:77], v[76:77], s[100:101], v[82:83] op_sel_hi:[1,0,1] neg_lo:[0,0,1] neg_hi:[0,0,1]
	v_pk_add_f32 v[88:89], v[74:75], v[126:127]
	v_pk_fma_f32 v[90:91], v[90:91], s[100:101], v[98:99] op_sel_hi:[1,0,1] neg_lo:[0,0,1] neg_hi:[0,0,1]
	v_pk_add_f32 v[70:71], v[170:171], v[82:83]
	v_pk_add_f32 v[74:75], v[74:75], v[126:127] neg_lo:[0,1] neg_hi:[0,1]
	v_pk_add_f32 v[126:127], v[94:95], v[98:99]
	v_pk_add_f32 v[82:83], v[170:171], v[82:83] neg_lo:[0,1] neg_hi:[0,1]
	v_pk_add_f32 v[170:171], v[172:173], v[72:73] op_sel:[0,1] op_sel_hi:[1,0] neg_hi:[0,1]
	v_pk_add_f32 v[94:95], v[94:95], v[98:99] neg_lo:[0,1] neg_hi:[0,1]
	v_pk_add_f32 v[98:99], v[174:175], v[76:77] op_sel:[0,1] op_sel_hi:[1,0] neg_hi:[0,1]
	v_pk_add_f32 v[72:73], v[172:173], v[72:73] op_sel:[0,1] op_sel_hi:[1,0] neg_lo:[0,1]
	v_pk_add_f32 v[172:173], v[68:69], v[90:91] op_sel:[0,1] op_sel_hi:[1,0] neg_hi:[0,1]
	v_pk_add_f32 v[174:175], v[174:175], v[76:77] op_sel:[0,1] op_sel_hi:[1,0] neg_lo:[0,1]
	v_pk_add_f32 v[90:91], v[68:69], v[90:91] op_sel:[0,1] op_sel_hi:[1,0] neg_lo:[0,1]
	v_pk_mul_f32 v[68:69], v[70:71], v[100:101] op_sel:[0,1] op_sel_hi:[1,1]
	v_pk_mul_f32 v[76:77], v[88:89], v[66:67] op_sel:[0,1] op_sel_hi:[1,1]
	v_pk_fma_f32 v[100:101], v[70:71], v[100:101], v[68:69] op_sel:[0,0,1] op_sel_hi:[1,0,0] neg_lo:[0,0,1]
	v_pk_mul_f32 v[68:69], v[126:127], v[64:65] op_sel:[0,1] op_sel_hi:[1,1]
	v_pk_fma_f32 v[88:89], v[88:89], v[66:67], v[76:77] op_sel:[0,0,1] op_sel_hi:[1,0,0] neg_lo:[0,0,1]
	v_pk_mul_f32 v[76:77], v[78:79], v[102:103] op_sel:[0,1] op_sel_hi:[1,1]
	v_pk_fma_f32 v[126:127], v[126:127], v[64:65], v[68:69] op_sel:[0,0,1] op_sel_hi:[1,0,0] neg_lo:[0,0,1]
; #define LAS __attribute__((address_space(3)))
; __device__ __forceinline__ f32x2 cmul(f32x2 a, f32x2 b) { return (f32x2){a.x * b.x - a.y * b.y, a.x * b.y + a.y * b.x}; }
; __device__ __forceinline__ f32x2 tw32k(const LAS f32x2* TH, const LAS f32x2* TL, int n) { return cmul(TH[n >> 7], TL[n & 127]); }
; template <bool INV> __device__ __forceinline__ void bfly16(f32x2 (&x)[16], const LAS f32x2* TH, const LAS f32x2* TL, int tw) {
;     f32x2 W = tw32k(TH, TL, tw); if (INV) W.y = -W.y;
;     if (INV) { f32x2 p = W;
; #pragma unroll
;         for (int q = 1; q < 16; ++q) { x[q] = cmul(x[q], p); if (q < 15) p = cmul(p, W); } }
;     dft16<INV>(x);
;     if (!INV) { f32x2 p = W;
; #pragma unroll
;         for (int r = 1; r < 16; ++r) { x[4 * (r & 3) + (r >> 2)] = cmul(x[4 * (r & 3) + (r >> 2)], p); if (r < 15) p = cmul(p, W); } }
; }
; template <bool INV> __device__ __forceinline__ void pass16_s64(LAS f32x2* X, const LAS f32x2* TH, int base, int j) {
;     f32x2 x[16];
; #pragma unroll
;     for (int q = 0; q < 16; ++q) x[q] = X[base + q * 68];
;     bfly16_tab<INV>(x, TH - 2048, 64, j);
; #pragma unroll
;     for (int c = 0; c < 4; ++c)
; #pragma unroll
;         for (int d = 0; d < 4; ++d) X[base + (c + 4 * d) * 68] = x[4 * c + d];
; }
	v_pk_mul_f32 v[68:69], v[98:99], v[104:105] op_sel:[0,1] op_sel_hi:[1,1]
	v_pk_fma_f32 v[76:77], v[78:79], v[102:103], v[76:77] op_sel:[0,0,1] op_sel_hi:[1,0,0] neg_lo:[0,0,1]
	v_pk_mul_f32 v[78:79], v[170:171], v[106:107] op_sel:[0,1] op_sel_hi:[1,1]
	v_pk_fma_f32 v[98:99], v[98:99], v[104:105], v[68:69] op_sel:[0,0,1] op_sel_hi:[1,0,0] neg_lo:[0,0,1]
	v_pk_mul_f32 v[68:69], v[172:173], v[108:109] op_sel:[0,1] op_sel_hi:[1,1]
	v_pk_fma_f32 v[106:107], v[170:171], v[106:107], v[78:79] op_sel:[0,0,1] op_sel_hi:[1,0,0] neg_lo:[0,0,1]
	v_pk_mul_f32 v[78:79], v[86:87], v[110:111] op_sel:[0,1] op_sel_hi:[1,1]
	v_pk_fma_f32 v[108:109], v[172:173], v[108:109], v[68:69] op_sel:[0,0,1] op_sel_hi:[1,0,0] neg_lo:[0,0,1]
	v_pk_mul_f32 v[68:69], v[82:83], v[112:113] op_sel:[0,1] op_sel_hi:[1,1]
	v_pk_fma_f32 v[78:79], v[86:87], v[110:111], v[78:79] op_sel:[0,0,1] op_sel_hi:[1,0,0] neg_lo:[0,0,1]
	v_pk_mul_f32 v[110:111], v[74:75], v[114:115] op_sel:[0,1] op_sel_hi:[1,1]
	v_pk_fma_f32 v[112:113], v[82:83], v[112:113], v[68:69] op_sel:[0,0,1] op_sel_hi:[1,0,0] neg_lo:[0,0,1]
	v_pk_mul_f32 v[68:69], v[94:95], v[116:117] op_sel:[0,1] op_sel_hi:[1,1]
	v_pk_fma_f32 v[114:115], v[74:75], v[114:115], v[110:111] op_sel:[0,0,1] op_sel_hi:[1,0,0] neg_lo:[0,0,1]
	v_pk_mul_f32 v[110:111], v[92:93], v[118:119] op_sel:[0,1] op_sel_hi:[1,1]
	v_pk_fma_f32 v[116:117], v[94:95], v[116:117], v[68:69] op_sel:[0,0,1] op_sel_hi:[1,0,0] neg_lo:[0,0,1]
	v_pk_mul_f32 v[94:95], v[174:175], v[120:121] op_sel:[0,1] op_sel_hi:[1,1]
	v_pk_fma_f32 v[110:111], v[92:93], v[118:119], v[110:111] op_sel:[0,0,1] op_sel_hi:[1,0,0] neg_lo:[0,0,1]
	v_pk_mul_f32 v[118:119], v[72:73], v[122:123] op_sel:[0,1] op_sel_hi:[1,1]
	v_pk_fma_f32 v[174:175], v[174:175], v[120:121], v[94:95] op_sel:[0,0,1] op_sel_hi:[1,0,0] neg_lo:[0,0,1]
	v_pk_mul_f32 v[94:95], v[90:91], v[124:125] op_sel:[0,1] op_sel_hi:[1,1]
	v_pk_fma_f32 v[72:73], v[72:73], v[122:123], v[118:119] op_sel:[0,0,1] op_sel_hi:[1,0,0] neg_lo:[0,0,1]
	v_pk_fma_f32 v[90:91], v[90:91], v[124:125], v[94:95] op_sel:[0,0,1] op_sel_hi:[1,0,0] neg_lo:[0,0,1]
	ds_write_b64 v151, v[96:97] offset:0
	ds_write_b64 v151, v[100:101] offset:8704
	ds_write_b64 v151, v[88:89] offset:17408
	ds_write_b64 v151, v[126:127] offset:26112
	ds_write_b64 v151, v[76:77] offset:34816
	ds_write_b64 v151, v[98:99] offset:43520
	ds_write_b64 v151, v[106:107] offset:52224
	ds_write_b64 v151, v[108:109] offset:60928
	ds_write_b64 v176, v[78:79] offset:0
	ds_write_b64 v176, v[112:113] offset:8704
	ds_write_b64 v176, v[114:115] offset:17408
	ds_write_b64 v176, v[116:117] offset:26112
	ds_write_b64 v176, v[110:111] offset:34816
	ds_write_b64 v176, v[174:175] offset:43520
	ds_write_b64 v176, v[72:73] offset:52224
	ds_write_b64 v176, v[90:91] offset:60928
	s_cbranch_scc1 .LBB0_846
	s_waitcnt lgkmcnt(0)
	s_barrier
	s_mov_b32 s0, 0
	s_mov_b64 s[12:13], -1
	ds_read2st64_b64 v[232:235], v139 offset0:1 offset1:2
	ds_read2st64_b64 v[208:211], v139 offset0:3 offset1:4
	ds_read2st64_b64 v[204:207], v139 offset0:5 offset1:6
	ds_read2st64_b64 v[200:203], v139 offset0:7 offset1:8
	ds_read2st64_b64 v[196:199], v139 offset0:9 offset1:10
	ds_read2st64_b64 v[192:195], v139 offset0:11 offset1:12
	ds_read2st64_b64 v[188:191], v139 offset0:13 offset1:14
	ds_read_b64 v[186:187], v139 offset:7680
.LBB0_848:
	v_add_u32_e32 v128, s0, v140
	v_lshrrev_b32_e32 v147, 6, v128
	v_mad_u32_u24 v151, v147, s77, v142
	ds_read_b64 v[64:65], v151 offset:0
	ds_read_b64 v[66:67], v151 offset:4352
	ds_read_b64 v[68:69], v151 offset:544
	ds_read_b64 v[70:71], v151 offset:4896
	ds_read_b64 v[72:73], v151 offset:1088
	ds_read_b64 v[74:75], v151 offset:5440
	ds_read_b64 v[76:77], v151 offset:1632
	ds_read_b64 v[78:79], v151 offset:5984
	ds_read_b64 v[80:81], v151 offset:2176
	ds_read_b64 v[82:83], v151 offset:6528
	ds_read_b64 v[84:85], v151 offset:2720
	ds_read_b64 v[86:87], v151 offset:7072
	ds_read_b64 v[88:89], v151 offset:3264
	ds_read_b64 v[90:91], v151 offset:7616
	ds_read_b64 v[92:93], v151 offset:3808
	ds_read_b64 v[94:95], v151 offset:8160
	s_cmp_eq_u32 s0, 0
	s_movk_i32 s0, 0x200
	s_mov_b64 s[12:13], 0
	s_waitcnt lgkmcnt(14)
	v_pk_add_f32 v[96:97], v[64:65], v[66:67]
	s_waitcnt lgkmcnt(12)
	v_pk_add_f32 v[98:99], v[68:69], v[70:71]
	s_waitcnt lgkmcnt(10)
	v_pk_add_f32 v[100:101], v[72:73], v[74:75]
	s_waitcnt lgkmcnt(8)
	v_pk_add_f32 v[102:103], v[76:77], v[78:79]
	v_pk_add_f32 v[66:67], v[64:65], v[66:67] neg_lo:[0,1] neg_hi:[0,1]
	v_pk_add_f32 v[68:69], v[68:69], v[70:71] neg_lo:[0,1] neg_hi:[0,1]
	v_pk_add_f32 v[74:75], v[72:73], v[74:75] neg_lo:[0,1] neg_hi:[0,1]
	v_pk_add_f32 v[78:79], v[76:77], v[78:79] neg_lo:[0,1] neg_hi:[0,1]
	s_waitcnt lgkmcnt(6)
	v_pk_add_f32 v[76:77], v[80:81], v[82:83]
	s_waitcnt lgkmcnt(4)
	v_pk_add_f32 v[72:73], v[84:85], v[86:87]
	s_waitcnt lgkmcnt(2)
	v_pk_add_f32 v[70:71], v[88:89], v[90:91]
	s_waitcnt lgkmcnt(0)
; #define LAS __attribute__((address_space(3)))
; __device__ __forceinline__ f32x2 cmul(f32x2 a, f32x2 b) { return (f32x2){a.x * b.x - a.y * b.y, a.x * b.y + a.y * b.x}; }
; template <bool INV> __device__ __forceinline__ void dft16(f32x2 (&x)[16]) {
; #pragma unroll
;     for (int b = 0; b < 4; ++b) r4<INV>(x[b], x[4 + b], x[8 + b], x[12 + b]);
;     const float sg = INV ? -1.f : 1.f;
;     const f32x2 W1 = {0.92387953251f, -0.38268343236f * sg}, W2 = {0.70710678118f, -0.70710678118f * sg}, W3 = {0.38268343236f, -0.92387953251f * sg},
;                 W4 = {0.f, -1.f * sg}, W6 = {-0.70710678118f, -0.70710678118f * sg}, W9 = {-0.92387953251f, 0.38268343236f * sg};
;     x[5] = cmul(x[5], W1); x[9] = cmul(x[9], W2); x[13] = cmul(x[13], W3);
;     x[6] = cmul(x[6], W2); x[10] = cmul(x[10], W4); x[14] = cmul(x[14], W6);
;     x[7] = cmul(x[7], W3); x[11] = cmul(x[11], W6); x[15] = cmul(x[15], W9);
; #pragma unroll
;     for (int c = 0; c < 4; ++c) r4<INV>(x[4 * c], x[4 * c + 1], x[4 * c + 2], x[4 * c + 3]);
; }
; template <bool INV> __device__ __forceinline__ void bfly16_tab(f32x2 (&x)[16], const LAS f32x2* T, int tstride, int j) {
;     if (INV) {
; #pragma unroll
;         for (int q = 1; q < 16; ++q) { f32x2 p = T[q * tstride + j]; p.y = -p.y; x[q] = cmul(x[q], p); } }
;     dft16<INV>(x);
;     if (!INV) {
; #pragma unroll
;         for (int r = 1; r < 16; ++r) { const f32x2 p = T[r * tstride + j]; x[4 * (r & 3) + (r >> 2)] = cmul(x[4 * (r & 3) + (r >> 2)], p); } }
; }
	v_pk_add_f32 v[64:65], v[92:93], v[94:95]
	v_pk_add_f32 v[80:81], v[80:81], v[82:83] neg_lo:[0,1] neg_hi:[0,1]
	v_pk_add_f32 v[84:85], v[84:85], v[86:87] neg_lo:[0,1] neg_hi:[0,1]
	v_pk_add_f32 v[90:91], v[88:89], v[90:91] neg_lo:[0,1] neg_hi:[0,1]
	v_pk_add_f32 v[92:93], v[92:93], v[94:95] neg_lo:[0,1] neg_hi:[0,1]
	v_pk_add_f32 v[94:95], v[96:97], v[76:77]
	v_pk_add_f32 v[88:89], v[98:99], v[72:73]
	v_pk_add_f32 v[86:87], v[100:101], v[70:71]
	v_pk_add_f32 v[82:83], v[102:103], v[64:65]
	v_pk_add_f32 v[76:77], v[96:97], v[76:77] neg_lo:[0,1] neg_hi:[0,1]
	v_pk_add_f32 v[98:99], v[98:99], v[72:73] neg_lo:[0,1] neg_hi:[0,1]
	v_pk_add_f32 v[100:101], v[100:101], v[70:71] neg_lo:[0,1] neg_hi:[0,1]
	v_pk_add_f32 v[102:103], v[102:103], v[64:65] neg_lo:[0,1] neg_hi:[0,1]
	v_pk_add_f32 v[64:65], v[66:67], v[80:81] op_sel:[0,1] op_sel_hi:[1,0] neg_hi:[0,1]
	v_pk_add_f32 v[70:71], v[68:69], v[84:85] op_sel:[0,1] op_sel_hi:[1,0] neg_hi:[0,1]
	v_pk_add_f32 v[72:73], v[74:75], v[90:91] op_sel:[0,1] op_sel_hi:[1,0] neg_hi:[0,1]
	v_pk_add_f32 v[96:97], v[78:79], v[92:93] op_sel:[0,1] op_sel_hi:[1,0] neg_hi:[0,1]
	v_pk_add_f32 v[80:81], v[66:67], v[80:81] op_sel:[0,1] op_sel_hi:[1,0] neg_lo:[0,1]
	v_pk_add_f32 v[68:69], v[68:69], v[84:85] op_sel:[0,1] op_sel_hi:[1,0] neg_lo:[0,1]
	v_pk_add_f32 v[90:91], v[74:75], v[90:91] op_sel:[0,1] op_sel_hi:[1,0] neg_lo:[0,1]
	v_pk_add_f32 v[92:93], v[78:79], v[92:93] op_sel:[0,1] op_sel_hi:[1,0] neg_lo:[0,1]
	v_pk_add_f32 v[78:79], v[94:95], v[86:87]
	v_pk_mul_f32 v[74:75], v[70:71], s[70:71] op_sel_hi:[1,0]
	v_pk_mul_f32 v[84:85], v[98:99], s[72:73] op_sel_hi:[1,0]
	v_pk_mul_f32 v[66:67], v[68:69], s[64:65] op_sel_hi:[1,0]
	v_pk_add_f32 v[86:87], v[94:95], v[86:87] neg_lo:[0,1] neg_hi:[0,1]
	v_pk_fma_f32 v[70:71], v[70:71], s[44:45], v[74:75] op_sel:[0,0,1] op_sel_hi:[1,0,0] neg_lo:[0,0,1]
	v_pk_fma_f32 v[84:85], v[98:99], s[76:77], v[84:85] op_sel:[0,0,1] op_sel_hi:[1,0,0] neg_lo:[0,0,1]
	v_pk_fma_f32 v[66:67], v[68:69], s[82:83], v[66:67] op_sel:[0,0,1] op_sel_hi:[1,0,0] neg_lo:[0,0,1]
	v_pk_add_f32 v[68:69], v[88:89], v[82:83]
	v_pk_fma_f32 v[98:99], v[72:73], s[72:73], v[64:65] op_sel:[0,0,1] op_sel_hi:[1,0,0] neg_hi:[0,0,1]
	v_pk_add_f32 v[74:75], v[76:77], v[100:101] op_sel:[0,1] op_sel_hi:[1,0] neg_hi:[0,1]
	v_pk_fma_f32 v[94:95], v[90:91], s[72:73], v[80:81] op_sel:[0,0,1] op_sel_hi:[1,0,0] neg_hi:[0,0,1]
	v_pk_add_f32 v[82:83], v[88:89], v[82:83] neg_lo:[0,1] neg_hi:[0,1]
	v_pk_fma_f32 v[72:73], v[72:73], s[76:77], v[98:99] op_sel:[0,0,1] op_sel_hi:[1,0,0] neg_lo:[0,0,1]
	v_pk_add_f32 v[100:101], v[76:77], v[100:101] op_sel:[0,1] op_sel_hi:[1,0] neg_lo:[0,1]
	v_pk_fma_f32 v[90:91], v[90:91], s[72:73], v[94:95] op_sel:[0,0,1] op_sel_hi:[1,0,0] neg_lo:[0,0,1]
	v_pk_add_f32 v[94:95], v[78:79], v[68:69]
	v_pk_fma_f32 v[64:65], v[64:65], s[100:101], v[72:73] op_sel_hi:[1,0,1] neg_lo:[0,0,1] neg_hi:[0,0,1]
	v_pk_fma_f32 v[76:77], v[102:103], s[72:73], v[84:85] op_sel:[0,0,1] op_sel_hi:[1,0,0] neg_hi:[0,0,1]
	v_pk_fma_f32 v[80:81], v[80:81], s[100:101], v[90:91] op_sel_hi:[1,0,1] neg_lo:[0,0,1] neg_hi:[0,0,1]
	v_pk_add_f32 v[68:69], v[78:79], v[68:69] neg_lo:[0,1] neg_hi:[0,1]
	v_pk_fma_f32 v[78:79], v[96:97], s[64:65], v[70:71] op_sel:[0,0,1] op_sel_hi:[1,0,0] neg_hi:[0,0,1]
	v_pk_fma_f32 v[76:77], v[102:103], s[72:73], v[76:77] op_sel:[0,0,1] op_sel_hi:[1,0,0] neg_lo:[0,0,1]
	v_pk_fma_f32 v[102:103], v[92:93], s[82:83], v[66:67] op_sel:[0,0,1] op_sel_hi:[1,0,0] neg_hi:[0,0,1]
	v_pk_add_f32 v[98:99], v[86:87], v[82:83] op_sel:[0,1] op_sel_hi:[1,0] neg_hi:[0,1]
	v_pk_fma_f32 v[78:79], v[96:97], s[82:83], v[78:79] op_sel:[0,0,1] op_sel_hi:[1,0,0] neg_lo:[0,0,1]
	v_pk_fma_f32 v[84:85], v[84:85], s[100:101], v[76:77] op_sel_hi:[1,0,1] neg_lo:[0,0,1] neg_hi:[0,0,1]
	v_pk_fma_f32 v[102:103], v[92:93], s[64:65], v[102:103] op_sel:[0,0,1] op_sel_hi:[1,0,0] neg_lo:[0,0,1]
	v_pk_add_f32 v[82:83], v[86:87], v[82:83] op_sel:[0,1] op_sel_hi:[1,0] neg_lo:[0,1]
	v_pk_fma_f32 v[70:71], v[70:71], s[100:101], v[78:79] op_sel_hi:[1,0,1] neg_lo:[0,0,1] neg_hi:[0,0,1]
	v_pk_add_f32 v[86:87], v[74:75], v[76:77]
	v_pk_fma_f32 v[66:67], v[66:67], s[100:101], v[102:103] op_sel_hi:[1,0,1] neg_lo:[0,0,1] neg_hi:[0,0,1]
	v_pk_add_f32 v[92:93], v[72:73], v[78:79]
	v_pk_add_f32 v[76:77], v[74:75], v[76:77] neg_lo:[0,1] neg_hi:[0,1]
	v_pk_add_f32 v[74:75], v[90:91], v[102:103]
	v_pk_add_f32 v[78:79], v[72:73], v[78:79] neg_lo:[0,1] neg_hi:[0,1]
	v_pk_add_f32 v[72:73], v[100:101], v[84:85] op_sel:[0,1] op_sel_hi:[1,0] neg_hi:[0,1]
	v_pk_add_f32 v[90:91], v[90:91], v[102:103] neg_lo:[0,1] neg_hi:[0,1]
	v_pk_add_f32 v[102:103], v[64:65], v[70:71] op_sel:[0,1] op_sel_hi:[1,0] neg_hi:[0,1]
	v_pk_add_f32 v[100:101], v[100:101], v[84:85] op_sel:[0,1] op_sel_hi:[1,0] neg_lo:[0,1]
	v_pk_add_f32 v[84:85], v[80:81], v[66:67] op_sel:[0,1] op_sel_hi:[1,0] neg_hi:[0,1]
	v_pk_add_f32 v[70:71], v[64:65], v[70:71] op_sel:[0,1] op_sel_hi:[1,0] neg_lo:[0,1]
	v_pk_add_f32 v[66:67], v[80:81], v[66:67] op_sel:[0,1] op_sel_hi:[1,0] neg_lo:[0,1]
	v_pk_mul_f32 v[80:81], v[92:93], v[232:233] op_sel:[0,1] op_sel_hi:[1,1]
	v_pk_mul_f32 v[64:65], v[86:87], v[234:235] op_sel:[0,1] op_sel_hi:[1,1]
	v_pk_fma_f32 v[80:81], v[92:93], v[232:233], v[80:81] op_sel:[0,0,1] op_sel_hi:[1,0,0] neg_lo:[0,0,1]
	v_pk_mul_f32 v[92:93], v[74:75], v[208:209] op_sel:[0,1] op_sel_hi:[1,1]
	v_pk_fma_f32 v[64:65], v[86:87], v[234:235], v[64:65] op_sel:[0,0,1] op_sel_hi:[1,0,0] neg_lo:[0,0,1]
	v_pk_mul_f32 v[86:87], v[98:99], v[210:211] op_sel:[0,1] op_sel_hi:[1,1]
	v_pk_fma_f32 v[92:93], v[74:75], v[208:209], v[92:93] op_sel:[0,0,1] op_sel_hi:[1,0,0] neg_lo:[0,0,1]
; #define LAS __attribute__((address_space(3)))
; template <bool INV> __device__ __forceinline__ void pass16_s64(LAS f32x2* X, const LAS f32x2* TH, int base, int j) {
;     ...
; #pragma unroll
;     for (int c = 0; c < 4; ++c)
; #pragma unroll
;         for (int d = 0; d < 4; ++d) X[base + (c + 4 * d) * 68] = x[4 * c + d];
; }
; template <bool INV> __device__ __forceinline__ void pass16_s4(LAS f32x2* X, const LAS f32x2* TH, const LAS f32x2* TL, int tid) {
; #pragma unroll 1
;     for (int s = 0; s < 2; ++s) {
;         const int b = tid + NTHR * s, blk = b >> 2, jj = b & 3;
;         LAS f32x2* P = X + blk * 68 + jj;
;         f32x2 x[16];
; #pragma unroll
;         for (int q = 0; q < 16; ++q) x[q] = P[4 * q];
;         bfly16_tab<INV>(x, TH - 1024, 4, jj);
; #pragma unroll
;         for (int c = 0; c < 4; ++c)
; #pragma unroll
;             for (int d = 0; d < 4; ++d) P[4 * (c + 4 * d)] = x[4 * c + d];
;     }
; }
	v_pk_mul_f32 v[74:75], v[102:103], v[204:205] op_sel:[0,1] op_sel_hi:[1,1]
	v_pk_fma_f32 v[86:87], v[98:99], v[210:211], v[86:87] op_sel:[0,0,1] op_sel_hi:[1,0,0] neg_lo:[0,0,1]
	v_pk_mul_f32 v[98:99], v[72:73], v[206:207] op_sel:[0,1] op_sel_hi:[1,1]
	v_pk_fma_f32 v[74:75], v[102:103], v[204:205], v[74:75] op_sel:[0,0,1] op_sel_hi:[1,0,0] neg_lo:[0,0,1]
	v_pk_mul_f32 v[102:103], v[84:85], v[200:201] op_sel:[0,1] op_sel_hi:[1,1]
	v_pk_fma_f32 v[98:99], v[72:73], v[206:207], v[98:99] op_sel:[0,0,1] op_sel_hi:[1,0,0] neg_lo:[0,0,1]
	v_pk_mul_f32 v[72:73], v[68:69], v[202:203] op_sel:[0,1] op_sel_hi:[1,1]
	v_pk_fma_f32 v[102:103], v[84:85], v[200:201], v[102:103] op_sel:[0,0,1] op_sel_hi:[1,0,0] neg_lo:[0,0,1]
	v_pk_mul_f32 v[84:85], v[78:79], v[196:197] op_sel:[0,1] op_sel_hi:[1,1]
	v_pk_fma_f32 v[72:73], v[68:69], v[202:203], v[72:73] op_sel:[0,0,1] op_sel_hi:[1,0,0] neg_lo:[0,0,1]
	v_pk_mul_f32 v[68:69], v[76:77], v[198:199] op_sel:[0,1] op_sel_hi:[1,1]
	v_pk_fma_f32 v[78:79], v[78:79], v[196:197], v[84:85] op_sel:[0,0,1] op_sel_hi:[1,0,0] neg_lo:[0,0,1]
	v_pk_mul_f32 v[84:85], v[90:91], v[192:193] op_sel:[0,1] op_sel_hi:[1,1]
	v_pk_fma_f32 v[68:69], v[76:77], v[198:199], v[68:69] op_sel:[0,0,1] op_sel_hi:[1,0,0] neg_lo:[0,0,1]
	v_pk_mul_f32 v[76:77], v[82:83], v[194:195] op_sel:[0,1] op_sel_hi:[1,1]
	v_pk_fma_f32 v[90:91], v[90:91], v[192:193], v[84:85] op_sel:[0,0,1] op_sel_hi:[1,0,0] neg_lo:[0,0,1]
	v_pk_mul_f32 v[84:85], v[70:71], v[188:189] op_sel:[0,1] op_sel_hi:[1,1]
	v_pk_fma_f32 v[76:77], v[82:83], v[194:195], v[76:77] op_sel:[0,0,1] op_sel_hi:[1,0,0] neg_lo:[0,0,1]
	v_pk_mul_f32 v[82:83], v[100:101], v[190:191] op_sel:[0,1] op_sel_hi:[1,1]
	v_pk_fma_f32 v[70:71], v[70:71], v[188:189], v[84:85] op_sel:[0,0,1] op_sel_hi:[1,0,0] neg_lo:[0,0,1]
	v_pk_mul_f32 v[84:85], v[66:67], v[186:187] op_sel:[0,1] op_sel_hi:[1,1]
	v_pk_fma_f32 v[100:101], v[100:101], v[190:191], v[82:83] op_sel:[0,0,1] op_sel_hi:[1,0,0] neg_lo:[0,0,1]
	v_pk_fma_f32 v[66:67], v[66:67], v[186:187], v[84:85] op_sel:[0,0,1] op_sel_hi:[1,0,0] neg_lo:[0,0,1]
	ds_write_b64 v151, v[94:95] offset:0
	ds_write_b64 v151, v[80:81] offset:544
	ds_write_b64 v151, v[64:65] offset:1088
	ds_write_b64 v151, v[92:93] offset:1632
	ds_write_b64 v151, v[86:87] offset:2176
	ds_write_b64 v151, v[74:75] offset:2720
	ds_write_b64 v151, v[98:99] offset:3264
	ds_write_b64 v151, v[102:103] offset:3808
	ds_write_b64 v151, v[72:73] offset:4352
	ds_write_b64 v151, v[78:79] offset:4896
	ds_write_b64 v151, v[68:69] offset:5440
	ds_write_b64 v151, v[90:91] offset:5984
	ds_write_b64 v151, v[76:77] offset:6528
	ds_write_b64 v151, v[70:71] offset:7072
	ds_write_b64 v151, v[100:101] offset:7616
	ds_write_b64 v151, v[66:67] offset:8160
	s_cbranch_scc1 .LBB0_848
	s_waitcnt lgkmcnt(0)
	s_barrier
	s_mov_b32 s0, 0
	s_mov_b64 s[12:13], -1
	ds_read2_b64 v[232:235], v141 offset0:4 offset1:8
	ds_read2_b64 v[208:211], v141 offset0:12 offset1:16
	ds_read2_b64 v[204:207], v141 offset0:20 offset1:24
	ds_read2_b64 v[200:203], v141 offset0:28 offset1:32
	ds_read2_b64 v[196:199], v141 offset0:36 offset1:40
	ds_read2_b64 v[192:195], v141 offset0:44 offset1:48
	ds_read2_b64 v[188:191], v141 offset0:52 offset1:56
	ds_read_b64 v[186:187], v141 offset:480
.LBB0_850:
	v_add_u32_e32 v128, s0, v140
	v_lshrrev_b32_e32 v147, 2, v128
	v_mad_u32_u24 v151, v147, s43, v144
	ds_read_b64 v[64:65], v151 offset:0
	ds_read_b64 v[66:67], v151 offset:256
	ds_read_b64 v[68:69], v151 offset:32
	ds_read_b64 v[70:71], v151 offset:288
	ds_read_b64 v[72:73], v151 offset:64
	ds_read_b64 v[74:75], v151 offset:320
	ds_read_b64 v[76:77], v151 offset:96
	ds_read_b64 v[78:79], v151 offset:352
	ds_read_b64 v[80:81], v151 offset:128
	ds_read_b64 v[82:83], v151 offset:384
	ds_read_b64 v[84:85], v151 offset:160
	ds_read_b64 v[86:87], v151 offset:416
	ds_read_b64 v[88:89], v151 offset:192
	ds_read_b64 v[90:91], v151 offset:448
	ds_read_b64 v[92:93], v151 offset:224
	ds_read_b64 v[94:95], v151 offset:480
	s_cmp_eq_u32 s0, 0
	s_movk_i32 s0, 0x200
	s_mov_b64 s[12:13], 0
	s_waitcnt lgkmcnt(14)
	v_pk_add_f32 v[96:97], v[64:65], v[66:67]
	s_waitcnt lgkmcnt(12)
	v_pk_add_f32 v[98:99], v[68:69], v[70:71]
	s_waitcnt lgkmcnt(10)
	v_pk_add_f32 v[100:101], v[72:73], v[74:75]
	s_waitcnt lgkmcnt(8)
	v_pk_add_f32 v[102:103], v[76:77], v[78:79]
	v_pk_add_f32 v[66:67], v[64:65], v[66:67] neg_lo:[0,1] neg_hi:[0,1]
	v_pk_add_f32 v[68:69], v[68:69], v[70:71] neg_lo:[0,1] neg_hi:[0,1]
	v_pk_add_f32 v[72:73], v[72:73], v[74:75] neg_lo:[0,1] neg_hi:[0,1]
	v_pk_add_f32 v[78:79], v[76:77], v[78:79] neg_lo:[0,1] neg_hi:[0,1]
	s_waitcnt lgkmcnt(6)
	v_pk_add_f32 v[76:77], v[80:81], v[82:83]
	s_waitcnt lgkmcnt(4)
	v_pk_add_f32 v[74:75], v[84:85], v[86:87]
	s_waitcnt lgkmcnt(2)
	v_pk_add_f32 v[70:71], v[88:89], v[90:91]
	s_waitcnt lgkmcnt(0)
; __device__ __forceinline__ f32x2 cmul(f32x2 a, f32x2 b) { return (f32x2){a.x * b.x - a.y * b.y, a.x * b.y + a.y * b.x}; }
; template <bool INV> __device__ __forceinline__ void dft16(f32x2 (&x)[16]) {
; #pragma unroll
;     for (int b = 0; b < 4; ++b) r4<INV>(x[b], x[4 + b], x[8 + b], x[12 + b]);
;     const float sg = INV ? -1.f : 1.f;
;     const f32x2 W1 = {0.92387953251f, -0.38268343236f * sg}, W2 = {0.70710678118f, -0.70710678118f * sg}, W3 = {0.38268343236f, -0.92387953251f * sg},
;                 W4 = {0.f, -1.f * sg}, W6 = {-0.70710678118f, -0.70710678118f * sg}, W9 = {-0.92387953251f, 0.38268343236f * sg};
;     x[5] = cmul(x[5], W1); x[9] = cmul(x[9], W2); x[13] = cmul(x[13], W3);
;     x[6] = cmul(x[6], W2); x[10] = cmul(x[10], W4); x[14] = cmul(x[14], W6);
;     x[7] = cmul(x[7], W3); x[11] = cmul(x[11], W6); x[15] = cmul(x[15], W9);
; #pragma unroll
;     for (int c = 0; c < 4; ++c) r4<INV>(x[4 * c], x[4 * c + 1], x[4 * c + 2], x[4 * c + 3]);
; }
	v_pk_add_f32 v[64:65], v[92:93], v[94:95]
	v_pk_add_f32 v[80:81], v[80:81], v[82:83] neg_lo:[0,1] neg_hi:[0,1]
	v_pk_add_f32 v[86:87], v[84:85], v[86:87] neg_lo:[0,1] neg_hi:[0,1]
	v_pk_add_f32 v[90:91], v[88:89], v[90:91] neg_lo:[0,1] neg_hi:[0,1]
	v_pk_add_f32 v[94:95], v[92:93], v[94:95] neg_lo:[0,1] neg_hi:[0,1]
	v_pk_add_f32 v[92:93], v[96:97], v[76:77]
	v_pk_add_f32 v[88:89], v[98:99], v[74:75]
	v_pk_add_f32 v[84:85], v[100:101], v[70:71]
	v_pk_add_f32 v[82:83], v[102:103], v[64:65]
	v_pk_add_f32 v[96:97], v[96:97], v[76:77] neg_lo:[0,1] neg_hi:[0,1]
	v_pk_add_f32 v[74:75], v[98:99], v[74:75] neg_lo:[0,1] neg_hi:[0,1]
	v_pk_add_f32 v[100:101], v[100:101], v[70:71] neg_lo:[0,1] neg_hi:[0,1]
	v_pk_add_f32 v[64:65], v[102:103], v[64:65] neg_lo:[0,1] neg_hi:[0,1]
	v_pk_add_f32 v[102:103], v[66:67], v[80:81] op_sel:[0,1] op_sel_hi:[1,0] neg_hi:[0,1]
	v_pk_add_f32 v[70:71], v[68:69], v[86:87] op_sel:[0,1] op_sel_hi:[1,0] neg_hi:[0,1]
	v_pk_add_f32 v[98:99], v[72:73], v[90:91] op_sel:[0,1] op_sel_hi:[1,0] neg_hi:[0,1]
	v_pk_add_f32 v[76:77], v[78:79], v[94:95] op_sel:[0,1] op_sel_hi:[1,0] neg_hi:[0,1]
	v_pk_add_f32 v[80:81], v[66:67], v[80:81] op_sel:[0,1] op_sel_hi:[1,0] neg_lo:[0,1]
	v_pk_add_f32 v[68:69], v[68:69], v[86:87] op_sel:[0,1] op_sel_hi:[1,0] neg_lo:[0,1]
	v_pk_add_f32 v[90:91], v[72:73], v[90:91] op_sel:[0,1] op_sel_hi:[1,0] neg_lo:[0,1]
	v_pk_add_f32 v[78:79], v[78:79], v[94:95] op_sel:[0,1] op_sel_hi:[1,0] neg_lo:[0,1]
	v_pk_add_f32 v[94:95], v[92:93], v[84:85]
	v_pk_mul_f32 v[72:73], v[70:71], s[70:71] op_sel_hi:[1,0]
	v_pk_mul_f32 v[86:87], v[74:75], s[72:73] op_sel_hi:[1,0]
	v_pk_mul_f32 v[66:67], v[68:69], s[64:65] op_sel_hi:[1,0]
	v_pk_add_f32 v[84:85], v[92:93], v[84:85] neg_lo:[0,1] neg_hi:[0,1]
	v_pk_fma_f32 v[70:71], v[70:71], s[44:45], v[72:73] op_sel:[0,0,1] op_sel_hi:[1,0,0] neg_lo:[0,0,1]
	v_pk_fma_f32 v[86:87], v[74:75], s[76:77], v[86:87] op_sel:[0,0,1] op_sel_hi:[1,0,0] neg_lo:[0,0,1]
	v_pk_fma_f32 v[68:69], v[68:69], s[82:83], v[66:67] op_sel:[0,0,1] op_sel_hi:[1,0,0] neg_lo:[0,0,1]
	v_pk_add_f32 v[66:67], v[88:89], v[82:83]
	v_pk_fma_f32 v[74:75], v[98:99], s[72:73], v[102:103] op_sel:[0,0,1] op_sel_hi:[1,0,0] neg_hi:[0,0,1]
	v_pk_add_f32 v[72:73], v[96:97], v[100:101] op_sel:[0,1] op_sel_hi:[1,0] neg_hi:[0,1]
	v_pk_fma_f32 v[92:93], v[90:91], s[72:73], v[80:81] op_sel:[0,0,1] op_sel_hi:[1,0,0] neg_hi:[0,0,1]
	v_pk_add_f32 v[88:89], v[88:89], v[82:83] neg_lo:[0,1] neg_hi:[0,1]
	v_pk_fma_f32 v[98:99], v[98:99], s[76:77], v[74:75] op_sel:[0,0,1] op_sel_hi:[1,0,0] neg_lo:[0,0,1]
	v_pk_add_f32 v[100:101], v[96:97], v[100:101] op_sel:[0,1] op_sel_hi:[1,0] neg_lo:[0,1]
	v_pk_fma_f32 v[92:93], v[90:91], s[72:73], v[92:93] op_sel:[0,0,1] op_sel_hi:[1,0,0] neg_lo:[0,0,1]
	v_pk_add_f32 v[90:91], v[94:95], v[66:67]
	v_pk_fma_f32 v[102:103], v[102:103], s[100:101], v[98:99] op_sel_hi:[1,0,1] neg_lo:[0,0,1] neg_hi:[0,0,1]
	v_pk_fma_f32 v[96:97], v[64:65], s[72:73], v[86:87] op_sel:[0,0,1] op_sel_hi:[1,0,0] neg_hi:[0,0,1]
	v_pk_fma_f32 v[80:81], v[80:81], s[100:101], v[92:93] op_sel_hi:[1,0,1] neg_lo:[0,0,1] neg_hi:[0,0,1]
	v_pk_add_f32 v[66:67], v[94:95], v[66:67] neg_lo:[0,1] neg_hi:[0,1]
	v_pk_fma_f32 v[94:95], v[76:77], s[64:65], v[70:71] op_sel:[0,0,1] op_sel_hi:[1,0,0] neg_hi:[0,0,1]
	v_pk_fma_f32 v[96:97], v[64:65], s[72:73], v[96:97] op_sel:[0,0,1] op_sel_hi:[1,0,0] neg_lo:[0,0,1]
	v_pk_fma_f32 v[64:65], v[78:79], s[82:83], v[68:69] op_sel:[0,0,1] op_sel_hi:[1,0,0] neg_hi:[0,0,1]
	v_pk_add_f32 v[74:75], v[84:85], v[88:89] op_sel:[0,1] op_sel_hi:[1,0] neg_hi:[0,1]
	v_pk_fma_f32 v[76:77], v[76:77], s[82:83], v[94:95] op_sel:[0,0,1] op_sel_hi:[1,0,0] neg_lo:[0,0,1]
	v_pk_fma_f32 v[86:87], v[86:87], s[100:101], v[96:97] op_sel_hi:[1,0,1] neg_lo:[0,0,1] neg_hi:[0,0,1]
	v_pk_fma_f32 v[64:65], v[78:79], s[64:65], v[64:65] op_sel:[0,0,1] op_sel_hi:[1,0,0] neg_lo:[0,0,1]
	v_pk_add_f32 v[84:85], v[84:85], v[88:89] op_sel:[0,1] op_sel_hi:[1,0] neg_lo:[0,1]
	v_pk_fma_f32 v[70:71], v[70:71], s[100:101], v[76:77] op_sel_hi:[1,0,1] neg_lo:[0,0,1] neg_hi:[0,0,1]
	v_pk_add_f32 v[88:89], v[72:73], v[96:97]
	v_pk_fma_f32 v[68:69], v[68:69], s[100:101], v[64:65] op_sel_hi:[1,0,1] neg_lo:[0,0,1] neg_hi:[0,0,1]
	v_pk_add_f32 v[78:79], v[98:99], v[76:77]
	v_pk_add_f32 v[96:97], v[72:73], v[96:97] neg_lo:[0,1] neg_hi:[0,1]
	v_pk_add_f32 v[72:73], v[92:93], v[64:65]
	v_pk_add_f32 v[76:77], v[98:99], v[76:77] neg_lo:[0,1] neg_hi:[0,1]
	v_pk_add_f32 v[98:99], v[100:101], v[86:87] op_sel:[0,1] op_sel_hi:[1,0] neg_hi:[0,1]
	v_pk_add_f32 v[64:65], v[92:93], v[64:65] neg_lo:[0,1] neg_hi:[0,1]
	v_pk_add_f32 v[92:93], v[102:103], v[70:71] op_sel:[0,1] op_sel_hi:[1,0] neg_hi:[0,1]
	v_pk_add_f32 v[86:87], v[100:101], v[86:87] op_sel:[0,1] op_sel_hi:[1,0] neg_lo:[0,1]
	v_pk_add_f32 v[100:101], v[80:81], v[68:69] op_sel:[0,1] op_sel_hi:[1,0] neg_hi:[0,1]
	v_pk_add_f32 v[70:71], v[102:103], v[70:71] op_sel:[0,1] op_sel_hi:[1,0] neg_lo:[0,1]
	v_pk_add_f32 v[68:69], v[80:81], v[68:69] op_sel:[0,1] op_sel_hi:[1,0] neg_lo:[0,1]
	v_pk_mul_f32 v[80:81], v[78:79], v[232:233] op_sel:[0,1] op_sel_hi:[1,1]
	v_pk_mul_f32 v[102:103], v[88:89], v[234:235] op_sel:[0,1] op_sel_hi:[1,1]
	v_pk_fma_f32 v[80:81], v[78:79], v[232:233], v[80:81] op_sel:[0,0,1] op_sel_hi:[1,0,0] neg_lo:[0,0,1]
	v_pk_mul_f32 v[78:79], v[72:73], v[208:209] op_sel:[0,1] op_sel_hi:[1,1]
	v_pk_fma_f32 v[102:103], v[88:89], v[234:235], v[102:103] op_sel:[0,0,1] op_sel_hi:[1,0,0] neg_lo:[0,0,1]
	v_pk_mul_f32 v[88:89], v[74:75], v[210:211] op_sel:[0,1] op_sel_hi:[1,1]
	v_pk_fma_f32 v[78:79], v[72:73], v[208:209], v[78:79] op_sel:[0,0,1] op_sel_hi:[1,0,0] neg_lo:[0,0,1]
; #define LAS __attribute__((address_space(3)))
; __device__ __forceinline__ f32x2 cmul(f32x2 a, f32x2 b) { return (f32x2){a.x * b.x - a.y * b.y, a.x * b.y + a.y * b.x}; }
; #define LDS_BARRIER() do { asm volatile("s_waitcnt lgkmcnt(0)" ::: "memory"); __builtin_amdgcn_s_barrier(); asm volatile("" ::: "memory"); } while (0)
; #define LT() ({ int lt_ = tid; asm volatile("" : "+v"(lt_)); lt_; })
; template <bool INV> __device__ __forceinline__ void bfly16_tab(f32x2 (&x)[16], const LAS f32x2* T, int tstride, int j) {
;     ...
;         for (int q = 1; q < 16; ++q) { f32x2 p = T[q * tstride + j]; p.y = -p.y; x[q] = cmul(x[q], p); } }
;     dft16<INV>(x);
;     if (!INV) {
; #pragma unroll
;         for (int r = 1; r < 16; ++r) { const f32x2 p = T[r * tstride + j]; x[4 * (r & 3) + (r >> 2)] = cmul(x[4 * (r & 3) + (r >> 2)], p); } }
; }
; __device__ __forceinline__ void hyena_latent(Frame& F, int l, int ch, LAS f32x2* X, const LAS f32x2* TH, const LAS f32x2* TL, GAS f32x2* KS, const LAS float* CT  , bool wr = true) {
;     ...
;             for (int i = 0; i < 8; ++i) { const int b = LT() + NTHR * i; const LAS f32x4* P = (const LAS f32x4*)(X + 4 * b + ((b >> 4) << 2)); const f32x4 u = P[0], v = P[1];
;                 f32x2 x0 = {u.x, u.y}, x1 = {u.z, u.w}, x2 = {v.x, v.y}, x3 = {v.z, v.w}; r4<false>(x0, x1, x2, x3);
;                 kreg[2 * i] = (f32x4){x0.x, x0.y, x1.x, x1.y}; kreg[2 * i + 1] = (f32x4){x2.x, x2.y, x3.x, x3.y}; }
;             LDS_BARRIER();
	v_pk_mul_f32 v[72:73], v[92:93], v[204:205] op_sel:[0,1] op_sel_hi:[1,1]
	v_pk_fma_f32 v[88:89], v[74:75], v[210:211], v[88:89] op_sel:[0,0,1] op_sel_hi:[1,0,0] neg_lo:[0,0,1]
	v_pk_mul_f32 v[74:75], v[98:99], v[206:207] op_sel:[0,1] op_sel_hi:[1,1]
	v_pk_fma_f32 v[92:93], v[92:93], v[204:205], v[72:73] op_sel:[0,0,1] op_sel_hi:[1,0,0] neg_lo:[0,0,1]
	v_pk_mul_f32 v[72:73], v[100:101], v[200:201] op_sel:[0,1] op_sel_hi:[1,1]
	v_pk_fma_f32 v[98:99], v[98:99], v[206:207], v[74:75] op_sel:[0,0,1] op_sel_hi:[1,0,0] neg_lo:[0,0,1]
	v_pk_mul_f32 v[74:75], v[66:67], v[202:203] op_sel:[0,1] op_sel_hi:[1,1]
	v_pk_fma_f32 v[100:101], v[100:101], v[200:201], v[72:73] op_sel:[0,0,1] op_sel_hi:[1,0,0] neg_lo:[0,0,1]
	v_pk_mul_f32 v[72:73], v[76:77], v[196:197] op_sel:[0,1] op_sel_hi:[1,1]
	v_pk_fma_f32 v[66:67], v[66:67], v[202:203], v[74:75] op_sel:[0,0,1] op_sel_hi:[1,0,0] neg_lo:[0,0,1]
	v_pk_mul_f32 v[74:75], v[96:97], v[198:199] op_sel:[0,1] op_sel_hi:[1,1]
	v_pk_fma_f32 v[76:77], v[76:77], v[196:197], v[72:73] op_sel:[0,0,1] op_sel_hi:[1,0,0] neg_lo:[0,0,1]
	v_pk_mul_f32 v[72:73], v[64:65], v[192:193] op_sel:[0,1] op_sel_hi:[1,1]
	v_pk_fma_f32 v[96:97], v[96:97], v[198:199], v[74:75] op_sel:[0,0,1] op_sel_hi:[1,0,0] neg_lo:[0,0,1]
	v_pk_mul_f32 v[74:75], v[84:85], v[194:195] op_sel:[0,1] op_sel_hi:[1,1]
	v_pk_fma_f32 v[64:65], v[64:65], v[192:193], v[72:73] op_sel:[0,0,1] op_sel_hi:[1,0,0] neg_lo:[0,0,1]
	v_pk_mul_f32 v[72:73], v[70:71], v[188:189] op_sel:[0,1] op_sel_hi:[1,1]
	v_pk_fma_f32 v[74:75], v[84:85], v[194:195], v[74:75] op_sel:[0,0,1] op_sel_hi:[1,0,0] neg_lo:[0,0,1]
	v_pk_mul_f32 v[84:85], v[86:87], v[190:191] op_sel:[0,1] op_sel_hi:[1,1]
	v_pk_fma_f32 v[70:71], v[70:71], v[188:189], v[72:73] op_sel:[0,0,1] op_sel_hi:[1,0,0] neg_lo:[0,0,1]
	v_pk_mul_f32 v[72:73], v[68:69], v[186:187] op_sel:[0,1] op_sel_hi:[1,1]
	v_pk_fma_f32 v[86:87], v[86:87], v[190:191], v[84:85] op_sel:[0,0,1] op_sel_hi:[1,0,0] neg_lo:[0,0,1]
	v_pk_fma_f32 v[72:73], v[68:69], v[186:187], v[72:73] op_sel:[0,0,1] op_sel_hi:[1,0,0] neg_lo:[0,0,1]
	ds_write_b64 v151, v[90:91] offset:0
	ds_write_b64 v151, v[80:81] offset:32
	ds_write_b64 v151, v[102:103] offset:64
	ds_write_b64 v151, v[78:79] offset:96
	ds_write_b64 v151, v[88:89] offset:128
	ds_write_b64 v151, v[92:93] offset:160
	ds_write_b64 v151, v[98:99] offset:192
	ds_write_b64 v151, v[100:101] offset:224
	ds_write_b64 v151, v[66:67] offset:256
	ds_write_b64 v151, v[76:77] offset:288
	ds_write_b64 v151, v[96:97] offset:320
	ds_write_b64 v151, v[64:65] offset:352
	ds_write_b64 v151, v[74:75] offset:384
	ds_write_b64 v151, v[70:71] offset:416
	ds_write_b64 v151, v[86:87] offset:448
	ds_write_b64 v151, v[72:73] offset:480
	s_cbranch_scc1 .LBB0_850
	v_pk_add_f32 v[68:69], v[56:57], v[60:61]
	v_pk_add_f32 v[56:57], v[56:57], v[60:61] neg_lo:[0,1] neg_hi:[0,1]
	v_pk_add_f32 v[60:61], v[58:59], v[62:63]
	v_pk_add_f32 v[58:59], v[58:59], v[62:63] neg_lo:[0,1] neg_hi:[0,1]
	v_pk_add_f32 v[66:67], v[68:69], v[60:61]
	v_xor_b32_e32 v71, 0x80000000, v58
	v_mov_b32_e32 v70, v59
	v_pk_add_f32 v[62:63], v[68:69], v[60:61] neg_lo:[0,1] neg_hi:[0,1]
	v_pk_add_f32 v[68:69], v[48:49], v[52:53]
	v_pk_add_f32 v[48:49], v[48:49], v[52:53] neg_lo:[0,1] neg_hi:[0,1]
	v_pk_add_f32 v[52:53], v[50:51], v[54:55]
	v_pk_add_f32 v[50:51], v[50:51], v[54:55] neg_lo:[0,1] neg_hi:[0,1]
	v_pk_add_f32 v[64:65], v[56:57], v[70:71]
	v_pk_add_f32 v[60:61], v[56:57], v[70:71] neg_lo:[0,1] neg_hi:[0,1]
	v_xor_b32_e32 v71, 0x80000000, v50
	v_mov_b32_e32 v70, v51
	v_pk_add_f32 v[58:59], v[68:69], v[52:53]
	v_pk_add_f32 v[54:55], v[68:69], v[52:53] neg_lo:[0,1] neg_hi:[0,1]
	v_pk_add_f32 v[68:69], v[40:41], v[44:45]
	v_pk_add_f32 v[40:41], v[40:41], v[44:45] neg_lo:[0,1] neg_hi:[0,1]
	v_pk_add_f32 v[44:45], v[42:43], v[46:47]
	v_pk_add_f32 v[42:43], v[42:43], v[46:47] neg_lo:[0,1] neg_hi:[0,1]
	v_pk_add_f32 v[56:57], v[48:49], v[70:71]
	v_pk_add_f32 v[52:53], v[48:49], v[70:71] neg_lo:[0,1] neg_hi:[0,1]
	v_xor_b32_e32 v71, 0x80000000, v42
	v_mov_b32_e32 v70, v43
	v_pk_add_f32 v[50:51], v[68:69], v[44:45]
	v_pk_add_f32 v[46:47], v[68:69], v[44:45] neg_lo:[0,1] neg_hi:[0,1]
	v_pk_add_f32 v[68:69], v[32:33], v[36:37]
	v_pk_add_f32 v[32:33], v[32:33], v[36:37] neg_lo:[0,1] neg_hi:[0,1]
	v_pk_add_f32 v[36:37], v[34:35], v[38:39]
	v_pk_add_f32 v[34:35], v[34:35], v[38:39] neg_lo:[0,1] neg_hi:[0,1]
	v_pk_add_f32 v[48:49], v[40:41], v[70:71]
	v_pk_add_f32 v[44:45], v[40:41], v[70:71] neg_lo:[0,1] neg_hi:[0,1]
	v_xor_b32_e32 v71, 0x80000000, v34
	v_mov_b32_e32 v70, v35
	v_pk_add_f32 v[42:43], v[68:69], v[36:37]
	v_pk_add_f32 v[38:39], v[68:69], v[36:37] neg_lo:[0,1] neg_hi:[0,1]
	v_pk_add_f32 v[68:69], v[24:25], v[28:29]
	v_pk_add_f32 v[24:25], v[24:25], v[28:29] neg_lo:[0,1] neg_hi:[0,1]
	v_pk_add_f32 v[28:29], v[26:27], v[30:31]
	v_pk_add_f32 v[26:27], v[26:27], v[30:31] neg_lo:[0,1] neg_hi:[0,1]
	v_pk_add_f32 v[40:41], v[32:33], v[70:71]
	v_pk_add_f32 v[36:37], v[32:33], v[70:71] neg_lo:[0,1] neg_hi:[0,1]
	v_xor_b32_e32 v71, 0x80000000, v26
	v_mov_b32_e32 v70, v27
	v_pk_add_f32 v[34:35], v[68:69], v[28:29]
	v_pk_add_f32 v[30:31], v[68:69], v[28:29] neg_lo:[0,1] neg_hi:[0,1]
	v_pk_add_f32 v[68:69], v[12:13], v[20:21]
	v_pk_add_f32 v[12:13], v[12:13], v[20:21] neg_lo:[0,1] neg_hi:[0,1]
	v_pk_add_f32 v[20:21], v[14:15], v[22:23]
	v_pk_add_f32 v[14:15], v[14:15], v[22:23] neg_lo:[0,1] neg_hi:[0,1]
	v_pk_add_f32 v[32:33], v[24:25], v[70:71]
	v_pk_add_f32 v[28:29], v[24:25], v[70:71] neg_lo:[0,1] neg_hi:[0,1]
	v_xor_b32_e32 v71, 0x80000000, v14
	v_mov_b32_e32 v70, v15
	v_pk_add_f32 v[14:15], v[6:7], v[18:19]
	v_pk_add_f32 v[6:7], v[6:7], v[18:19] neg_lo:[0,1] neg_hi:[0,1]
	v_pk_add_f32 v[26:27], v[68:69], v[20:21]
	v_pk_add_f32 v[24:25], v[12:13], v[70:71]
	v_pk_add_f32 v[22:23], v[68:69], v[20:21] neg_lo:[0,1] neg_hi:[0,1]
	v_pk_add_f32 v[20:21], v[12:13], v[70:71] neg_lo:[0,1] neg_hi:[0,1]
	v_pk_add_f32 v[12:13], v[4:5], v[16:17]
	v_pk_add_f32 v[4:5], v[4:5], v[16:17] neg_lo:[0,1] neg_hi:[0,1]
	v_xor_b32_e32 v69, 0x80000000, v6
	v_mov_b32_e32 v68, v7
	v_pk_add_f32 v[18:19], v[12:13], v[14:15]
	v_pk_add_f32 v[16:17], v[4:5], v[68:69]
	v_pk_add_f32 v[14:15], v[12:13], v[14:15] neg_lo:[0,1] neg_hi:[0,1]
	v_pk_add_f32 v[12:13], v[4:5], v[68:69] neg_lo:[0,1] neg_hi:[0,1]
	v_pk_add_f32 v[68:69], v[0:1], v[8:9]
	v_pk_add_f32 v[0:1], v[0:1], v[8:9] neg_lo:[0,1] neg_hi:[0,1]
	v_pk_add_f32 v[8:9], v[2:3], v[10:11]
	v_pk_add_f32 v[2:3], v[2:3], v[10:11] neg_lo:[0,1] neg_hi:[0,1]
	v_pk_add_f32 v[6:7], v[68:69], v[8:9]
	v_xor_b32_e32 v11, 0x80000000, v2
	v_mov_b32_e32 v10, v3
	v_pk_add_f32 v[2:3], v[68:69], v[8:9] neg_lo:[0,1] neg_hi:[0,1]
	v_mov_b32_e32 v8, v140
	s_waitcnt lgkmcnt(0)
	s_barrier
; #define LAS __attribute__((address_space(3)))
; __device__ __forceinline__ f32x2 cmul(f32x2 a, f32x2 b) { return (f32x2){a.x * b.x - a.y * b.y, a.x * b.y + a.y * b.x}; }
; #define LT() ({ int lt_ = tid; asm volatile("" : "+v"(lt_)); lt_; })
; __device__ __forceinline__ void hyena_latent(Frame& F, int l, int ch, LAS f32x2* X, const LAS f32x2* TH, const LAS f32x2* TL, GAS f32x2* KS, const LAS float* CT  , bool wr = true) {
;     ...
;             fft_fwd_head(X, TH, TL, tid);
; #pragma unroll
;             for (int i = 0; i < 8; ++i) { const int b = LT() + NTHR * i; LAS f32x4* P = (LAS f32x4*)(X + 4 * b + ((b >> 4) << 2)); const f32x4 u = P[0], v = P[1], k0 = kreg[2 * i], k1 = kreg[2 * i + 1];
;                 f32x2 x0 = {u.x, u.y}, x1 = {u.z, u.w}, x2 = {v.x, v.y}, x3 = {v.z, v.w}; r4<false>(x0, x1, x2, x3);
;                 x0 = cmul(x0, (f32x2){k0.x, k0.y}); x1 = cmul(x1, (f32x2){k0.z, k0.w}); x2 = cmul(x2, (f32x2){k1.x, k1.y}); x3 = cmul(x3, (f32x2){k1.z, k1.w});
;                 r4<true>(x0, x1, x2, x3);
;                 P[0] = (f32x4){x0.x, x0.y, x1.x, x1.y}; P[1] = (f32x4){x2.x, x2.y, x3.x, x3.y};
;                 if (i & 1) asm volatile("" ::: "memory"); }
;             __syncthreads();
	v_pk_add_f32 v[4:5], v[0:1], v[10:11]
	v_lshlrev_b32_e32 v9, 5, v8
	v_lshlrev_b32_e32 v8, 1, v8
	v_and_b32_e32 v8, 0xffffffe0, v8
	v_add3_u32 v76, 0, v9, v8
	v_pk_add_f32 v[0:1], v[0:1], v[10:11] neg_lo:[0,1] neg_hi:[0,1]
	ds_read_b128 v[8:11], v76
	ds_read_b128 v[68:71], v76 offset:16
	s_mov_b32 s0, 0
	s_mov_b64 s[12:13], -1
	s_waitcnt lgkmcnt(0)
	v_pk_add_f32 v[72:73], v[8:9], v[68:69]
	v_pk_add_f32 v[8:9], v[8:9], v[68:69] neg_lo:[0,1] neg_hi:[0,1]
	v_pk_add_f32 v[68:69], v[10:11], v[70:71]
	v_pk_add_f32 v[10:11], v[10:11], v[70:71] neg_lo:[0,1] neg_hi:[0,1]
	s_nop 0
	v_xor_b32_e32 v71, 0x80000000, v10
	v_mov_b32_e32 v70, v11
	v_pk_add_f32 v[10:11], v[72:73], v[68:69]
	v_pk_add_f32 v[74:75], v[8:9], v[70:71]
	v_pk_add_f32 v[8:9], v[8:9], v[70:71] neg_lo:[0,1] neg_hi:[0,1]
	v_pk_mul_f32 v[70:71], v[66:67], v[10:11] op_sel:[1,1] op_sel_hi:[0,1]
	v_pk_add_f32 v[68:69], v[72:73], v[68:69] neg_lo:[0,1] neg_hi:[0,1]
	v_pk_fma_f32 v[72:73], v[66:67], v[10:11], v[70:71] neg_lo:[0,0,1] neg_hi:[0,0,1]
	v_pk_fma_f32 v[10:11], v[66:67], v[10:11], v[70:71] op_sel_hi:[1,0,1]
	s_nop 0
	v_mov_b32_e32 v73, v11
	v_pk_mul_f32 v[10:11], v[64:65], v[74:75] op_sel:[1,1] op_sel_hi:[0,1]
	v_pk_fma_f32 v[66:67], v[64:65], v[74:75], v[10:11] neg_lo:[0,0,1] neg_hi:[0,0,1]
	v_pk_fma_f32 v[10:11], v[64:65], v[74:75], v[10:11] op_sel_hi:[1,0,1]
	s_nop 0
	v_mov_b32_e32 v67, v11
	v_pk_mul_f32 v[10:11], v[62:63], v[68:69] op_sel:[1,1] op_sel_hi:[0,1]
	v_pk_fma_f32 v[64:65], v[62:63], v[68:69], v[10:11] neg_lo:[0,0,1] neg_hi:[0,0,1]
	v_pk_fma_f32 v[10:11], v[62:63], v[68:69], v[10:11] op_sel_hi:[1,0,1]
	s_nop 0
	v_mov_b32_e32 v65, v11
	v_pk_mul_f32 v[10:11], v[60:61], v[8:9] op_sel:[1,1] op_sel_hi:[0,1]
	v_pk_fma_f32 v[62:63], v[60:61], v[8:9], v[10:11] neg_lo:[0,0,1] neg_hi:[0,0,1]
	v_pk_fma_f32 v[8:9], v[60:61], v[8:9], v[10:11] op_sel_hi:[1,0,1]
	v_pk_add_f32 v[60:61], v[72:73], v[64:65]
	v_mov_b32_e32 v63, v9
	v_pk_add_f32 v[8:9], v[66:67], v[62:63] neg_lo:[0,1] neg_hi:[0,1]
	v_pk_add_f32 v[64:65], v[72:73], v[64:65] neg_lo:[0,1] neg_hi:[0,1]
	v_pk_add_f32 v[68:69], v[66:67], v[62:63]
	v_xor_b32_e32 v62, 0x80000000, v9
	v_mov_b32_e32 v63, v8
	v_pk_add_f32 v[8:9], v[60:61], v[68:69]
	v_pk_add_f32 v[10:11], v[64:65], v[62:63]
	v_pk_add_f32 v[60:61], v[60:61], v[68:69] neg_lo:[0,1] neg_hi:[0,1]
	v_pk_add_f32 v[62:63], v[64:65], v[62:63] neg_lo:[0,1] neg_hi:[0,1]
	ds_write_b128 v76, v[8:11]
	ds_write_b128 v76, v[60:63] offset:16
	v_mov_b32_e32 v8, v140
	s_nop 0
	v_add_u32_e32 v8, 0x200, v8
	v_lshlrev_b32_e32 v9, 5, v8
	v_lshlrev_b32_e32 v8, 1, v8
	v_and_b32_e32 v8, 0xffffffe0, v8
	v_add3_u32 v68, 0, v9, v8
	ds_read_b128 v[8:11], v68
	ds_read_b128 v[60:63], v68 offset:16
	s_waitcnt lgkmcnt(0)
	v_pk_add_f32 v[64:65], v[8:9], v[60:61]
	v_pk_add_f32 v[8:9], v[8:9], v[60:61] neg_lo:[0,1] neg_hi:[0,1]
	v_pk_add_f32 v[60:61], v[10:11], v[62:63]
	v_pk_add_f32 v[10:11], v[10:11], v[62:63] neg_lo:[0,1] neg_hi:[0,1]
	s_nop 0
	v_xor_b32_e32 v63, 0x80000000, v10
	v_mov_b32_e32 v62, v11
	v_pk_add_f32 v[10:11], v[64:65], v[60:61]
	v_pk_add_f32 v[66:67], v[8:9], v[62:63]
	v_pk_add_f32 v[8:9], v[8:9], v[62:63] neg_lo:[0,1] neg_hi:[0,1]
	v_pk_mul_f32 v[62:63], v[58:59], v[10:11] op_sel:[1,1] op_sel_hi:[0,1]
	v_pk_add_f32 v[60:61], v[64:65], v[60:61] neg_lo:[0,1] neg_hi:[0,1]
	v_pk_fma_f32 v[64:65], v[58:59], v[10:11], v[62:63] neg_lo:[0,0,1] neg_hi:[0,0,1]
	v_pk_fma_f32 v[10:11], v[58:59], v[10:11], v[62:63] op_sel_hi:[1,0,1]
	s_nop 0
	v_mov_b32_e32 v65, v11
	v_pk_mul_f32 v[10:11], v[56:57], v[66:67] op_sel:[1,1] op_sel_hi:[0,1]
	v_pk_fma_f32 v[58:59], v[56:57], v[66:67], v[10:11] neg_lo:[0,0,1] neg_hi:[0,0,1]
	v_pk_fma_f32 v[10:11], v[56:57], v[66:67], v[10:11] op_sel_hi:[1,0,1]
	s_nop 0
	v_mov_b32_e32 v59, v11
	v_pk_mul_f32 v[10:11], v[54:55], v[60:61] op_sel:[1,1] op_sel_hi:[0,1]
	v_pk_fma_f32 v[56:57], v[54:55], v[60:61], v[10:11] neg_lo:[0,0,1] neg_hi:[0,0,1]
	v_pk_fma_f32 v[10:11], v[54:55], v[60:61], v[10:11] op_sel_hi:[1,0,1]
	s_nop 0
	v_mov_b32_e32 v57, v11
	v_pk_mul_f32 v[10:11], v[52:53], v[8:9] op_sel:[1,1] op_sel_hi:[0,1]
	v_pk_fma_f32 v[54:55], v[52:53], v[8:9], v[10:11] neg_lo:[0,0,1] neg_hi:[0,0,1]
	v_pk_fma_f32 v[8:9], v[52:53], v[8:9], v[10:11] op_sel_hi:[1,0,1]
	v_pk_add_f32 v[52:53], v[64:65], v[56:57]
	v_mov_b32_e32 v55, v9
	v_pk_add_f32 v[8:9], v[58:59], v[54:55] neg_lo:[0,1] neg_hi:[0,1]
	v_pk_add_f32 v[56:57], v[64:65], v[56:57] neg_lo:[0,1] neg_hi:[0,1]
	v_pk_add_f32 v[60:61], v[58:59], v[54:55]
	v_xor_b32_e32 v54, 0x80000000, v9
	v_mov_b32_e32 v55, v8
	v_pk_add_f32 v[8:9], v[52:53], v[60:61]
	v_pk_add_f32 v[10:11], v[56:57], v[54:55]
	v_pk_add_f32 v[52:53], v[52:53], v[60:61] neg_lo:[0,1] neg_hi:[0,1]
	v_pk_add_f32 v[54:55], v[56:57], v[54:55] neg_lo:[0,1] neg_hi:[0,1]
	ds_write_b128 v68, v[8:11]
	ds_write_b128 v68, v[52:55] offset:16
	v_mov_b32_e32 v8, v140
	s_nop 0
	v_add_u32_e32 v8, 0x400, v8
	v_lshlrev_b32_e32 v9, 5, v8
	v_lshlrev_b32_e32 v8, 1, v8
	v_and_b32_e32 v8, 0xffffffe0, v8
	v_add3_u32 v60, 0, v9, v8
	ds_read_b128 v[8:11], v60
	ds_read_b128 v[52:55], v60 offset:16
	s_waitcnt lgkmcnt(0)
; #define LAS __attribute__((address_space(3)))
; __device__ __forceinline__ f32x2 cmul(f32x2 a, f32x2 b) { return (f32x2){a.x * b.x - a.y * b.y, a.x * b.y + a.y * b.x}; }
; #define LT() ({ int lt_ = tid; asm volatile("" : "+v"(lt_)); lt_; })
; __device__ __forceinline__ void hyena_latent(Frame& F, int l, int ch, LAS f32x2* X, const LAS f32x2* TH, const LAS f32x2* TL, GAS f32x2* KS, const LAS float* CT  , bool wr = true) {
;     ...
;             fft_fwd_head(X, TH, TL, tid);
; #pragma unroll
;             for (int i = 0; i < 8; ++i) { const int b = LT() + NTHR * i; LAS f32x4* P = (LAS f32x4*)(X + 4 * b + ((b >> 4) << 2)); const f32x4 u = P[0], v = P[1], k0 = kreg[2 * i], k1 = kreg[2 * i + 1];
;                 f32x2 x0 = {u.x, u.y}, x1 = {u.z, u.w}, x2 = {v.x, v.y}, x3 = {v.z, v.w}; r4<false>(x0, x1, x2, x3);
;                 x0 = cmul(x0, (f32x2){k0.x, k0.y}); x1 = cmul(x1, (f32x2){k0.z, k0.w}); x2 = cmul(x2, (f32x2){k1.x, k1.y}); x3 = cmul(x3, (f32x2){k1.z, k1.w});
;                 r4<true>(x0, x1, x2, x3);
;                 P[0] = (f32x4){x0.x, x0.y, x1.x, x1.y}; P[1] = (f32x4){x2.x, x2.y, x3.x, x3.y};
;                 if (i & 1) asm volatile("" ::: "memory"); }
;             __syncthreads();
	v_pk_add_f32 v[56:57], v[8:9], v[52:53]
	v_pk_add_f32 v[8:9], v[8:9], v[52:53] neg_lo:[0,1] neg_hi:[0,1]
	v_pk_add_f32 v[52:53], v[10:11], v[54:55]
	v_pk_add_f32 v[10:11], v[10:11], v[54:55] neg_lo:[0,1] neg_hi:[0,1]
	s_nop 0
	v_xor_b32_e32 v55, 0x80000000, v10
	v_mov_b32_e32 v54, v11
	v_pk_add_f32 v[10:11], v[56:57], v[52:53]
	v_pk_add_f32 v[58:59], v[8:9], v[54:55]
	v_pk_add_f32 v[8:9], v[8:9], v[54:55] neg_lo:[0,1] neg_hi:[0,1]
	v_pk_mul_f32 v[54:55], v[50:51], v[10:11] op_sel:[1,1] op_sel_hi:[0,1]
	v_pk_add_f32 v[52:53], v[56:57], v[52:53] neg_lo:[0,1] neg_hi:[0,1]
	v_pk_fma_f32 v[56:57], v[50:51], v[10:11], v[54:55] neg_lo:[0,0,1] neg_hi:[0,0,1]
	v_pk_fma_f32 v[10:11], v[50:51], v[10:11], v[54:55] op_sel_hi:[1,0,1]
	s_nop 0
	v_mov_b32_e32 v57, v11
	v_pk_mul_f32 v[10:11], v[48:49], v[58:59] op_sel:[1,1] op_sel_hi:[0,1]
	v_pk_fma_f32 v[50:51], v[48:49], v[58:59], v[10:11] neg_lo:[0,0,1] neg_hi:[0,0,1]
	v_pk_fma_f32 v[10:11], v[48:49], v[58:59], v[10:11] op_sel_hi:[1,0,1]
	s_nop 0
	v_mov_b32_e32 v51, v11
	v_pk_mul_f32 v[10:11], v[46:47], v[52:53] op_sel:[1,1] op_sel_hi:[0,1]
	v_pk_fma_f32 v[48:49], v[46:47], v[52:53], v[10:11] neg_lo:[0,0,1] neg_hi:[0,0,1]
	v_pk_fma_f32 v[10:11], v[46:47], v[52:53], v[10:11] op_sel_hi:[1,0,1]
	s_nop 0
	v_mov_b32_e32 v49, v11
	v_pk_mul_f32 v[10:11], v[44:45], v[8:9] op_sel:[1,1] op_sel_hi:[0,1]
	v_pk_fma_f32 v[46:47], v[44:45], v[8:9], v[10:11] neg_lo:[0,0,1] neg_hi:[0,0,1]
	v_pk_fma_f32 v[8:9], v[44:45], v[8:9], v[10:11] op_sel_hi:[1,0,1]
	v_pk_add_f32 v[44:45], v[56:57], v[48:49]
	v_mov_b32_e32 v47, v9
	v_pk_add_f32 v[8:9], v[50:51], v[46:47] neg_lo:[0,1] neg_hi:[0,1]
	v_pk_add_f32 v[48:49], v[56:57], v[48:49] neg_lo:[0,1] neg_hi:[0,1]
	v_pk_add_f32 v[52:53], v[50:51], v[46:47]
	v_xor_b32_e32 v46, 0x80000000, v9
	v_mov_b32_e32 v47, v8
	v_pk_add_f32 v[8:9], v[44:45], v[52:53]
	v_pk_add_f32 v[10:11], v[48:49], v[46:47]
	v_pk_add_f32 v[44:45], v[44:45], v[52:53] neg_lo:[0,1] neg_hi:[0,1]
	v_pk_add_f32 v[46:47], v[48:49], v[46:47] neg_lo:[0,1] neg_hi:[0,1]
	ds_write_b128 v60, v[8:11]
	ds_write_b128 v60, v[44:47] offset:16
	v_mov_b32_e32 v8, v140
	s_nop 0
	v_add_u32_e32 v8, 0x600, v8
	v_lshlrev_b32_e32 v9, 5, v8
	v_lshlrev_b32_e32 v8, 1, v8
	v_and_b32_e32 v8, 0xffffffe0, v8
	v_add3_u32 v52, 0, v9, v8
	ds_read_b128 v[8:11], v52
	ds_read_b128 v[44:47], v52 offset:16
	s_waitcnt lgkmcnt(0)
	v_pk_add_f32 v[48:49], v[8:9], v[44:45]
	v_pk_add_f32 v[8:9], v[8:9], v[44:45] neg_lo:[0,1] neg_hi:[0,1]
	v_pk_add_f32 v[44:45], v[10:11], v[46:47]
	v_pk_add_f32 v[10:11], v[10:11], v[46:47] neg_lo:[0,1] neg_hi:[0,1]
	s_nop 0
	v_xor_b32_e32 v47, 0x80000000, v10
	v_mov_b32_e32 v46, v11
	v_pk_add_f32 v[10:11], v[48:49], v[44:45]
	v_pk_add_f32 v[50:51], v[8:9], v[46:47]
	v_pk_add_f32 v[8:9], v[8:9], v[46:47] neg_lo:[0,1] neg_hi:[0,1]
	v_pk_mul_f32 v[46:47], v[42:43], v[10:11] op_sel:[1,1] op_sel_hi:[0,1]
	v_pk_add_f32 v[44:45], v[48:49], v[44:45] neg_lo:[0,1] neg_hi:[0,1]
	v_pk_fma_f32 v[48:49], v[42:43], v[10:11], v[46:47] neg_lo:[0,0,1] neg_hi:[0,0,1]
	v_pk_fma_f32 v[10:11], v[42:43], v[10:11], v[46:47] op_sel_hi:[1,0,1]
	s_nop 0
	v_mov_b32_e32 v49, v11
	v_pk_mul_f32 v[10:11], v[40:41], v[50:51] op_sel:[1,1] op_sel_hi:[0,1]
	v_pk_fma_f32 v[42:43], v[40:41], v[50:51], v[10:11] neg_lo:[0,0,1] neg_hi:[0,0,1]
	v_pk_fma_f32 v[10:11], v[40:41], v[50:51], v[10:11] op_sel_hi:[1,0,1]
	s_nop 0
	v_mov_b32_e32 v43, v11
	v_pk_mul_f32 v[10:11], v[38:39], v[44:45] op_sel:[1,1] op_sel_hi:[0,1]
	v_pk_fma_f32 v[40:41], v[38:39], v[44:45], v[10:11] neg_lo:[0,0,1] neg_hi:[0,0,1]
	v_pk_fma_f32 v[10:11], v[38:39], v[44:45], v[10:11] op_sel_hi:[1,0,1]
	s_nop 0
	v_mov_b32_e32 v41, v11
	v_pk_mul_f32 v[10:11], v[36:37], v[8:9] op_sel:[1,1] op_sel_hi:[0,1]
	v_pk_fma_f32 v[38:39], v[36:37], v[8:9], v[10:11] neg_lo:[0,0,1] neg_hi:[0,0,1]
	v_pk_fma_f32 v[8:9], v[36:37], v[8:9], v[10:11] op_sel_hi:[1,0,1]
	v_pk_add_f32 v[36:37], v[48:49], v[40:41]
	v_mov_b32_e32 v39, v9
	v_pk_add_f32 v[8:9], v[42:43], v[38:39] neg_lo:[0,1] neg_hi:[0,1]
	v_pk_add_f32 v[40:41], v[48:49], v[40:41] neg_lo:[0,1] neg_hi:[0,1]
	v_pk_add_f32 v[44:45], v[42:43], v[38:39]
	v_xor_b32_e32 v38, 0x80000000, v9
	v_mov_b32_e32 v39, v8
	v_pk_add_f32 v[8:9], v[36:37], v[44:45]
	v_pk_add_f32 v[10:11], v[40:41], v[38:39]
	v_pk_add_f32 v[36:37], v[36:37], v[44:45] neg_lo:[0,1] neg_hi:[0,1]
	v_pk_add_f32 v[38:39], v[40:41], v[38:39] neg_lo:[0,1] neg_hi:[0,1]
	ds_write_b128 v52, v[8:11]
	ds_write_b128 v52, v[36:39] offset:16
	v_mov_b32_e32 v8, v140
	s_nop 0
	v_add_u32_e32 v8, 0x800, v8
	v_lshlrev_b32_e32 v9, 5, v8
	v_lshlrev_b32_e32 v8, 1, v8
	v_and_b32_e32 v8, 0xffffffe0, v8
	v_add3_u32 v44, 0, v9, v8
	ds_read_b128 v[8:11], v44
	ds_read_b128 v[36:39], v44 offset:16
	s_waitcnt lgkmcnt(0)
; #define LAS __attribute__((address_space(3)))
; __device__ __forceinline__ f32x2 cmul(f32x2 a, f32x2 b) { return (f32x2){a.x * b.x - a.y * b.y, a.x * b.y + a.y * b.x}; }
; #define LT() ({ int lt_ = tid; asm volatile("" : "+v"(lt_)); lt_; })
; __device__ __forceinline__ void hyena_latent(Frame& F, int l, int ch, LAS f32x2* X, const LAS f32x2* TH, const LAS f32x2* TL, GAS f32x2* KS, const LAS float* CT  , bool wr = true) {
;     ...
;             fft_fwd_head(X, TH, TL, tid);
; #pragma unroll
;             for (int i = 0; i < 8; ++i) { const int b = LT() + NTHR * i; LAS f32x4* P = (LAS f32x4*)(X + 4 * b + ((b >> 4) << 2)); const f32x4 u = P[0], v = P[1], k0 = kreg[2 * i], k1 = kreg[2 * i + 1];
;                 f32x2 x0 = {u.x, u.y}, x1 = {u.z, u.w}, x2 = {v.x, v.y}, x3 = {v.z, v.w}; r4<false>(x0, x1, x2, x3);
;                 x0 = cmul(x0, (f32x2){k0.x, k0.y}); x1 = cmul(x1, (f32x2){k0.z, k0.w}); x2 = cmul(x2, (f32x2){k1.x, k1.y}); x3 = cmul(x3, (f32x2){k1.z, k1.w});
;                 r4<true>(x0, x1, x2, x3);
;                 P[0] = (f32x4){x0.x, x0.y, x1.x, x1.y}; P[1] = (f32x4){x2.x, x2.y, x3.x, x3.y};
;                 if (i & 1) asm volatile("" ::: "memory"); }
;             __syncthreads();
	v_pk_add_f32 v[40:41], v[8:9], v[36:37]
	v_pk_add_f32 v[8:9], v[8:9], v[36:37] neg_lo:[0,1] neg_hi:[0,1]
	v_pk_add_f32 v[36:37], v[10:11], v[38:39]
	v_pk_add_f32 v[10:11], v[10:11], v[38:39] neg_lo:[0,1] neg_hi:[0,1]
	s_nop 0
	v_xor_b32_e32 v39, 0x80000000, v10
	v_mov_b32_e32 v38, v11
	v_pk_add_f32 v[10:11], v[40:41], v[36:37]
	v_pk_add_f32 v[42:43], v[8:9], v[38:39]
	v_pk_add_f32 v[8:9], v[8:9], v[38:39] neg_lo:[0,1] neg_hi:[0,1]
	v_pk_mul_f32 v[38:39], v[34:35], v[10:11] op_sel:[1,1] op_sel_hi:[0,1]
	v_pk_add_f32 v[36:37], v[40:41], v[36:37] neg_lo:[0,1] neg_hi:[0,1]
	v_pk_fma_f32 v[40:41], v[34:35], v[10:11], v[38:39] neg_lo:[0,0,1] neg_hi:[0,0,1]
	v_pk_fma_f32 v[10:11], v[34:35], v[10:11], v[38:39] op_sel_hi:[1,0,1]
	s_nop 0
	v_mov_b32_e32 v41, v11
	v_pk_mul_f32 v[10:11], v[32:33], v[42:43] op_sel:[1,1] op_sel_hi:[0,1]
	v_pk_fma_f32 v[34:35], v[32:33], v[42:43], v[10:11] neg_lo:[0,0,1] neg_hi:[0,0,1]
	v_pk_fma_f32 v[10:11], v[32:33], v[42:43], v[10:11] op_sel_hi:[1,0,1]
	s_nop 0
	v_mov_b32_e32 v35, v11
	v_pk_mul_f32 v[10:11], v[30:31], v[36:37] op_sel:[1,1] op_sel_hi:[0,1]
	v_pk_fma_f32 v[32:33], v[30:31], v[36:37], v[10:11] neg_lo:[0,0,1] neg_hi:[0,0,1]
	v_pk_fma_f32 v[10:11], v[30:31], v[36:37], v[10:11] op_sel_hi:[1,0,1]
	s_nop 0
	v_mov_b32_e32 v33, v11
	v_pk_mul_f32 v[10:11], v[28:29], v[8:9] op_sel:[1,1] op_sel_hi:[0,1]
	v_pk_fma_f32 v[30:31], v[28:29], v[8:9], v[10:11] neg_lo:[0,0,1] neg_hi:[0,0,1]
	v_pk_fma_f32 v[8:9], v[28:29], v[8:9], v[10:11] op_sel_hi:[1,0,1]
	v_pk_add_f32 v[28:29], v[40:41], v[32:33]
	v_mov_b32_e32 v31, v9
	v_pk_add_f32 v[8:9], v[34:35], v[30:31] neg_lo:[0,1] neg_hi:[0,1]
	v_pk_add_f32 v[32:33], v[40:41], v[32:33] neg_lo:[0,1] neg_hi:[0,1]
	v_pk_add_f32 v[36:37], v[34:35], v[30:31]
	v_xor_b32_e32 v30, 0x80000000, v9
	v_mov_b32_e32 v31, v8
	v_pk_add_f32 v[8:9], v[28:29], v[36:37]
	v_pk_add_f32 v[10:11], v[32:33], v[30:31]
	v_pk_add_f32 v[28:29], v[28:29], v[36:37] neg_lo:[0,1] neg_hi:[0,1]
	v_pk_add_f32 v[30:31], v[32:33], v[30:31] neg_lo:[0,1] neg_hi:[0,1]
	ds_write_b128 v44, v[8:11]
	ds_write_b128 v44, v[28:31] offset:16
	v_mov_b32_e32 v8, v140
	s_nop 0
	v_add_u32_e32 v8, 0xa00, v8
	v_lshlrev_b32_e32 v9, 5, v8
	v_lshlrev_b32_e32 v8, 1, v8
	v_and_b32_e32 v8, 0xffffffe0, v8
	v_add3_u32 v36, 0, v9, v8
	ds_read_b128 v[8:11], v36
	ds_read_b128 v[28:31], v36 offset:16
	s_waitcnt lgkmcnt(0)
	v_pk_add_f32 v[32:33], v[8:9], v[28:29]
	v_pk_add_f32 v[8:9], v[8:9], v[28:29] neg_lo:[0,1] neg_hi:[0,1]
	v_pk_add_f32 v[28:29], v[10:11], v[30:31]
	v_pk_add_f32 v[10:11], v[10:11], v[30:31] neg_lo:[0,1] neg_hi:[0,1]
	s_nop 0
	v_xor_b32_e32 v31, 0x80000000, v10
	v_mov_b32_e32 v30, v11
	v_pk_add_f32 v[10:11], v[32:33], v[28:29]
	v_pk_add_f32 v[34:35], v[8:9], v[30:31]
	v_pk_add_f32 v[8:9], v[8:9], v[30:31] neg_lo:[0,1] neg_hi:[0,1]
	v_pk_mul_f32 v[30:31], v[26:27], v[10:11] op_sel:[1,1] op_sel_hi:[0,1]
	v_pk_add_f32 v[28:29], v[32:33], v[28:29] neg_lo:[0,1] neg_hi:[0,1]
	v_pk_fma_f32 v[32:33], v[26:27], v[10:11], v[30:31] neg_lo:[0,0,1] neg_hi:[0,0,1]
	v_pk_fma_f32 v[10:11], v[26:27], v[10:11], v[30:31] op_sel_hi:[1,0,1]
	s_nop 0
	v_mov_b32_e32 v33, v11
	v_pk_mul_f32 v[10:11], v[24:25], v[34:35] op_sel:[1,1] op_sel_hi:[0,1]
	v_pk_fma_f32 v[26:27], v[24:25], v[34:35], v[10:11] neg_lo:[0,0,1] neg_hi:[0,0,1]
	v_pk_fma_f32 v[10:11], v[24:25], v[34:35], v[10:11] op_sel_hi:[1,0,1]
	s_nop 0
	v_mov_b32_e32 v27, v11
	v_pk_mul_f32 v[10:11], v[22:23], v[28:29] op_sel:[1,1] op_sel_hi:[0,1]
	v_pk_fma_f32 v[24:25], v[22:23], v[28:29], v[10:11] neg_lo:[0,0,1] neg_hi:[0,0,1]
	v_pk_fma_f32 v[10:11], v[22:23], v[28:29], v[10:11] op_sel_hi:[1,0,1]
	s_nop 0
	v_mov_b32_e32 v25, v11
	v_pk_mul_f32 v[10:11], v[20:21], v[8:9] op_sel:[1,1] op_sel_hi:[0,1]
	v_pk_fma_f32 v[22:23], v[20:21], v[8:9], v[10:11] neg_lo:[0,0,1] neg_hi:[0,0,1]
	v_pk_fma_f32 v[8:9], v[20:21], v[8:9], v[10:11] op_sel_hi:[1,0,1]
	v_pk_add_f32 v[20:21], v[32:33], v[24:25]
	v_mov_b32_e32 v23, v9
	v_pk_add_f32 v[8:9], v[26:27], v[22:23] neg_lo:[0,1] neg_hi:[0,1]
	v_pk_add_f32 v[24:25], v[32:33], v[24:25] neg_lo:[0,1] neg_hi:[0,1]
	v_pk_add_f32 v[28:29], v[26:27], v[22:23]
	v_xor_b32_e32 v22, 0x80000000, v9
	v_mov_b32_e32 v23, v8
	v_pk_add_f32 v[8:9], v[20:21], v[28:29]
	v_pk_add_f32 v[10:11], v[24:25], v[22:23]
	v_pk_add_f32 v[20:21], v[20:21], v[28:29] neg_lo:[0,1] neg_hi:[0,1]
	v_pk_add_f32 v[22:23], v[24:25], v[22:23] neg_lo:[0,1] neg_hi:[0,1]
	ds_write_b128 v36, v[8:11]
	ds_write_b128 v36, v[20:23] offset:16
	v_mov_b32_e32 v8, v140
	s_nop 0
	v_add_u32_e32 v8, 0xc00, v8
	v_lshlrev_b32_e32 v9, 5, v8
	v_lshlrev_b32_e32 v8, 1, v8
	v_and_b32_e32 v8, 0xffffffe0, v8
	v_add3_u32 v28, 0, v9, v8
	ds_read_b128 v[8:11], v28
	ds_read_b128 v[20:23], v28 offset:16
	s_waitcnt lgkmcnt(0)
; #define LAS __attribute__((address_space(3)))
; __device__ __forceinline__ f32x2 cmul(f32x2 a, f32x2 b) { return (f32x2){a.x * b.x - a.y * b.y, a.x * b.y + a.y * b.x}; }
; #define LT() ({ int lt_ = tid; asm volatile("" : "+v"(lt_)); lt_; })
; __device__ __forceinline__ void hyena_latent(Frame& F, int l, int ch, LAS f32x2* X, const LAS f32x2* TH, const LAS f32x2* TL, GAS f32x2* KS, const LAS float* CT  , bool wr = true) {
;     ...
;             fft_fwd_head(X, TH, TL, tid);
; #pragma unroll
;             for (int i = 0; i < 8; ++i) { const int b = LT() + NTHR * i; LAS f32x4* P = (LAS f32x4*)(X + 4 * b + ((b >> 4) << 2)); const f32x4 u = P[0], v = P[1], k0 = kreg[2 * i], k1 = kreg[2 * i + 1];
;                 f32x2 x0 = {u.x, u.y}, x1 = {u.z, u.w}, x2 = {v.x, v.y}, x3 = {v.z, v.w}; r4<false>(x0, x1, x2, x3);
;                 x0 = cmul(x0, (f32x2){k0.x, k0.y}); x1 = cmul(x1, (f32x2){k0.z, k0.w}); x2 = cmul(x2, (f32x2){k1.x, k1.y}); x3 = cmul(x3, (f32x2){k1.z, k1.w});
;                 r4<true>(x0, x1, x2, x3);
;                 P[0] = (f32x4){x0.x, x0.y, x1.x, x1.y}; P[1] = (f32x4){x2.x, x2.y, x3.x, x3.y};
;                 if (i & 1) asm volatile("" ::: "memory"); }
;             __syncthreads();
;             fft_inv_tail(X, TH, TL, tid);
	v_pk_add_f32 v[24:25], v[8:9], v[20:21]
	v_pk_add_f32 v[8:9], v[8:9], v[20:21] neg_lo:[0,1] neg_hi:[0,1]
	v_pk_add_f32 v[20:21], v[10:11], v[22:23]
	v_pk_add_f32 v[10:11], v[10:11], v[22:23] neg_lo:[0,1] neg_hi:[0,1]
	s_nop 0
	v_xor_b32_e32 v23, 0x80000000, v10
	v_mov_b32_e32 v22, v11
	v_pk_add_f32 v[10:11], v[24:25], v[20:21]
	v_pk_add_f32 v[26:27], v[8:9], v[22:23]
	v_pk_add_f32 v[8:9], v[8:9], v[22:23] neg_lo:[0,1] neg_hi:[0,1]
	v_pk_mul_f32 v[22:23], v[18:19], v[10:11] op_sel:[1,1] op_sel_hi:[0,1]
	v_pk_add_f32 v[20:21], v[24:25], v[20:21] neg_lo:[0,1] neg_hi:[0,1]
	v_pk_fma_f32 v[24:25], v[18:19], v[10:11], v[22:23] neg_lo:[0,0,1] neg_hi:[0,0,1]
	v_pk_fma_f32 v[10:11], v[18:19], v[10:11], v[22:23] op_sel_hi:[1,0,1]
	s_nop 0
	v_mov_b32_e32 v25, v11
	v_pk_mul_f32 v[10:11], v[16:17], v[26:27] op_sel:[1,1] op_sel_hi:[0,1]
	v_pk_fma_f32 v[18:19], v[16:17], v[26:27], v[10:11] neg_lo:[0,0,1] neg_hi:[0,0,1]
	v_pk_fma_f32 v[10:11], v[16:17], v[26:27], v[10:11] op_sel_hi:[1,0,1]
	s_nop 0
	v_mov_b32_e32 v19, v11
	v_pk_mul_f32 v[10:11], v[14:15], v[20:21] op_sel:[1,1] op_sel_hi:[0,1]
	v_pk_fma_f32 v[16:17], v[14:15], v[20:21], v[10:11] neg_lo:[0,0,1] neg_hi:[0,0,1]
	v_pk_fma_f32 v[10:11], v[14:15], v[20:21], v[10:11] op_sel_hi:[1,0,1]
	s_nop 0
	v_mov_b32_e32 v17, v11
	v_pk_mul_f32 v[10:11], v[12:13], v[8:9] op_sel:[1,1] op_sel_hi:[0,1]
	v_pk_fma_f32 v[14:15], v[12:13], v[8:9], v[10:11] neg_lo:[0,0,1] neg_hi:[0,0,1]
	v_pk_fma_f32 v[8:9], v[12:13], v[8:9], v[10:11] op_sel_hi:[1,0,1]
	v_pk_add_f32 v[12:13], v[24:25], v[16:17]
	v_mov_b32_e32 v15, v9
	v_pk_add_f32 v[8:9], v[18:19], v[14:15] neg_lo:[0,1] neg_hi:[0,1]
	v_pk_add_f32 v[16:17], v[24:25], v[16:17] neg_lo:[0,1] neg_hi:[0,1]
	v_pk_add_f32 v[20:21], v[18:19], v[14:15]
	v_xor_b32_e32 v14, 0x80000000, v9
	v_mov_b32_e32 v15, v8
	v_pk_add_f32 v[8:9], v[12:13], v[20:21]
	v_pk_add_f32 v[10:11], v[16:17], v[14:15]
	v_pk_add_f32 v[12:13], v[12:13], v[20:21] neg_lo:[0,1] neg_hi:[0,1]
	v_pk_add_f32 v[14:15], v[16:17], v[14:15] neg_lo:[0,1] neg_hi:[0,1]
	ds_write_b128 v28, v[8:11]
	ds_write_b128 v28, v[12:15] offset:16
	v_mov_b32_e32 v8, v140
	s_nop 0
	v_add_u32_e32 v8, 0xe00, v8
	v_lshlrev_b32_e32 v9, 5, v8
	v_lshlrev_b32_e32 v8, 1, v8
	v_and_b32_e32 v8, 0xffffffe0, v8
	v_add3_u32 v20, 0, v9, v8
	ds_read_b128 v[8:11], v20
	ds_read_b128 v[12:15], v20 offset:16
	s_waitcnt lgkmcnt(0)
	v_pk_add_f32 v[16:17], v[8:9], v[12:13]
	v_pk_add_f32 v[8:9], v[8:9], v[12:13] neg_lo:[0,1] neg_hi:[0,1]
	v_pk_add_f32 v[12:13], v[10:11], v[14:15]
	v_pk_add_f32 v[10:11], v[10:11], v[14:15] neg_lo:[0,1] neg_hi:[0,1]
	s_nop 0
	v_xor_b32_e32 v15, 0x80000000, v10
	v_mov_b32_e32 v14, v11
	v_pk_add_f32 v[10:11], v[16:17], v[12:13]
	v_pk_add_f32 v[18:19], v[8:9], v[14:15]
	v_pk_add_f32 v[8:9], v[8:9], v[14:15] neg_lo:[0,1] neg_hi:[0,1]
	v_pk_mul_f32 v[14:15], v[6:7], v[10:11] op_sel:[1,1] op_sel_hi:[0,1]
	v_pk_add_f32 v[12:13], v[16:17], v[12:13] neg_lo:[0,1] neg_hi:[0,1]
	v_pk_fma_f32 v[16:17], v[6:7], v[10:11], v[14:15] neg_lo:[0,0,1] neg_hi:[0,0,1]
	v_pk_fma_f32 v[6:7], v[6:7], v[10:11], v[14:15] op_sel_hi:[1,0,1]
	s_nop 0
	v_mov_b32_e32 v17, v7
	v_pk_mul_f32 v[6:7], v[4:5], v[18:19] op_sel:[1,1] op_sel_hi:[0,1]
	v_pk_fma_f32 v[10:11], v[4:5], v[18:19], v[6:7] neg_lo:[0,0,1] neg_hi:[0,0,1]
	v_pk_fma_f32 v[4:5], v[4:5], v[18:19], v[6:7] op_sel_hi:[1,0,1]
	s_nop 0
	v_mov_b32_e32 v11, v5
	v_pk_mul_f32 v[4:5], v[2:3], v[12:13] op_sel:[1,1] op_sel_hi:[0,1]
	v_pk_fma_f32 v[6:7], v[2:3], v[12:13], v[4:5] neg_lo:[0,0,1] neg_hi:[0,0,1]
	v_pk_fma_f32 v[2:3], v[2:3], v[12:13], v[4:5] op_sel_hi:[1,0,1]
	s_nop 0
	v_mov_b32_e32 v7, v3
	v_pk_mul_f32 v[2:3], v[0:1], v[8:9] op_sel:[1,1] op_sel_hi:[0,1]
	v_pk_fma_f32 v[4:5], v[0:1], v[8:9], v[2:3] neg_lo:[0,0,1] neg_hi:[0,0,1]
	v_pk_fma_f32 v[0:1], v[0:1], v[8:9], v[2:3] op_sel_hi:[1,0,1]
	v_pk_add_f32 v[8:9], v[16:17], v[6:7]
	v_mov_b32_e32 v5, v1
	v_pk_add_f32 v[0:1], v[10:11], v[4:5] neg_lo:[0,1] neg_hi:[0,1]
	v_pk_add_f32 v[6:7], v[16:17], v[6:7] neg_lo:[0,1] neg_hi:[0,1]
	v_pk_add_f32 v[12:13], v[10:11], v[4:5]
	v_xor_b32_e32 v10, 0x80000000, v1
	v_mov_b32_e32 v11, v0
	v_pk_add_f32 v[0:1], v[8:9], v[12:13]
	v_pk_add_f32 v[2:3], v[6:7], v[10:11]
	v_pk_add_f32 v[4:5], v[8:9], v[12:13] neg_lo:[0,1] neg_hi:[0,1]
	v_pk_add_f32 v[6:7], v[6:7], v[10:11] neg_lo:[0,1] neg_hi:[0,1]
	ds_write_b128 v20, v[0:3]
	ds_write_b128 v20, v[4:7] offset:16
	s_waitcnt lgkmcnt(0)
	s_barrier
	ds_read2_b64 v[232:235], v141 offset0:4 offset1:8
	ds_read2_b64 v[208:211], v141 offset0:12 offset1:16
	ds_read2_b64 v[204:207], v141 offset0:20 offset1:24
	ds_read2_b64 v[200:203], v141 offset0:28 offset1:32
	ds_read2_b64 v[196:199], v141 offset0:36 offset1:40
	ds_read2_b64 v[192:195], v141 offset0:44 offset1:48
	ds_read2_b64 v[188:191], v141 offset0:52 offset1:56
	ds_read_b64 v[186:187], v141 offset:480
; #define LAS __attribute__((address_space(3)))
; __device__ __forceinline__ f32x2 cmul(f32x2 a, f32x2 b) { return (f32x2){a.x * b.x - a.y * b.y, a.x * b.y + a.y * b.x}; }
; template <bool INV> __device__ __forceinline__ void dft16(f32x2 (&x)[16]) {
; #pragma unroll
;     for (int b = 0; b < 4; ++b) r4<INV>(x[b], x[4 + b], x[8 + b], x[12 + b]);
;     const float sg = INV ? -1.f : 1.f;
;     const f32x2 W1 = {0.92387953251f, -0.38268343236f * sg}, W2 = {0.70710678118f, -0.70710678118f * sg}, W3 = {0.38268343236f, -0.92387953251f * sg},
;                 W4 = {0.f, -1.f * sg}, W6 = {-0.70710678118f, -0.70710678118f * sg}, W9 = {-0.92387953251f, 0.38268343236f * sg};
;     x[5] = cmul(x[5], W1); x[9] = cmul(x[9], W2); x[13] = cmul(x[13], W3);
;     x[6] = cmul(x[6], W2); x[10] = cmul(x[10], W4); x[14] = cmul(x[14], W6);
;     x[7] = cmul(x[7], W3); x[11] = cmul(x[11], W6); x[15] = cmul(x[15], W9);
; #pragma unroll
;     for (int c = 0; c < 4; ++c) r4<INV>(x[4 * c], x[4 * c + 1], x[4 * c + 2], x[4 * c + 3]);
; }
; template <bool INV> __device__ __forceinline__ void bfly16_tab(f32x2 (&x)[16], const LAS f32x2* T, int tstride, int j) {
;     if (INV) {
; #pragma unroll
;         for (int q = 1; q < 16; ++q) { f32x2 p = T[q * tstride + j]; p.y = -p.y; x[q] = cmul(x[q], p); } }
;     dft16<INV>(x);
.LBB0_852:
	v_add_u32_e32 v128, s0, v140
	v_lshrrev_b32_e32 v147, 2, v128
	v_mad_u32_u24 v151, v147, s43, v144
	ds_read_b64 v[0:1], v151 offset:128
	ds_read_b64 v[2:3], v151 offset:32
	ds_read_b64 v[4:5], v151 offset:64
	ds_read_b64 v[6:7], v151 offset:96
	ds_read_b64 v[8:9], v151 offset:160
	ds_read_b64 v[10:11], v151 offset:192
	ds_read_b64 v[12:13], v151 offset:224
	ds_read_b64 v[14:15], v151 offset:0
	ds_read_b64 v[16:17], v151 offset:256
	ds_read_b64 v[18:19], v151 offset:384
	ds_read_b64 v[20:21], v151 offset:288
	ds_read_b64 v[22:23], v151 offset:320
	ds_read_b64 v[24:25], v151 offset:352
	ds_read_b64 v[26:27], v151 offset:416
	ds_read_b64 v[28:29], v151 offset:448
	ds_read_b64 v[30:31], v151 offset:480
	s_cmp_eq_u32 s0, 0
	s_movk_i32 s0, 0x200
	s_mov_b64 s[12:13], 0
	s_waitcnt lgkmcnt(15)
	v_pk_mul_f32 v[32:33], v[0:1], v[210:211] op_sel:[0,1] op_sel_hi:[1,1]
	s_waitcnt lgkmcnt(14)
	v_pk_mul_f32 v[34:35], v[2:3], v[232:233] op_sel:[0,1] op_sel_hi:[1,1]
	s_waitcnt lgkmcnt(13)
	v_pk_mul_f32 v[36:37], v[4:5], v[234:235] op_sel:[0,1] op_sel_hi:[1,1]
	s_waitcnt lgkmcnt(12)
	v_pk_mul_f32 v[38:39], v[6:7], v[208:209] op_sel:[0,1] op_sel_hi:[1,1]
	v_pk_fma_f32 v[32:33], v[0:1], v[210:211], v[32:33] op_sel:[0,0,1] op_sel_hi:[1,0,0] neg_hi:[0,0,1]
	s_waitcnt lgkmcnt(11)
	v_pk_mul_f32 v[0:1], v[8:9], v[204:205] op_sel:[0,1] op_sel_hi:[1,1]
	s_waitcnt lgkmcnt(10)
	v_pk_mul_f32 v[40:41], v[10:11], v[206:207] op_sel:[0,1] op_sel_hi:[1,1]
	s_waitcnt lgkmcnt(9)
	v_pk_mul_f32 v[42:43], v[12:13], v[200:201] op_sel:[0,1] op_sel_hi:[1,1]
	s_waitcnt lgkmcnt(7)
	v_pk_fma_f32 v[44:45], v[16:17], v[202:203], v[14:15] op_sel:[0,1,1] op_sel_hi:[1,1,0] neg_lo:[0,0,1]
	v_pk_fma_f32 v[2:3], v[2:3], v[232:233], v[34:35] op_sel:[0,0,1] op_sel_hi:[1,0,0] neg_hi:[0,0,1]
	v_pk_fma_f32 v[4:5], v[4:5], v[234:235], v[36:37] op_sel:[0,0,1] op_sel_hi:[1,0,0] neg_hi:[0,0,1]
	v_pk_fma_f32 v[38:39], v[6:7], v[208:209], v[38:39] op_sel:[0,0,1] op_sel_hi:[1,0,0] neg_hi:[0,0,1]
	v_pk_fma_f32 v[16:17], v[16:17], v[202:203], v[44:45] op_sel:[0,0,1] op_sel_hi:[1,0,0] neg_hi:[0,0,1]
	v_pk_fma_f32 v[8:9], v[8:9], v[204:205], v[0:1] op_sel:[0,0,1] op_sel_hi:[1,0,0] neg_hi:[0,0,1]
	v_pk_fma_f32 v[10:11], v[10:11], v[206:207], v[40:41] op_sel:[0,0,1] op_sel_hi:[1,0,0] neg_hi:[0,0,1]
	v_pk_fma_f32 v[12:13], v[12:13], v[200:201], v[42:43] op_sel:[0,0,1] op_sel_hi:[1,0,0] neg_hi:[0,0,1]
	s_waitcnt lgkmcnt(6)
	v_pk_fma_f32 v[42:43], v[18:19], v[194:195], v[32:33] op_sel:[0,1,1] op_sel_hi:[1,1,0] neg_lo:[0,0,1]
	s_waitcnt lgkmcnt(5)
	v_pk_fma_f32 v[40:41], v[20:21], v[196:197], v[2:3] op_sel:[0,1,1] op_sel_hi:[1,1,0] neg_lo:[0,0,1]
	s_waitcnt lgkmcnt(4)
	v_pk_fma_f32 v[0:1], v[22:23], v[198:199], v[4:5] op_sel:[0,1,1] op_sel_hi:[1,1,0] neg_lo:[0,0,1]
	s_waitcnt lgkmcnt(3)
	v_pk_fma_f32 v[44:45], v[24:25], v[192:193], v[38:39] op_sel:[0,1,1] op_sel_hi:[1,1,0] neg_lo:[0,0,1]
	v_pk_fma_f32 v[18:19], v[18:19], v[194:195], v[42:43] op_sel:[0,0,1] op_sel_hi:[1,0,0] neg_hi:[0,0,1]
	v_pk_fma_f32 v[40:41], v[20:21], v[196:197], v[40:41] op_sel:[0,0,1] op_sel_hi:[1,0,0] neg_hi:[0,0,1]
	v_pk_fma_f32 v[0:1], v[22:23], v[198:199], v[0:1] op_sel:[0,0,1] op_sel_hi:[1,0,0] neg_hi:[0,0,1]
	v_pk_fma_f32 v[44:45], v[24:25], v[192:193], v[44:45] op_sel:[0,0,1] op_sel_hi:[1,0,0] neg_hi:[0,0,1]
	v_pk_fma_f32 v[14:15], v[14:15], s[100:101], v[16:17] op_sel_hi:[1,0,1] neg_lo:[0,0,1] neg_hi:[0,0,1]
	s_waitcnt lgkmcnt(2)
	v_pk_fma_f32 v[24:25], v[26:27], v[188:189], v[8:9] op_sel:[0,1,1] op_sel_hi:[1,1,0] neg_lo:[0,0,1]
	s_waitcnt lgkmcnt(1)
	v_pk_fma_f32 v[22:23], v[28:29], v[190:191], v[10:11] op_sel:[0,1,1] op_sel_hi:[1,1,0] neg_lo:[0,0,1]
	s_waitcnt lgkmcnt(0)
	v_pk_fma_f32 v[20:21], v[30:31], v[186:187], v[12:13] op_sel:[0,1,1] op_sel_hi:[1,1,0] neg_lo:[0,0,1]
	v_pk_fma_f32 v[32:33], v[32:33], s[100:101], v[18:19] op_sel_hi:[1,0,1] neg_lo:[0,0,1] neg_hi:[0,0,1]
	v_pk_fma_f32 v[24:25], v[26:27], v[188:189], v[24:25] op_sel:[0,0,1] op_sel_hi:[1,0,0] neg_hi:[0,0,1]
	v_pk_fma_f32 v[28:29], v[28:29], v[190:191], v[22:23] op_sel:[0,0,1] op_sel_hi:[1,0,0] neg_hi:[0,0,1]
	v_pk_fma_f32 v[30:31], v[30:31], v[186:187], v[20:21] op_sel:[0,0,1] op_sel_hi:[1,0,0] neg_hi:[0,0,1]
	v_pk_add_f32 v[20:21], v[16:17], v[18:19]
	v_pk_fma_f32 v[2:3], v[2:3], s[100:101], v[40:41] op_sel_hi:[1,0,1] neg_lo:[0,0,1] neg_hi:[0,0,1]
	v_pk_fma_f32 v[4:5], v[4:5], s[100:101], v[0:1] op_sel_hi:[1,0,1] neg_lo:[0,0,1] neg_hi:[0,0,1]
	v_pk_fma_f32 v[38:39], v[38:39], s[100:101], v[44:45] op_sel_hi:[1,0,1] neg_lo:[0,0,1] neg_hi:[0,0,1]
	v_pk_add_f32 v[16:17], v[16:17], v[18:19] neg_lo:[0,1] neg_hi:[0,1]
	v_pk_fma_f32 v[8:9], v[8:9], s[100:101], v[24:25] op_sel_hi:[1,0,1] neg_lo:[0,0,1] neg_hi:[0,0,1]
	v_pk_fma_f32 v[10:11], v[10:11], s[100:101], v[28:29] op_sel_hi:[1,0,1] neg_lo:[0,0,1] neg_hi:[0,0,1]
	v_pk_fma_f32 v[12:13], v[12:13], s[100:101], v[30:31] op_sel_hi:[1,0,1] neg_lo:[0,0,1] neg_hi:[0,0,1]
	v_pk_add_f32 v[18:19], v[14:15], v[32:33] op_sel:[0,1] op_sel_hi:[1,0] neg_lo:[0,1]
	v_pk_add_f32 v[22:23], v[40:41], v[24:25]
	v_pk_add_f32 v[26:27], v[0:1], v[28:29]
	v_pk_add_f32 v[42:43], v[44:45], v[30:31]
	v_pk_add_f32 v[14:15], v[14:15], v[32:33] op_sel:[0,1] op_sel_hi:[1,0] neg_hi:[0,1]
	v_pk_add_f32 v[40:41], v[40:41], v[24:25] neg_lo:[0,1] neg_hi:[0,1]
	v_pk_add_f32 v[0:1], v[0:1], v[28:29] neg_lo:[0,1] neg_hi:[0,1]
	v_pk_add_f32 v[30:31], v[44:45], v[30:31] neg_lo:[0,1] neg_hi:[0,1]
	v_pk_add_f32 v[44:45], v[2:3], v[8:9] op_sel:[0,1] op_sel_hi:[1,0] neg_lo:[0,1]
	v_pk_add_f32 v[28:29], v[4:5], v[10:11] op_sel:[0,1] op_sel_hi:[1,0] neg_lo:[0,1]
	v_pk_add_f32 v[24:25], v[38:39], v[12:13] op_sel:[0,1] op_sel_hi:[1,0] neg_lo:[0,1]
; __device__ __forceinline__ f32x2 cmul(f32x2 a, f32x2 b) { return (f32x2){a.x * b.x - a.y * b.y, a.x * b.y + a.y * b.x}; }
; template <bool INV> __device__ __forceinline__ void dft16(f32x2 (&x)[16]) {
; #pragma unroll
;     for (int b = 0; b < 4; ++b) r4<INV>(x[b], x[4 + b], x[8 + b], x[12 + b]);
;     const float sg = INV ? -1.f : 1.f;
;     const f32x2 W1 = {0.92387953251f, -0.38268343236f * sg}, W2 = {0.70710678118f, -0.70710678118f * sg}, W3 = {0.38268343236f, -0.92387953251f * sg},
;                 W4 = {0.f, -1.f * sg}, W6 = {-0.70710678118f, -0.70710678118f * sg}, W9 = {-0.92387953251f, 0.38268343236f * sg};
;     x[5] = cmul(x[5], W1); x[9] = cmul(x[9], W2); x[13] = cmul(x[13], W3);
;     x[6] = cmul(x[6], W2); x[10] = cmul(x[10], W4); x[14] = cmul(x[14], W6);
;     x[7] = cmul(x[7], W3); x[11] = cmul(x[11], W6); x[15] = cmul(x[15], W9);
; #pragma unroll
;     for (int c = 0; c < 4; ++c) r4<INV>(x[4 * c], x[4 * c + 1], x[4 * c + 2], x[4 * c + 3]);
; }
; template <bool INV> __device__ __forceinline__ void pass16_s4(LAS f32x2* X, const LAS f32x2* TH, const LAS f32x2* TL, int tid) {
;     ...
; #pragma unroll
;         for (int c = 0; c < 4; ++c)
; #pragma unroll
;             for (int d = 0; d < 4; ++d) P[4 * (c + 4 * d)] = x[4 * c + d];
;     }
; }
	v_pk_add_f32 v[8:9], v[2:3], v[8:9] op_sel:[0,1] op_sel_hi:[1,0] neg_hi:[0,1]
	v_pk_add_f32 v[4:5], v[4:5], v[10:11] op_sel:[0,1] op_sel_hi:[1,0] neg_hi:[0,1]
	v_pk_add_f32 v[38:39], v[38:39], v[12:13] op_sel:[0,1] op_sel_hi:[1,0] neg_hi:[0,1]
	v_pk_add_f32 v[12:13], v[20:21], v[26:27]
	v_pk_mul_f32 v[10:11], v[44:45], s[82:83] op_sel_hi:[1,0]
	v_pk_mul_f32 v[2:3], v[40:41], s[76:77] op_sel_hi:[1,0]
	v_pk_mul_f32 v[32:33], v[8:9], s[44:45] op_sel_hi:[1,0]
	v_pk_add_f32 v[26:27], v[20:21], v[26:27] neg_lo:[0,1] neg_hi:[0,1]
	v_pk_fma_f32 v[10:11], v[44:45], s[44:45], v[10:11] op_sel:[0,0,1] op_sel_hi:[1,0,0] neg_lo:[0,0,1]
	v_pk_fma_f32 v[40:41], v[40:41], s[76:77], v[2:3] op_sel:[0,0,1] op_sel_hi:[1,0,0] neg_lo:[0,0,1]
	v_pk_fma_f32 v[8:9], v[8:9], s[82:83], v[32:33] op_sel:[0,0,1] op_sel_hi:[1,0,0] neg_lo:[0,0,1]
	v_pk_add_f32 v[32:33], v[22:23], v[42:43]
	v_pk_fma_f32 v[2:3], v[28:29], s[76:77], v[18:19] op_sel:[0,0,1] op_sel_hi:[1,0,0] neg_hi:[0,0,1]
	v_pk_add_f32 v[44:45], v[16:17], v[0:1] op_sel:[0,1] op_sel_hi:[1,0] neg_lo:[0,1]
	v_pk_fma_f32 v[20:21], v[4:5], s[76:77], v[14:15] op_sel:[0,0,1] op_sel_hi:[1,0,0] neg_hi:[0,0,1]
	v_pk_add_f32 v[22:23], v[22:23], v[42:43] neg_lo:[0,1] neg_hi:[0,1]
	v_pk_fma_f32 v[28:29], v[28:29], s[76:77], v[2:3] op_sel:[0,0,1] op_sel_hi:[1,0,0] neg_lo:[0,0,1]
	v_pk_add_f32 v[16:17], v[16:17], v[0:1] op_sel:[0,1] op_sel_hi:[1,0] neg_hi:[0,1]
	v_pk_fma_f32 v[20:21], v[4:5], s[72:73], v[20:21] op_sel:[0,0,1] op_sel_hi:[1,0,0] neg_lo:[0,0,1]
	v_pk_add_f32 v[4:5], v[12:13], v[32:33]
	v_pk_fma_f32 v[18:19], v[18:19], s[100:101], v[28:29] op_sel_hi:[1,0,1] neg_lo:[0,0,1] neg_hi:[0,0,1]
	v_pk_fma_f32 v[0:1], v[30:31], s[76:77], v[40:41] op_sel:[0,0,1] op_sel_hi:[1,0,0] neg_hi:[0,0,1]
	v_pk_fma_f32 v[14:15], v[14:15], s[100:101], v[20:21] op_sel_hi:[1,0,1] neg_lo:[0,0,1] neg_hi:[0,0,1]
	v_pk_add_f32 v[32:33], v[12:13], v[32:33] neg_lo:[0,1] neg_hi:[0,1]
	v_pk_fma_f32 v[12:13], v[24:25], s[44:45], v[10:11] op_sel:[0,0,1] op_sel_hi:[1,0,0] neg_hi:[0,0,1]
	v_pk_fma_f32 v[0:1], v[30:31], s[72:73], v[0:1] op_sel:[0,0,1] op_sel_hi:[1,0,0] neg_lo:[0,0,1]
	v_pk_fma_f32 v[30:31], v[38:39], s[70:71], v[8:9] op_sel:[0,0,1] op_sel_hi:[1,0,0] neg_hi:[0,0,1]
	v_pk_add_f32 v[2:3], v[26:27], v[22:23] op_sel:[0,1] op_sel_hi:[1,0] neg_lo:[0,1]
	v_pk_fma_f32 v[24:25], v[24:25], s[82:83], v[12:13] op_sel:[0,0,1] op_sel_hi:[1,0,0] neg_lo:[0,0,1]
	v_pk_fma_f32 v[40:41], v[40:41], s[100:101], v[0:1] op_sel_hi:[1,0,1] neg_lo:[0,0,1] neg_hi:[0,0,1]
	v_pk_fma_f32 v[38:39], v[38:39], s[64:65], v[30:31] op_sel:[0,0,1] op_sel_hi:[1,0,0] neg_lo:[0,0,1]
	v_pk_add_f32 v[22:23], v[26:27], v[22:23] op_sel:[0,1] op_sel_hi:[1,0] neg_hi:[0,1]
	v_pk_fma_f32 v[10:11], v[10:11], s[100:101], v[24:25] op_sel_hi:[1,0,1] neg_lo:[0,0,1] neg_hi:[0,0,1]
	v_pk_add_f32 v[26:27], v[44:45], v[0:1]
	v_pk_fma_f32 v[8:9], v[8:9], s[100:101], v[38:39] op_sel_hi:[1,0,1] neg_lo:[0,0,1] neg_hi:[0,0,1]
	v_pk_add_f32 v[30:31], v[28:29], v[24:25]
	v_pk_add_f32 v[44:45], v[44:45], v[0:1] neg_lo:[0,1] neg_hi:[0,1]
	v_pk_add_f32 v[0:1], v[20:21], v[38:39]
	v_pk_add_f32 v[24:25], v[28:29], v[24:25] neg_lo:[0,1] neg_hi:[0,1]
	v_pk_add_f32 v[28:29], v[16:17], v[40:41] op_sel:[0,1] op_sel_hi:[1,0] neg_lo:[0,1]
	v_pk_add_f32 v[38:39], v[20:21], v[38:39] neg_lo:[0,1] neg_hi:[0,1]
	v_pk_add_f32 v[20:21], v[18:19], v[10:11] op_sel:[0,1] op_sel_hi:[1,0] neg_lo:[0,1]
	v_pk_add_f32 v[40:41], v[16:17], v[40:41] op_sel:[0,1] op_sel_hi:[1,0] neg_hi:[0,1]
	v_pk_add_f32 v[16:17], v[14:15], v[8:9] op_sel:[0,1] op_sel_hi:[1,0] neg_lo:[0,1]
	v_pk_add_f32 v[18:19], v[18:19], v[10:11] op_sel:[0,1] op_sel_hi:[1,0] neg_hi:[0,1]
	v_pk_add_f32 v[14:15], v[14:15], v[8:9] op_sel:[0,1] op_sel_hi:[1,0] neg_hi:[0,1]
	ds_write_b64 v151, v[4:5] offset:0
	ds_write_b64 v151, v[30:31] offset:32
	ds_write_b64 v151, v[26:27] offset:64
	ds_write_b64 v151, v[0:1] offset:96
	ds_write_b64 v151, v[2:3] offset:128
	ds_write_b64 v151, v[20:21] offset:160
	ds_write_b64 v151, v[28:29] offset:192
	ds_write_b64 v151, v[16:17] offset:224
	ds_write_b64 v151, v[32:33] offset:256
	ds_write_b64 v151, v[24:25] offset:288
	ds_write_b64 v151, v[44:45] offset:320
	ds_write_b64 v151, v[38:39] offset:352
	ds_write_b64 v151, v[22:23] offset:384
	ds_write_b64 v151, v[18:19] offset:416
	ds_write_b64 v151, v[40:41] offset:448
	ds_write_b64 v151, v[14:15] offset:480
	s_cbranch_scc1 .LBB0_852
	s_waitcnt lgkmcnt(0)
	s_barrier
	s_mov_b32 s0, 0
	s_mov_b64 s[12:13], -1
	ds_read2st64_b64 v[232:235], v139 offset0:1 offset1:2
	ds_read2st64_b64 v[208:211], v139 offset0:3 offset1:4
	ds_read2st64_b64 v[204:207], v139 offset0:5 offset1:6
	ds_read2st64_b64 v[200:203], v139 offset0:7 offset1:8
	ds_read2st64_b64 v[196:199], v139 offset0:9 offset1:10
	ds_read2st64_b64 v[192:195], v139 offset0:11 offset1:12
	ds_read2st64_b64 v[188:191], v139 offset0:13 offset1:14
	ds_read_b64 v[186:187], v139 offset:7680
; #define LAS __attribute__((address_space(3)))
; __device__ __forceinline__ f32x2 cmul(f32x2 a, f32x2 b) { return (f32x2){a.x * b.x - a.y * b.y, a.x * b.y + a.y * b.x}; }
; template <bool INV> __device__ __forceinline__ void dft16(f32x2 (&x)[16]) {
; #pragma unroll
;     for (int b = 0; b < 4; ++b) r4<INV>(x[b], x[4 + b], x[8 + b], x[12 + b]);
;     const float sg = INV ? -1.f : 1.f;
;     const f32x2 W1 = {0.92387953251f, -0.38268343236f * sg}, W2 = {0.70710678118f, -0.70710678118f * sg}, W3 = {0.38268343236f, -0.92387953251f * sg},
;                 W4 = {0.f, -1.f * sg}, W6 = {-0.70710678118f, -0.70710678118f * sg}, W9 = {-0.92387953251f, 0.38268343236f * sg};
;     x[5] = cmul(x[5], W1); x[9] = cmul(x[9], W2); x[13] = cmul(x[13], W3);
;     x[6] = cmul(x[6], W2); x[10] = cmul(x[10], W4); x[14] = cmul(x[14], W6);
;     x[7] = cmul(x[7], W3); x[11] = cmul(x[11], W6); x[15] = cmul(x[15], W9);
; #pragma unroll
;     for (int c = 0; c < 4; ++c) r4<INV>(x[4 * c], x[4 * c + 1], x[4 * c + 2], x[4 * c + 3]);
; }
; template <bool INV> __device__ __forceinline__ void bfly16_tab(f32x2 (&x)[16], const LAS f32x2* T, int tstride, int j) {
;     if (INV) {
; #pragma unroll
;         for (int q = 1; q < 16; ++q) { f32x2 p = T[q * tstride + j]; p.y = -p.y; x[q] = cmul(x[q], p); } }
;     dft16<INV>(x);
;     if (!INV) {
; #pragma unroll
;         for (int r = 1; r < 16; ++r) { const f32x2 p = T[r * tstride + j]; x[4 * (r & 3) + (r >> 2)] = cmul(x[4 * (r & 3) + (r >> 2)], p); } }
; }
; template <bool INV> __device__ __forceinline__ void pass16_s64(LAS f32x2* X, const LAS f32x2* TH, int base, int j) {
;     f32x2 x[16];
; #pragma unroll
;     for (int q = 0; q < 16; ++q) x[q] = X[base + q * 68];
;     bfly16_tab<INV>(x, TH - 2048, 64, j);
; #pragma unroll
;     for (int c = 0; c < 4; ++c)
; #pragma unroll
;         for (int d = 0; d < 4; ++d) X[base + (c + 4 * d) * 68] = x[4 * c + d];
; }
.LBB0_854:
	v_add_u32_e32 v128, s0, v140
	v_lshrrev_b32_e32 v147, 6, v128
	v_mad_u32_u24 v151, v147, s77, v142
	ds_read_b64 v[0:1], v151 offset:2176
	ds_read_b64 v[2:3], v151 offset:544
	ds_read_b64 v[4:5], v151 offset:1088
	ds_read_b64 v[6:7], v151 offset:1632
	ds_read_b64 v[8:9], v151 offset:2720
	ds_read_b64 v[10:11], v151 offset:3264
	ds_read_b64 v[12:13], v151 offset:3808
	ds_read_b64 v[14:15], v151 offset:0
	ds_read_b64 v[16:17], v151 offset:4352
	ds_read_b64 v[18:19], v151 offset:6528
	ds_read_b64 v[20:21], v151 offset:4896
	ds_read_b64 v[22:23], v151 offset:5440
	ds_read_b64 v[24:25], v151 offset:5984
	ds_read_b64 v[26:27], v151 offset:7072
	ds_read_b64 v[28:29], v151 offset:7616
	ds_read_b64 v[30:31], v151 offset:8160
	s_cmp_eq_u32 s0, 0
	s_movk_i32 s0, 0x200
	s_mov_b64 s[12:13], 0
	s_waitcnt lgkmcnt(15)
	v_pk_mul_f32 v[32:33], v[0:1], v[210:211] op_sel:[0,1] op_sel_hi:[1,1]
	s_waitcnt lgkmcnt(14)
	v_pk_mul_f32 v[34:35], v[2:3], v[232:233] op_sel:[0,1] op_sel_hi:[1,1]
	s_waitcnt lgkmcnt(13)
	v_pk_mul_f32 v[36:37], v[4:5], v[234:235] op_sel:[0,1] op_sel_hi:[1,1]
	s_waitcnt lgkmcnt(12)
	v_pk_mul_f32 v[38:39], v[6:7], v[208:209] op_sel:[0,1] op_sel_hi:[1,1]
	v_pk_fma_f32 v[0:1], v[0:1], v[210:211], v[32:33] op_sel:[0,0,1] op_sel_hi:[1,0,0] neg_hi:[0,0,1]
	s_waitcnt lgkmcnt(11)
	v_pk_mul_f32 v[32:33], v[8:9], v[204:205] op_sel:[0,1] op_sel_hi:[1,1]
	s_waitcnt lgkmcnt(10)
	v_pk_mul_f32 v[40:41], v[10:11], v[206:207] op_sel:[0,1] op_sel_hi:[1,1]
	s_waitcnt lgkmcnt(9)
	v_pk_mul_f32 v[42:43], v[12:13], v[200:201] op_sel:[0,1] op_sel_hi:[1,1]
	s_waitcnt lgkmcnt(7)
	v_pk_fma_f32 v[44:45], v[16:17], v[202:203], v[14:15] op_sel:[0,1,1] op_sel_hi:[1,1,0] neg_lo:[0,0,1]
	v_pk_fma_f32 v[2:3], v[2:3], v[232:233], v[34:35] op_sel:[0,0,1] op_sel_hi:[1,0,0] neg_hi:[0,0,1]
	v_pk_fma_f32 v[4:5], v[4:5], v[234:235], v[36:37] op_sel:[0,0,1] op_sel_hi:[1,0,0] neg_hi:[0,0,1]
	v_pk_fma_f32 v[38:39], v[6:7], v[208:209], v[38:39] op_sel:[0,0,1] op_sel_hi:[1,0,0] neg_hi:[0,0,1]
	v_pk_fma_f32 v[44:45], v[16:17], v[202:203], v[44:45] op_sel:[0,0,1] op_sel_hi:[1,0,0] neg_hi:[0,0,1]
	v_pk_fma_f32 v[32:33], v[8:9], v[204:205], v[32:33] op_sel:[0,0,1] op_sel_hi:[1,0,0] neg_hi:[0,0,1]
	v_pk_fma_f32 v[40:41], v[10:11], v[206:207], v[40:41] op_sel:[0,0,1] op_sel_hi:[1,0,0] neg_hi:[0,0,1]
	v_pk_fma_f32 v[12:13], v[12:13], v[200:201], v[42:43] op_sel:[0,0,1] op_sel_hi:[1,0,0] neg_hi:[0,0,1]
	s_waitcnt lgkmcnt(6)
	v_pk_fma_f32 v[42:43], v[18:19], v[194:195], v[0:1] op_sel:[0,1,1] op_sel_hi:[1,1,0] neg_lo:[0,0,1]
	s_waitcnt lgkmcnt(5)
	v_pk_fma_f32 v[10:11], v[20:21], v[196:197], v[2:3] op_sel:[0,1,1] op_sel_hi:[1,1,0] neg_lo:[0,0,1]
	s_waitcnt lgkmcnt(4)
	v_pk_fma_f32 v[8:9], v[22:23], v[198:199], v[4:5] op_sel:[0,1,1] op_sel_hi:[1,1,0] neg_lo:[0,0,1]
	s_waitcnt lgkmcnt(3)
	v_pk_fma_f32 v[16:17], v[24:25], v[192:193], v[38:39] op_sel:[0,1,1] op_sel_hi:[1,1,0] neg_lo:[0,0,1]
	v_pk_fma_f32 v[18:19], v[18:19], v[194:195], v[42:43] op_sel:[0,0,1] op_sel_hi:[1,0,0] neg_hi:[0,0,1]
	v_pk_fma_f32 v[20:21], v[20:21], v[196:197], v[10:11] op_sel:[0,0,1] op_sel_hi:[1,0,0] neg_hi:[0,0,1]
	v_pk_fma_f32 v[22:23], v[22:23], v[198:199], v[8:9] op_sel:[0,0,1] op_sel_hi:[1,0,0] neg_hi:[0,0,1]
	v_pk_fma_f32 v[24:25], v[24:25], v[192:193], v[16:17] op_sel:[0,0,1] op_sel_hi:[1,0,0] neg_hi:[0,0,1]
	v_pk_fma_f32 v[14:15], v[14:15], s[100:101], v[44:45] op_sel_hi:[1,0,1] neg_lo:[0,0,1] neg_hi:[0,0,1]
	s_waitcnt lgkmcnt(2)
	v_pk_fma_f32 v[16:17], v[26:27], v[188:189], v[32:33] op_sel:[0,1,1] op_sel_hi:[1,1,0] neg_lo:[0,0,1]
	s_waitcnt lgkmcnt(1)
	v_pk_fma_f32 v[8:9], v[28:29], v[190:191], v[40:41] op_sel:[0,1,1] op_sel_hi:[1,1,0] neg_lo:[0,0,1]
	s_waitcnt lgkmcnt(0)
	v_pk_fma_f32 v[10:11], v[30:31], v[186:187], v[12:13] op_sel:[0,1,1] op_sel_hi:[1,1,0] neg_lo:[0,0,1]
	v_pk_fma_f32 v[0:1], v[0:1], s[100:101], v[18:19] op_sel_hi:[1,0,1] neg_lo:[0,0,1] neg_hi:[0,0,1]
	v_pk_fma_f32 v[16:17], v[26:27], v[188:189], v[16:17] op_sel:[0,0,1] op_sel_hi:[1,0,0] neg_hi:[0,0,1]
	v_pk_fma_f32 v[28:29], v[28:29], v[190:191], v[8:9] op_sel:[0,0,1] op_sel_hi:[1,0,0] neg_hi:[0,0,1]
	v_pk_fma_f32 v[10:11], v[30:31], v[186:187], v[10:11] op_sel:[0,0,1] op_sel_hi:[1,0,0] neg_hi:[0,0,1]
	v_pk_add_f32 v[30:31], v[44:45], v[18:19]
	v_pk_fma_f32 v[2:3], v[2:3], s[100:101], v[20:21] op_sel_hi:[1,0,1] neg_lo:[0,0,1] neg_hi:[0,0,1]
	v_pk_fma_f32 v[4:5], v[4:5], s[100:101], v[22:23] op_sel_hi:[1,0,1] neg_lo:[0,0,1] neg_hi:[0,0,1]
	v_pk_fma_f32 v[38:39], v[38:39], s[100:101], v[24:25] op_sel_hi:[1,0,1] neg_lo:[0,0,1] neg_hi:[0,0,1]
	v_pk_add_f32 v[18:19], v[44:45], v[18:19] neg_lo:[0,1] neg_hi:[0,1]
	v_pk_fma_f32 v[32:33], v[32:33], s[100:101], v[16:17] op_sel_hi:[1,0,1] neg_lo:[0,0,1] neg_hi:[0,0,1]
	v_pk_fma_f32 v[40:41], v[40:41], s[100:101], v[28:29] op_sel_hi:[1,0,1] neg_lo:[0,0,1] neg_hi:[0,0,1]
	v_pk_fma_f32 v[12:13], v[12:13], s[100:101], v[10:11] op_sel_hi:[1,0,1] neg_lo:[0,0,1] neg_hi:[0,0,1]
	v_pk_add_f32 v[44:45], v[14:15], v[0:1] op_sel:[0,1] op_sel_hi:[1,0] neg_lo:[0,1]
	v_pk_add_f32 v[8:9], v[20:21], v[16:17]
	v_pk_add_f32 v[26:27], v[22:23], v[28:29]
	v_pk_add_f32 v[42:43], v[24:25], v[10:11]
	v_pk_add_f32 v[0:1], v[14:15], v[0:1] op_sel:[0,1] op_sel_hi:[1,0] neg_hi:[0,1]
	v_pk_add_f32 v[16:17], v[20:21], v[16:17] neg_lo:[0,1] neg_hi:[0,1]
	v_pk_add_f32 v[28:29], v[22:23], v[28:29] neg_lo:[0,1] neg_hi:[0,1]
	v_pk_add_f32 v[24:25], v[24:25], v[10:11] neg_lo:[0,1] neg_hi:[0,1]
	v_pk_add_f32 v[10:11], v[2:3], v[32:33] op_sel:[0,1] op_sel_hi:[1,0] neg_lo:[0,1]
	v_pk_add_f32 v[22:23], v[4:5], v[40:41] op_sel:[0,1] op_sel_hi:[1,0] neg_lo:[0,1]
	v_pk_add_f32 v[20:21], v[38:39], v[12:13] op_sel:[0,1] op_sel_hi:[1,0] neg_lo:[0,1]
; #define LAS __attribute__((address_space(3)))
; __device__ __forceinline__ f32x2 cmul(f32x2 a, f32x2 b) { return (f32x2){a.x * b.x - a.y * b.y, a.x * b.y + a.y * b.x}; }
; template <bool INV> __device__ __forceinline__ void dft16(f32x2 (&x)[16]) {
; #pragma unroll
;     for (int b = 0; b < 4; ++b) r4<INV>(x[b], x[4 + b], x[8 + b], x[12 + b]);
;     const float sg = INV ? -1.f : 1.f;
;     const f32x2 W1 = {0.92387953251f, -0.38268343236f * sg}, W2 = {0.70710678118f, -0.70710678118f * sg}, W3 = {0.38268343236f, -0.92387953251f * sg},
;                 W4 = {0.f, -1.f * sg}, W6 = {-0.70710678118f, -0.70710678118f * sg}, W9 = {-0.92387953251f, 0.38268343236f * sg};
;     x[5] = cmul(x[5], W1); x[9] = cmul(x[9], W2); x[13] = cmul(x[13], W3);
;     x[6] = cmul(x[6], W2); x[10] = cmul(x[10], W4); x[14] = cmul(x[14], W6);
;     x[7] = cmul(x[7], W3); x[11] = cmul(x[11], W6); x[15] = cmul(x[15], W9);
; #pragma unroll
;     for (int c = 0; c < 4; ++c) r4<INV>(x[4 * c], x[4 * c + 1], x[4 * c + 2], x[4 * c + 3]);
; }
; template <bool INV> __device__ __forceinline__ void pass16_s64(LAS f32x2* X, const LAS f32x2* TH, int base, int j) {
;     f32x2 x[16];
; #pragma unroll
;     for (int q = 0; q < 16; ++q) x[q] = X[base + q * 68];
;     bfly16_tab<INV>(x, TH - 2048, 64, j);
; #pragma unroll
;     for (int c = 0; c < 4; ++c)
; #pragma unroll
;         for (int d = 0; d < 4; ++d) X[base + (c + 4 * d) * 68] = x[4 * c + d];
; }
	v_pk_add_f32 v[32:33], v[2:3], v[32:33] op_sel:[0,1] op_sel_hi:[1,0] neg_hi:[0,1]
	v_pk_add_f32 v[4:5], v[4:5], v[40:41] op_sel:[0,1] op_sel_hi:[1,0] neg_hi:[0,1]
	v_pk_add_f32 v[38:39], v[38:39], v[12:13] op_sel:[0,1] op_sel_hi:[1,0] neg_hi:[0,1]
	v_pk_add_f32 v[12:13], v[30:31], v[26:27]
	v_pk_mul_f32 v[40:41], v[10:11], s[82:83] op_sel_hi:[1,0]
	v_pk_mul_f32 v[2:3], v[16:17], s[76:77] op_sel_hi:[1,0]
	v_pk_mul_f32 v[14:15], v[32:33], s[44:45] op_sel_hi:[1,0]
	v_pk_add_f32 v[30:31], v[30:31], v[26:27] neg_lo:[0,1] neg_hi:[0,1]
	v_pk_fma_f32 v[40:41], v[10:11], s[44:45], v[40:41] op_sel:[0,0,1] op_sel_hi:[1,0,0] neg_lo:[0,0,1]
	v_pk_fma_f32 v[2:3], v[16:17], s[76:77], v[2:3] op_sel:[0,0,1] op_sel_hi:[1,0,0] neg_lo:[0,0,1]
	v_pk_fma_f32 v[32:33], v[32:33], s[82:83], v[14:15] op_sel:[0,0,1] op_sel_hi:[1,0,0] neg_lo:[0,0,1]
	v_pk_add_f32 v[14:15], v[8:9], v[42:43]
	v_pk_fma_f32 v[16:17], v[22:23], s[76:77], v[44:45] op_sel:[0,0,1] op_sel_hi:[1,0,0] neg_hi:[0,0,1]
	v_pk_add_f32 v[10:11], v[18:19], v[28:29] op_sel:[0,1] op_sel_hi:[1,0] neg_lo:[0,1]
	v_pk_fma_f32 v[26:27], v[4:5], s[76:77], v[0:1] op_sel:[0,0,1] op_sel_hi:[1,0,0] neg_hi:[0,0,1]
	v_pk_add_f32 v[8:9], v[8:9], v[42:43] neg_lo:[0,1] neg_hi:[0,1]
	v_pk_fma_f32 v[22:23], v[22:23], s[76:77], v[16:17] op_sel:[0,0,1] op_sel_hi:[1,0,0] neg_lo:[0,0,1]
	v_pk_add_f32 v[18:19], v[18:19], v[28:29] op_sel:[0,1] op_sel_hi:[1,0] neg_hi:[0,1]
	v_pk_fma_f32 v[4:5], v[4:5], s[72:73], v[26:27] op_sel:[0,0,1] op_sel_hi:[1,0,0] neg_lo:[0,0,1]
	v_pk_add_f32 v[26:27], v[12:13], v[14:15]
	v_pk_fma_f32 v[44:45], v[44:45], s[100:101], v[22:23] op_sel_hi:[1,0,1] neg_lo:[0,0,1] neg_hi:[0,0,1]
	v_pk_fma_f32 v[28:29], v[24:25], s[76:77], v[2:3] op_sel:[0,0,1] op_sel_hi:[1,0,0] neg_hi:[0,0,1]
	v_pk_fma_f32 v[0:1], v[0:1], s[100:101], v[4:5] op_sel_hi:[1,0,1] neg_lo:[0,0,1] neg_hi:[0,0,1]
	v_pk_add_f32 v[14:15], v[12:13], v[14:15] neg_lo:[0,1] neg_hi:[0,1]
	v_pk_fma_f32 v[12:13], v[20:21], s[44:45], v[40:41] op_sel:[0,0,1] op_sel_hi:[1,0,0] neg_hi:[0,0,1]
	v_pk_fma_f32 v[28:29], v[24:25], s[72:73], v[28:29] op_sel:[0,0,1] op_sel_hi:[1,0,0] neg_lo:[0,0,1]
	v_pk_fma_f32 v[24:25], v[38:39], s[70:71], v[32:33] op_sel:[0,0,1] op_sel_hi:[1,0,0] neg_hi:[0,0,1]
	v_pk_add_f32 v[16:17], v[30:31], v[8:9] op_sel:[0,1] op_sel_hi:[1,0] neg_lo:[0,1]
	v_pk_fma_f32 v[20:21], v[20:21], s[82:83], v[12:13] op_sel:[0,0,1] op_sel_hi:[1,0,0] neg_lo:[0,0,1]
	v_pk_fma_f32 v[2:3], v[2:3], s[100:101], v[28:29] op_sel_hi:[1,0,1] neg_lo:[0,0,1] neg_hi:[0,0,1]
	v_pk_fma_f32 v[38:39], v[38:39], s[64:65], v[24:25] op_sel:[0,0,1] op_sel_hi:[1,0,0] neg_lo:[0,0,1]
	v_pk_add_f32 v[8:9], v[30:31], v[8:9] op_sel:[0,1] op_sel_hi:[1,0] neg_hi:[0,1]
	v_pk_fma_f32 v[40:41], v[40:41], s[100:101], v[20:21] op_sel_hi:[1,0,1] neg_lo:[0,0,1] neg_hi:[0,0,1]
	v_pk_add_f32 v[30:31], v[10:11], v[28:29]
	v_pk_fma_f32 v[32:33], v[32:33], s[100:101], v[38:39] op_sel_hi:[1,0,1] neg_lo:[0,0,1] neg_hi:[0,0,1]
	v_pk_add_f32 v[24:25], v[22:23], v[20:21]
	v_pk_add_f32 v[28:29], v[10:11], v[28:29] neg_lo:[0,1] neg_hi:[0,1]
	v_pk_add_f32 v[10:11], v[4:5], v[38:39]
	v_pk_add_f32 v[20:21], v[22:23], v[20:21] neg_lo:[0,1] neg_hi:[0,1]
	v_pk_add_f32 v[22:23], v[18:19], v[2:3] op_sel:[0,1] op_sel_hi:[1,0] neg_lo:[0,1]
	v_pk_add_f32 v[38:39], v[4:5], v[38:39] neg_lo:[0,1] neg_hi:[0,1]
	v_pk_add_f32 v[4:5], v[44:45], v[40:41] op_sel:[0,1] op_sel_hi:[1,0] neg_lo:[0,1]
	v_pk_add_f32 v[2:3], v[18:19], v[2:3] op_sel:[0,1] op_sel_hi:[1,0] neg_hi:[0,1]
	v_pk_add_f32 v[18:19], v[0:1], v[32:33] op_sel:[0,1] op_sel_hi:[1,0] neg_lo:[0,1]
	v_pk_add_f32 v[44:45], v[44:45], v[40:41] op_sel:[0,1] op_sel_hi:[1,0] neg_hi:[0,1]
	v_pk_add_f32 v[0:1], v[0:1], v[32:33] op_sel:[0,1] op_sel_hi:[1,0] neg_hi:[0,1]
	ds_write_b64 v151, v[26:27] offset:0
	ds_write_b64 v151, v[24:25] offset:544
	ds_write_b64 v151, v[30:31] offset:1088
	ds_write_b64 v151, v[10:11] offset:1632
	ds_write_b64 v151, v[16:17] offset:2176
	ds_write_b64 v151, v[4:5] offset:2720
	ds_write_b64 v151, v[22:23] offset:3264
	ds_write_b64 v151, v[18:19] offset:3808
	ds_write_b64 v151, v[14:15] offset:4352
	ds_write_b64 v151, v[20:21] offset:4896
	ds_write_b64 v151, v[28:29] offset:5440
	ds_write_b64 v151, v[38:39] offset:5984
	ds_write_b64 v151, v[8:9] offset:6528
	ds_write_b64 v151, v[44:45] offset:7072
	ds_write_b64 v151, v[2:3] offset:7616
	ds_write_b64 v151, v[0:1] offset:8160
	s_cbranch_scc1 .LBB0_854
	s_waitcnt lgkmcnt(0)
	s_barrier
	s_mov_b32 s0, 0
	s_mov_b64 s[12:13], -1
; #define LAS __attribute__((address_space(3)))
; __device__ __forceinline__ f32x2 cmul(f32x2 a, f32x2 b) { return (f32x2){a.x * b.x - a.y * b.y, a.x * b.y + a.y * b.x}; }
; __device__ __forceinline__ f32x2 tw32k(const LAS f32x2* TH, const LAS f32x2* TL, int n) { return cmul(TH[n >> 7], TL[n & 127]); }
; template <bool INV> __device__ __forceinline__ void dft16(f32x2 (&x)[16]) {
; #pragma unroll
;     for (int b = 0; b < 4; ++b) r4<INV>(x[b], x[4 + b], x[8 + b], x[12 + b]);
;     const float sg = INV ? -1.f : 1.f;
;     const f32x2 W1 = {0.92387953251f, -0.38268343236f * sg}, W2 = {0.70710678118f, -0.70710678118f * sg}, W3 = {0.38268343236f, -0.92387953251f * sg},
;                 W4 = {0.f, -1.f * sg}, W6 = {-0.70710678118f, -0.70710678118f * sg}, W9 = {-0.92387953251f, 0.38268343236f * sg};
;     x[5] = cmul(x[5], W1); x[9] = cmul(x[9], W2); x[13] = cmul(x[13], W3);
;     x[6] = cmul(x[6], W2); x[10] = cmul(x[10], W4); x[14] = cmul(x[14], W6);
;     x[7] = cmul(x[7], W3); x[11] = cmul(x[11], W6); x[15] = cmul(x[15], W9);
; #pragma unroll
;     for (int c = 0; c < 4; ++c) r4<INV>(x[4 * c], x[4 * c + 1], x[4 * c + 2], x[4 * c + 3]);
; }
; template <bool INV> __device__ __forceinline__ void bfly16(f32x2 (&x)[16], const LAS f32x2* TH, const LAS f32x2* TL, int tw) {
;     f32x2 W = tw32k(TH, TL, tw); if (INV) W.y = -W.y;
;     if (INV) { f32x2 p = W;
; #pragma unroll
;         for (int q = 1; q < 16; ++q) { x[q] = cmul(x[q], p); if (q < 15) p = cmul(p, W); } }
;     dft16<INV>(x);
;     if (!INV) { f32x2 p = W;
; #pragma unroll
;         for (int r = 1; r < 16; ++r) { x[4 * (r & 3) + (r >> 2)] = cmul(x[4 * (r & 3) + (r >> 2)], p); if (r < 15) p = cmul(p, W); } }
; }
; template <bool INV> __device__ __forceinline__ void pass16(LAS f32x2* X, const LAS f32x2* TH, const LAS f32x2* TL, int base, int stride, int tw) {
;     f32x2 x[16];
; #pragma unroll
;     for (int q = 0; q < 16; ++q) x[q] = X[base + q * stride];
;     bfly16<INV>(x, TH, TL, tw);
; #pragma unroll
;     for (int c = 0; c < 4; ++c)
; #pragma unroll
;         for (int d = 0; d < 4; ++d) X[base + (c + 4 * d) * stride] = x[4 * c + d];
; }
.LBB0_856:
	v_add_u32_e32 v128, s0, v140
	v_lshrrev_b32_e32 v147, 6, v128
	v_and_b32_e32 v157, 63, v128
	v_lshlrev_b32_e32 v151, 5, v147
	v_lshlrev_b32_e32 v155, 3, v147
	v_lshlrev_b32_e32 v157, 4, v157
	v_lshl_add_u32 v151, v128, 3, v151
	v_add_u32_e32 v155, 0x26000, v155
	v_add_u32_e32 v157, 0x26400, v157
	v_add_u32_e32 v176, 0x11000, v151
	ds_read_b64 v[0:1], v155
	ds_read_b64 v[2:3], v157
	ds_read_b64 v[4:5], v151 offset:34816
	ds_read_b64 v[6:7], v151 offset:8704
	ds_read_b64 v[8:9], v151 offset:17408
	ds_read_b64 v[10:11], v151 offset:26112
	ds_read_b64 v[12:13], v151 offset:43520
	ds_read_b64 v[14:15], v151 offset:52224
	ds_read_b64 v[16:17], v151 offset:60928
	ds_read_b64 v[18:19], v151 offset:0
	ds_read_b64 v[20:21], v176 offset:0
	ds_read_b64 v[22:23], v176 offset:34816
	ds_read_b64 v[24:25], v176 offset:8704
	ds_read_b64 v[26:27], v176 offset:17408
	ds_read_b64 v[28:29], v176 offset:26112
	ds_read_b64 v[30:31], v176 offset:43520
	ds_read_b64 v[32:33], v176 offset:52224
	ds_read_b64 v[34:35], v176 offset:60928
	s_cmp_eq_u32 s0, 0
	s_movk_i32 s0, 0x200
	s_mov_b64 s[12:13], 0
	s_waitcnt lgkmcnt(15)
	v_pk_mul_f32 v[36:37], v[0:1], v[2:3] op_sel:[0,1] op_sel_hi:[1,1]
	s_nop 0
	v_pk_fma_f32 v[2:3], v[0:1], v[2:3], v[36:37] op_sel:[0,0,1] op_sel_hi:[1,0,0] neg_lo:[0,0,1]
	s_nop 0
	v_pk_mul_f32 v[0:1], v[2:3], v[2:3] op_sel:[0,1] op_sel_hi:[1,1]
	s_nop 0
	v_pk_fma_f32 v[0:1], v[2:3], v[2:3], v[0:1] op_sel:[0,0,1] op_sel_hi:[1,0,0] neg_lo:[0,0,1]
	s_nop 0
	v_pk_mul_f32 v[36:37], v[0:1], v[2:3] op_sel:[0,1] op_sel_hi:[1,1]
	v_pk_mul_f32 v[38:39], v[0:1], v[0:1] op_sel:[0,1] op_sel_hi:[1,1]
	v_pk_fma_f32 v[36:37], v[0:1], v[2:3], v[36:37] op_sel:[0,0,1] op_sel_hi:[1,0,0] neg_lo:[0,0,1]
	v_pk_fma_f32 v[38:39], v[0:1], v[0:1], v[38:39] op_sel:[0,0,1] op_sel_hi:[1,0,0] neg_lo:[0,0,1]
	s_nop 0
	v_pk_mul_f32 v[40:41], v[38:39], v[2:3] op_sel:[0,1] op_sel_hi:[1,1]
	v_pk_mul_f32 v[42:43], v[38:39], v[0:1] op_sel:[0,1] op_sel_hi:[1,1]
	v_pk_mul_f32 v[44:45], v[38:39], v[36:37] op_sel:[0,1] op_sel_hi:[1,1]
	v_pk_fma_f32 v[40:41], v[38:39], v[2:3], v[40:41] op_sel:[0,0,1] op_sel_hi:[1,0,0] neg_lo:[0,0,1]
	v_pk_fma_f32 v[42:43], v[38:39], v[0:1], v[42:43] op_sel:[0,0,1] op_sel_hi:[1,0,0] neg_lo:[0,0,1]
	v_pk_fma_f32 v[44:45], v[38:39], v[36:37], v[44:45] op_sel:[0,0,1] op_sel_hi:[1,0,0] neg_lo:[0,0,1]
	v_pk_mul_f32 v[46:47], v[38:39], v[38:39] op_sel:[0,1] op_sel_hi:[1,1]
	s_nop 0
	v_pk_fma_f32 v[46:47], v[38:39], v[38:39], v[46:47] op_sel:[0,0,1] op_sel_hi:[1,0,0] neg_lo:[0,0,1]
	s_nop 0
	v_pk_mul_f32 v[48:49], v[46:47], v[2:3] op_sel:[0,1] op_sel_hi:[1,1]
	v_pk_mul_f32 v[50:51], v[46:47], v[0:1] op_sel:[0,1] op_sel_hi:[1,1]
	v_pk_mul_f32 v[52:53], v[46:47], v[36:37] op_sel:[0,1] op_sel_hi:[1,1]
	v_pk_fma_f32 v[48:49], v[46:47], v[2:3], v[48:49] op_sel:[0,0,1] op_sel_hi:[1,0,0] neg_lo:[0,0,1]
	v_pk_fma_f32 v[50:51], v[46:47], v[0:1], v[50:51] op_sel:[0,0,1] op_sel_hi:[1,0,0] neg_lo:[0,0,1]
	v_pk_fma_f32 v[52:53], v[46:47], v[36:37], v[52:53] op_sel:[0,0,1] op_sel_hi:[1,0,0] neg_lo:[0,0,1]
	v_pk_mul_f32 v[54:55], v[46:47], v[38:39] op_sel:[0,1] op_sel_hi:[1,1]
	v_pk_mul_f32 v[56:57], v[46:47], v[40:41] op_sel:[0,1] op_sel_hi:[1,1]
	v_pk_mul_f32 v[58:59], v[46:47], v[42:43] op_sel:[0,1] op_sel_hi:[1,1]
	v_pk_fma_f32 v[54:55], v[46:47], v[38:39], v[54:55] op_sel:[0,0,1] op_sel_hi:[1,0,0] neg_lo:[0,0,1]
	v_pk_fma_f32 v[56:57], v[46:47], v[40:41], v[56:57] op_sel:[0,0,1] op_sel_hi:[1,0,0] neg_lo:[0,0,1]
	v_pk_fma_f32 v[58:59], v[46:47], v[42:43], v[58:59] op_sel:[0,0,1] op_sel_hi:[1,0,0] neg_lo:[0,0,1]
	v_pk_mul_f32 v[60:61], v[46:47], v[44:45] op_sel:[0,1] op_sel_hi:[1,1]
	s_nop 0
	v_pk_fma_f32 v[60:61], v[46:47], v[44:45], v[60:61] op_sel:[0,0,1] op_sel_hi:[1,0,0] neg_lo:[0,0,1]
	v_pk_mul_f32 v[62:63], v[4:5], v[38:39] op_sel:[0,1] op_sel_hi:[1,1]
	s_waitcnt lgkmcnt(14)
	v_pk_mul_f32 v[64:65], v[6:7], v[2:3] op_sel:[0,1] op_sel_hi:[1,1]
	s_waitcnt lgkmcnt(13)
	v_pk_mul_f32 v[66:67], v[8:9], v[0:1] op_sel:[0,1] op_sel_hi:[1,1]
	s_waitcnt lgkmcnt(12)
	v_pk_mul_f32 v[68:69], v[10:11], v[36:37] op_sel:[0,1] op_sel_hi:[1,1]
	v_pk_fma_f32 v[38:39], v[4:5], v[38:39], v[62:63] op_sel:[0,0,1] op_sel_hi:[1,0,0] neg_hi:[0,0,1]
	s_waitcnt lgkmcnt(11)
	v_pk_mul_f32 v[62:63], v[12:13], v[40:41] op_sel:[0,1] op_sel_hi:[1,1]
	s_waitcnt lgkmcnt(10)
	v_pk_mul_f32 v[4:5], v[14:15], v[42:43] op_sel:[0,1] op_sel_hi:[1,1]
	s_waitcnt lgkmcnt(9)
	v_pk_mul_f32 v[70:71], v[16:17], v[44:45] op_sel:[0,1] op_sel_hi:[1,1]
	s_waitcnt lgkmcnt(7)
	v_pk_fma_f32 v[72:73], v[20:21], v[46:47], v[18:19] op_sel:[0,1,1] op_sel_hi:[1,1,0] neg_lo:[0,0,1]
	v_pk_fma_f32 v[2:3], v[6:7], v[2:3], v[64:65] op_sel:[0,0,1] op_sel_hi:[1,0,0] neg_hi:[0,0,1]
	v_pk_fma_f32 v[8:9], v[8:9], v[0:1], v[66:67] op_sel:[0,0,1] op_sel_hi:[1,0,0] neg_hi:[0,0,1]
	v_pk_fma_f32 v[68:69], v[10:11], v[36:37], v[68:69] op_sel:[0,0,1] op_sel_hi:[1,0,0] neg_hi:[0,0,1]
	v_pk_fma_f32 v[72:73], v[20:21], v[46:47], v[72:73] op_sel:[0,0,1] op_sel_hi:[1,0,0] neg_hi:[0,0,1]
	v_pk_fma_f32 v[12:13], v[12:13], v[40:41], v[62:63] op_sel:[0,0,1] op_sel_hi:[1,0,0] neg_hi:[0,0,1]
	v_pk_fma_f32 v[4:5], v[14:15], v[42:43], v[4:5] op_sel:[0,0,1] op_sel_hi:[1,0,0] neg_hi:[0,0,1]
	v_pk_fma_f32 v[70:71], v[16:17], v[44:45], v[70:71] op_sel:[0,0,1] op_sel_hi:[1,0,0] neg_hi:[0,0,1]
	s_waitcnt lgkmcnt(6)
	v_pk_fma_f32 v[16:17], v[22:23], v[54:55], v[38:39] op_sel:[0,1,1] op_sel_hi:[1,1,0] neg_lo:[0,0,1]
	s_waitcnt lgkmcnt(5)
	v_pk_fma_f32 v[44:45], v[24:25], v[48:49], v[2:3] op_sel:[0,1,1] op_sel_hi:[1,1,0] neg_lo:[0,0,1]
	s_waitcnt lgkmcnt(4)
	v_pk_fma_f32 v[14:15], v[26:27], v[50:51], v[8:9] op_sel:[0,1,1] op_sel_hi:[1,1,0] neg_lo:[0,0,1]
	s_waitcnt lgkmcnt(3)
; #define LAS __attribute__((address_space(3)))
; __device__ __forceinline__ f32x2 cmul(f32x2 a, f32x2 b) { return (f32x2){a.x * b.x - a.y * b.y, a.x * b.y + a.y * b.x}; }
; __device__ __forceinline__ f32x2 tw32k(const LAS f32x2* TH, const LAS f32x2* TL, int n) { return cmul(TH[n >> 7], TL[n & 127]); }
; template <bool INV> __device__ __forceinline__ void dft16(f32x2 (&x)[16]) {
; #pragma unroll
;     for (int b = 0; b < 4; ++b) r4<INV>(x[b], x[4 + b], x[8 + b], x[12 + b]);
;     const float sg = INV ? -1.f : 1.f;
;     const f32x2 W1 = {0.92387953251f, -0.38268343236f * sg}, W2 = {0.70710678118f, -0.70710678118f * sg}, W3 = {0.38268343236f, -0.92387953251f * sg},
;                 W4 = {0.f, -1.f * sg}, W6 = {-0.70710678118f, -0.70710678118f * sg}, W9 = {-0.92387953251f, 0.38268343236f * sg};
;     x[5] = cmul(x[5], W1); x[9] = cmul(x[9], W2); x[13] = cmul(x[13], W3);
;     x[6] = cmul(x[6], W2); x[10] = cmul(x[10], W4); x[14] = cmul(x[14], W6);
;     x[7] = cmul(x[7], W3); x[11] = cmul(x[11], W6); x[15] = cmul(x[15], W9);
; #pragma unroll
;     for (int c = 0; c < 4; ++c) r4<INV>(x[4 * c], x[4 * c + 1], x[4 * c + 2], x[4 * c + 3]);
; }
; template <bool INV> __device__ __forceinline__ void bfly16(f32x2 (&x)[16], const LAS f32x2* TH, const LAS f32x2* TL, int tw) {
;     f32x2 W = tw32k(TH, TL, tw); if (INV) W.y = -W.y;
;     if (INV) { f32x2 p = W;
; #pragma unroll
;         for (int q = 1; q < 16; ++q) { x[q] = cmul(x[q], p); if (q < 15) p = cmul(p, W); } }
;     dft16<INV>(x);
;     if (!INV) { f32x2 p = W;
; #pragma unroll
;         for (int r = 1; r < 16; ++r) { x[4 * (r & 3) + (r >> 2)] = cmul(x[4 * (r & 3) + (r >> 2)], p); if (r < 15) p = cmul(p, W); } }
; }
	v_pk_fma_f32 v[42:43], v[28:29], v[52:53], v[68:69] op_sel:[0,1,1] op_sel_hi:[1,1,0] neg_lo:[0,0,1]
	v_pk_fma_f32 v[22:23], v[22:23], v[54:55], v[16:17] op_sel:[0,0,1] op_sel_hi:[1,0,0] neg_hi:[0,0,1]
	v_pk_fma_f32 v[48:49], v[24:25], v[48:49], v[44:45] op_sel:[0,0,1] op_sel_hi:[1,0,0] neg_hi:[0,0,1]
	v_pk_fma_f32 v[26:27], v[26:27], v[50:51], v[14:15] op_sel:[0,0,1] op_sel_hi:[1,0,0] neg_hi:[0,0,1]
	v_pk_fma_f32 v[42:43], v[28:29], v[52:53], v[42:43] op_sel:[0,0,1] op_sel_hi:[1,0,0] neg_hi:[0,0,1]
	v_pk_fma_f32 v[18:19], v[18:19], s[100:101], v[72:73] op_sel_hi:[1,0,1] neg_lo:[0,0,1] neg_hi:[0,0,1]
	s_waitcnt lgkmcnt(2)
	v_pk_fma_f32 v[28:29], v[30:31], v[56:57], v[12:13] op_sel:[0,1,1] op_sel_hi:[1,1,0] neg_lo:[0,0,1]
	s_waitcnt lgkmcnt(1)
	v_pk_fma_f32 v[52:53], v[32:33], v[58:59], v[4:5] op_sel:[0,1,1] op_sel_hi:[1,1,0] neg_lo:[0,0,1]
	s_waitcnt lgkmcnt(0)
	v_pk_fma_f32 v[14:15], v[34:35], v[60:61], v[70:71] op_sel:[0,1,1] op_sel_hi:[1,1,0] neg_lo:[0,0,1]
	v_pk_fma_f32 v[38:39], v[38:39], s[100:101], v[22:23] op_sel_hi:[1,0,1] neg_lo:[0,0,1] neg_hi:[0,0,1]
	v_pk_fma_f32 v[30:31], v[30:31], v[56:57], v[28:29] op_sel:[0,0,1] op_sel_hi:[1,0,0] neg_hi:[0,0,1]
	v_pk_fma_f32 v[58:59], v[32:33], v[58:59], v[52:53] op_sel:[0,0,1] op_sel_hi:[1,0,0] neg_hi:[0,0,1]
	v_pk_fma_f32 v[14:15], v[34:35], v[60:61], v[14:15] op_sel:[0,0,1] op_sel_hi:[1,0,0] neg_hi:[0,0,1]
	v_pk_add_f32 v[60:61], v[72:73], v[22:23]
	v_pk_fma_f32 v[2:3], v[2:3], s[100:101], v[48:49] op_sel_hi:[1,0,1] neg_lo:[0,0,1] neg_hi:[0,0,1]
	v_pk_fma_f32 v[8:9], v[8:9], s[100:101], v[26:27] op_sel_hi:[1,0,1] neg_lo:[0,0,1] neg_hi:[0,0,1]
	v_pk_fma_f32 v[68:69], v[68:69], s[100:101], v[42:43] op_sel_hi:[1,0,1] neg_lo:[0,0,1] neg_hi:[0,0,1]
	v_pk_add_f32 v[72:73], v[72:73], v[22:23] neg_lo:[0,1] neg_hi:[0,1]
	v_pk_fma_f32 v[12:13], v[12:13], s[100:101], v[30:31] op_sel_hi:[1,0,1] neg_lo:[0,0,1] neg_hi:[0,0,1]
	v_pk_fma_f32 v[4:5], v[4:5], s[100:101], v[58:59] op_sel_hi:[1,0,1] neg_lo:[0,0,1] neg_hi:[0,0,1]
	v_pk_fma_f32 v[70:71], v[70:71], s[100:101], v[14:15] op_sel_hi:[1,0,1] neg_lo:[0,0,1] neg_hi:[0,0,1]
	v_pk_add_f32 v[22:23], v[18:19], v[38:39] op_sel:[0,1] op_sel_hi:[1,0] neg_lo:[0,1]
	v_pk_add_f32 v[34:35], v[48:49], v[30:31]
	v_pk_add_f32 v[32:33], v[26:27], v[58:59]
	v_pk_add_f32 v[52:53], v[42:43], v[14:15]
	v_pk_add_f32 v[38:39], v[18:19], v[38:39] op_sel:[0,1] op_sel_hi:[1,0] neg_hi:[0,1]
	v_pk_add_f32 v[30:31], v[48:49], v[30:31] neg_lo:[0,1] neg_hi:[0,1]
	v_pk_add_f32 v[58:59], v[26:27], v[58:59] neg_lo:[0,1] neg_hi:[0,1]
	v_pk_add_f32 v[14:15], v[42:43], v[14:15] neg_lo:[0,1] neg_hi:[0,1]
	v_pk_add_f32 v[42:43], v[2:3], v[12:13] op_sel:[0,1] op_sel_hi:[1,0] neg_lo:[0,1]
	v_pk_add_f32 v[26:27], v[8:9], v[4:5] op_sel:[0,1] op_sel_hi:[1,0] neg_lo:[0,1]
	v_pk_add_f32 v[48:49], v[68:69], v[70:71] op_sel:[0,1] op_sel_hi:[1,0] neg_lo:[0,1]
	v_pk_add_f32 v[12:13], v[2:3], v[12:13] op_sel:[0,1] op_sel_hi:[1,0] neg_hi:[0,1]
	v_pk_add_f32 v[8:9], v[8:9], v[4:5] op_sel:[0,1] op_sel_hi:[1,0] neg_hi:[0,1]
	v_pk_add_f32 v[68:69], v[68:69], v[70:71] op_sel:[0,1] op_sel_hi:[1,0] neg_hi:[0,1]
	v_pk_add_f32 v[70:71], v[60:61], v[32:33]
	v_pk_mul_f32 v[4:5], v[42:43], s[82:83] op_sel_hi:[1,0]
	v_pk_mul_f32 v[2:3], v[30:31], s[76:77] op_sel_hi:[1,0]
	v_pk_mul_f32 v[18:19], v[12:13], s[44:45] op_sel_hi:[1,0]
	v_pk_add_f32 v[60:61], v[60:61], v[32:33] neg_lo:[0,1] neg_hi:[0,1]
	v_pk_fma_f32 v[4:5], v[42:43], s[44:45], v[4:5] op_sel:[0,0,1] op_sel_hi:[1,0,0] neg_lo:[0,0,1]
	v_pk_fma_f32 v[30:31], v[30:31], s[76:77], v[2:3] op_sel:[0,0,1] op_sel_hi:[1,0,0] neg_lo:[0,0,1]
	v_pk_fma_f32 v[18:19], v[12:13], s[82:83], v[18:19] op_sel:[0,0,1] op_sel_hi:[1,0,0] neg_lo:[0,0,1]
	v_pk_add_f32 v[12:13], v[34:35], v[52:53]
	v_pk_fma_f32 v[2:3], v[26:27], s[76:77], v[22:23] op_sel:[0,0,1] op_sel_hi:[1,0,0] neg_hi:[0,0,1]
	v_pk_add_f32 v[42:43], v[72:73], v[58:59] op_sel:[0,1] op_sel_hi:[1,0] neg_lo:[0,1]
	v_pk_fma_f32 v[32:33], v[8:9], s[76:77], v[38:39] op_sel:[0,0,1] op_sel_hi:[1,0,0] neg_hi:[0,0,1]
	v_pk_add_f32 v[34:35], v[34:35], v[52:53] neg_lo:[0,1] neg_hi:[0,1]
	v_pk_fma_f32 v[26:27], v[26:27], s[76:77], v[2:3] op_sel:[0,0,1] op_sel_hi:[1,0,0] neg_lo:[0,0,1]
	v_pk_add_f32 v[72:73], v[72:73], v[58:59] op_sel:[0,1] op_sel_hi:[1,0] neg_hi:[0,1]
	v_pk_fma_f32 v[8:9], v[8:9], s[72:73], v[32:33] op_sel:[0,0,1] op_sel_hi:[1,0,0] neg_lo:[0,0,1]
	v_pk_add_f32 v[32:33], v[70:71], v[12:13]
	v_pk_fma_f32 v[22:23], v[22:23], s[100:101], v[26:27] op_sel_hi:[1,0,1] neg_lo:[0,0,1] neg_hi:[0,0,1]
	v_pk_fma_f32 v[58:59], v[14:15], s[76:77], v[30:31] op_sel:[0,0,1] op_sel_hi:[1,0,0] neg_hi:[0,0,1]
	v_pk_fma_f32 v[38:39], v[38:39], s[100:101], v[8:9] op_sel_hi:[1,0,1] neg_lo:[0,0,1] neg_hi:[0,0,1]
	v_pk_add_f32 v[70:71], v[70:71], v[12:13] neg_lo:[0,1] neg_hi:[0,1]
	v_pk_fma_f32 v[12:13], v[48:49], s[44:45], v[4:5] op_sel:[0,0,1] op_sel_hi:[1,0,0] neg_hi:[0,0,1]
	v_pk_fma_f32 v[14:15], v[14:15], s[72:73], v[58:59] op_sel:[0,0,1] op_sel_hi:[1,0,0] neg_lo:[0,0,1]
	v_pk_fma_f32 v[58:59], v[68:69], s[70:71], v[18:19] op_sel:[0,0,1] op_sel_hi:[1,0,0] neg_hi:[0,0,1]
	v_pk_add_f32 v[2:3], v[60:61], v[34:35] op_sel:[0,1] op_sel_hi:[1,0] neg_lo:[0,1]
	v_pk_fma_f32 v[48:49], v[48:49], s[82:83], v[12:13] op_sel:[0,0,1] op_sel_hi:[1,0,0] neg_lo:[0,0,1]
	v_pk_fma_f32 v[30:31], v[30:31], s[100:101], v[14:15] op_sel_hi:[1,0,1] neg_lo:[0,0,1] neg_hi:[0,0,1]
	v_pk_fma_f32 v[68:69], v[68:69], s[64:65], v[58:59] op_sel:[0,0,1] op_sel_hi:[1,0,0] neg_lo:[0,0,1]
	v_pk_add_f32 v[60:61], v[60:61], v[34:35] op_sel:[0,1] op_sel_hi:[1,0] neg_hi:[0,1]
; #define LAS __attribute__((address_space(3)))
; #define LT() ({ int lt_ = tid; asm volatile("" : "+v"(lt_)); lt_; })
; template <bool INV> __device__ __forceinline__ void pass16(LAS f32x2* X, const LAS f32x2* TH, const LAS f32x2* TL, int base, int stride, int tw) {
;     f32x2 x[16];
; #pragma unroll
;     for (int q = 0; q < 16; ++q) x[q] = X[base + q * stride];
;     bfly16<INV>(x, TH, TL, tw);
; #pragma unroll
;     for (int c = 0; c < 4; ++c)
; #pragma unroll
;         for (int d = 0; d < 4; ++d) X[base + (c + 4 * d) * stride] = x[4 * c + d];
; }
; __device__ __forceinline__ void hyena_latent(Frame& F, int l, int ch, LAS f32x2* X, const LAS f32x2* TH, const LAS f32x2* TL, GAS f32x2* KS, const LAS float* CT  , bool wr = true) {
;     ...
;             if (par == 0) {
; #pragma unroll
;                 for (int i = 0; i < 8; ++i) { const int g = LT() + NTHR * i; const LAS f32x4* XP = (const LAS f32x4*)(X + phys(4 * g)); KE4[2 * g] = XP[0]; KE4[2 * g + 1] = XP[1]; }
;                 __syncthreads();
;             }
	v_pk_fma_f32 v[4:5], v[4:5], s[100:101], v[48:49] op_sel_hi:[1,0,1] neg_lo:[0,0,1] neg_hi:[0,0,1]
	v_pk_add_f32 v[34:35], v[42:43], v[14:15]
	v_pk_fma_f32 v[18:19], v[18:19], s[100:101], v[68:69] op_sel_hi:[1,0,1] neg_lo:[0,0,1] neg_hi:[0,0,1]
	v_pk_add_f32 v[58:59], v[26:27], v[48:49]
	v_pk_add_f32 v[14:15], v[42:43], v[14:15] neg_lo:[0,1] neg_hi:[0,1]
	v_pk_add_f32 v[42:43], v[8:9], v[68:69]
	v_pk_add_f32 v[26:27], v[26:27], v[48:49] neg_lo:[0,1] neg_hi:[0,1]
	v_pk_add_f32 v[48:49], v[72:73], v[30:31] op_sel:[0,1] op_sel_hi:[1,0] neg_lo:[0,1]
	v_pk_add_f32 v[68:69], v[8:9], v[68:69] neg_lo:[0,1] neg_hi:[0,1]
	v_pk_add_f32 v[8:9], v[22:23], v[4:5] op_sel:[0,1] op_sel_hi:[1,0] neg_lo:[0,1]
	v_pk_add_f32 v[30:31], v[72:73], v[30:31] op_sel:[0,1] op_sel_hi:[1,0] neg_hi:[0,1]
	v_pk_add_f32 v[72:73], v[38:39], v[18:19] op_sel:[0,1] op_sel_hi:[1,0] neg_lo:[0,1]
	v_pk_add_f32 v[22:23], v[22:23], v[4:5] op_sel:[0,1] op_sel_hi:[1,0] neg_hi:[0,1]
	v_pk_add_f32 v[38:39], v[38:39], v[18:19] op_sel:[0,1] op_sel_hi:[1,0] neg_hi:[0,1]
	ds_write_b64 v151, v[32:33] offset:0
	ds_write_b64 v151, v[58:59] offset:8704
	ds_write_b64 v151, v[34:35] offset:17408
	ds_write_b64 v151, v[42:43] offset:26112
	ds_write_b64 v151, v[2:3] offset:34816
	ds_write_b64 v151, v[8:9] offset:43520
	ds_write_b64 v151, v[48:49] offset:52224
	ds_write_b64 v151, v[72:73] offset:60928
	ds_write_b64 v176, v[70:71] offset:0
	ds_write_b64 v176, v[26:27] offset:8704
	ds_write_b64 v176, v[14:15] offset:17408
	ds_write_b64 v176, v[68:69] offset:26112
	ds_write_b64 v176, v[60:61] offset:34816
	ds_write_b64 v176, v[22:23] offset:43520
	ds_write_b64 v176, v[30:31] offset:52224
	ds_write_b64 v176, v[38:39] offset:60928
	s_cbranch_scc1 .LBB0_856
	s_waitcnt lgkmcnt(0)
	s_barrier
	s_andn2_b64 vcc, exec, s[34:35]
	s_mov_b64 s[12:13], -1
	s_cbranch_vccnz .LBB0_662
	v_mov_b32_e32 v1, v140
	s_mov_b64 s[12:13], 0
	v_lshlrev_b32_e32 v0, 1, v1
	v_and_b32_e32 v2, 0xffffffe0, v0
	v_lshlrev_b32_e32 v1, 5, v1
	v_add3_u32 v4, 0, v2, v1
	v_ashrrev_i32_e32 v1, 31, v0
	v_lshl_add_u64 v[8:9], v[0:1], 4, s[18:19]
	ds_read_b128 v[0:3], v4
	ds_read_b128 v[4:7], v4 offset:16
	s_waitcnt lgkmcnt(1)
	global_store_dwordx4 v[8:9], v[0:3], off
	s_waitcnt lgkmcnt(0)
	global_store_dwordx4 v[8:9], v[4:7], off offset:16
	v_mov_b32_e32 v0, v140
	s_nop 0
	v_add_u32_e32 v1, 0x200, v0
	v_lshlrev_b32_e32 v0, 1, v1
	v_and_b32_e32 v2, 0xffffffe0, v0
	v_lshlrev_b32_e32 v1, 5, v1
	v_add3_u32 v4, 0, v2, v1
	v_ashrrev_i32_e32 v1, 31, v0
	v_lshl_add_u64 v[8:9], v[0:1], 4, s[18:19]
	ds_read_b128 v[0:3], v4
	ds_read_b128 v[4:7], v4 offset:16
	s_waitcnt lgkmcnt(1)
	global_store_dwordx4 v[8:9], v[0:3], off
	s_waitcnt lgkmcnt(0)
	global_store_dwordx4 v[8:9], v[4:7], off offset:16
	v_mov_b32_e32 v0, v140
	s_nop 0
	v_add_u32_e32 v1, 0x400, v0
	v_lshlrev_b32_e32 v0, 1, v1
	v_and_b32_e32 v2, 0xffffffe0, v0
	v_lshlrev_b32_e32 v1, 5, v1
	v_add3_u32 v4, 0, v2, v1
	v_ashrrev_i32_e32 v1, 31, v0
	v_lshl_add_u64 v[8:9], v[0:1], 4, s[18:19]
	ds_read_b128 v[0:3], v4
	ds_read_b128 v[4:7], v4 offset:16
	s_waitcnt lgkmcnt(1)
	global_store_dwordx4 v[8:9], v[0:3], off
	s_waitcnt lgkmcnt(0)
	global_store_dwordx4 v[8:9], v[4:7], off offset:16
	v_mov_b32_e32 v0, v140
	s_nop 0
	v_add_u32_e32 v1, 0x600, v0
	v_lshlrev_b32_e32 v0, 1, v1
	v_and_b32_e32 v2, 0xffffffe0, v0
	v_lshlrev_b32_e32 v1, 5, v1
	v_add3_u32 v4, 0, v2, v1
	v_ashrrev_i32_e32 v1, 31, v0
	v_lshl_add_u64 v[8:9], v[0:1], 4, s[18:19]
	ds_read_b128 v[0:3], v4
	ds_read_b128 v[4:7], v4 offset:16
	s_waitcnt lgkmcnt(1)
	global_store_dwordx4 v[8:9], v[0:3], off
	s_waitcnt lgkmcnt(0)
	global_store_dwordx4 v[8:9], v[4:7], off offset:16
	v_mov_b32_e32 v0, v140
	s_nop 0
	v_add_u32_e32 v1, 0x800, v0
	v_lshlrev_b32_e32 v0, 1, v1
	v_and_b32_e32 v2, 0xffffffe0, v0
	v_lshlrev_b32_e32 v1, 5, v1
	v_add3_u32 v4, 0, v2, v1
	v_ashrrev_i32_e32 v1, 31, v0
	v_lshl_add_u64 v[8:9], v[0:1], 4, s[18:19]
	ds_read_b128 v[0:3], v4
	ds_read_b128 v[4:7], v4 offset:16
	s_waitcnt lgkmcnt(1)
	global_store_dwordx4 v[8:9], v[0:3], off
	s_waitcnt lgkmcnt(0)
	global_store_dwordx4 v[8:9], v[4:7], off offset:16
	v_mov_b32_e32 v0, v140
	s_nop 0
	v_add_u32_e32 v1, 0xa00, v0
	v_lshlrev_b32_e32 v0, 1, v1
	v_and_b32_e32 v2, 0xffffffe0, v0
	v_lshlrev_b32_e32 v1, 5, v1
	v_add3_u32 v4, 0, v2, v1
	v_ashrrev_i32_e32 v1, 31, v0
	v_lshl_add_u64 v[8:9], v[0:1], 4, s[18:19]
	ds_read_b128 v[0:3], v4
	ds_read_b128 v[4:7], v4 offset:16
	s_waitcnt lgkmcnt(1)
	global_store_dwordx4 v[8:9], v[0:3], off
	s_waitcnt lgkmcnt(0)
	global_store_dwordx4 v[8:9], v[4:7], off offset:16
	v_mov_b32_e32 v0, v140
	s_nop 0
	v_add_u32_e32 v1, 0xc00, v0
	v_lshlrev_b32_e32 v0, 1, v1
	v_and_b32_e32 v2, 0xffffffe0, v0
	v_lshlrev_b32_e32 v1, 5, v1
	v_add3_u32 v4, 0, v2, v1
	v_ashrrev_i32_e32 v1, 31, v0
	v_lshl_add_u64 v[8:9], v[0:1], 4, s[18:19]
	ds_read_b128 v[0:3], v4
	ds_read_b128 v[4:7], v4 offset:16
	s_waitcnt lgkmcnt(1)
	global_store_dwordx4 v[8:9], v[0:3], off
	s_waitcnt lgkmcnt(0)
	global_store_dwordx4 v[8:9], v[4:7], off offset:16
	v_mov_b32_e32 v0, v140
	s_nop 0
	v_add_u32_e32 v1, 0xe00, v0
	v_lshlrev_b32_e32 v0, 1, v1
	v_and_b32_e32 v2, 0xffffffe0, v0
	v_lshlrev_b32_e32 v1, 5, v1
	v_add3_u32 v4, 0, v2, v1
	v_ashrrev_i32_e32 v1, 31, v0
	v_lshl_add_u64 v[8:9], v[0:1], 4, s[18:19]
	ds_read_b128 v[0:3], v4
	ds_read_b128 v[4:7], v4 offset:16
	s_waitcnt lgkmcnt(1)
	global_store_dwordx4 v[8:9], v[0:3], off
	s_waitcnt lgkmcnt(0)
	global_store_dwordx4 v[8:9], v[4:7], off offset:16
	s_barrier
	s_branch .LBB0_662

; #define LAS __attribute__((address_space(3)))
; __device__ __forceinline__ f32x2 cmul(f32x2 a, f32x2 b) { return (f32x2){a.x * b.x - a.y * b.y, a.x * b.y + a.y * b.x}; }
; __device__ __forceinline__ f32x2 tw32k(const LAS f32x2* TH, const LAS f32x2* TL, int n) { return cmul(TH[n >> 7], TL[n & 127]); }
; template <bool INV> __device__ __forceinline__ void dft16(f32x2 (&x)[16]) {
; #pragma unroll
;     for (int b = 0; b < 4; ++b) r4<INV>(x[b], x[4 + b], x[8 + b], x[12 + b]);
;     const float sg = INV ? -1.f : 1.f;
;     const f32x2 W1 = {0.92387953251f, -0.38268343236f * sg}, W2 = {0.70710678118f, -0.70710678118f * sg}, W3 = {0.38268343236f, -0.92387953251f * sg},
;                 W4 = {0.f, -1.f * sg}, W6 = {-0.70710678118f, -0.70710678118f * sg}, W9 = {-0.92387953251f, 0.38268343236f * sg};
;     x[5] = cmul(x[5], W1); x[9] = cmul(x[9], W2); x[13] = cmul(x[13], W3);
;     x[6] = cmul(x[6], W2); x[10] = cmul(x[10], W4); x[14] = cmul(x[14], W6);
;     x[7] = cmul(x[7], W3); x[11] = cmul(x[11], W6); x[15] = cmul(x[15], W9);
; #pragma unroll
;     for (int c = 0; c < 4; ++c) r4<INV>(x[4 * c], x[4 * c + 1], x[4 * c + 2], x[4 * c + 3]);
; }
; template <bool INV> __device__ __forceinline__ void bfly16(f32x2 (&x)[16], const LAS f32x2* TH, const LAS f32x2* TL, int tw) {
;     f32x2 W = tw32k(TH, TL, tw); if (INV) W.y = -W.y;
;     if (INV) { f32x2 p = W;
; #pragma unroll
;         for (int q = 1; q < 16; ++q) { x[q] = cmul(x[q], p); if (q < 15) p = cmul(p, W); } }
;     dft16<INV>(x);
;     if (!INV) { f32x2 p = W;
; #pragma unroll
;         for (int r = 1; r < 16; ++r) { x[4 * (r & 3) + (r >> 2)] = cmul(x[4 * (r & 3) + (r >> 2)], p); if (r < 15) p = cmul(p, W); } }
; }
.LBB0_944:
	v_add_u32_e32 v37, s0, v140
	v_lshrrev_b32_e32 v138, 6, v37
	v_and_b32_e32 v234, 63, v37
	v_lshlrev_b32_e32 v176, 5, v138
	v_lshlrev_b32_e32 v218, 3, v138
	v_lshlrev_b32_e32 v234, 4, v234
	v_lshl_add_u32 v176, v37, 3, v176
	v_add_u32_e32 v218, 0x26000, v218
	v_add_u32_e32 v234, 0x26400, v234
	v_add_u32_e32 v235, 0x11000, v176
	ds_read_b64 v[0:1], v218
	ds_read_b64 v[2:3], v234
	ds_read_b64 v[4:5], v176 offset:0
	ds_read_b64 v[6:7], v235 offset:0
	ds_read_b64 v[8:9], v176 offset:8704
	ds_read_b64 v[10:11], v235 offset:8704
	ds_read_b64 v[12:13], v176 offset:17408
	ds_read_b64 v[14:15], v235 offset:17408
	ds_read_b64 v[16:17], v176 offset:26112
	ds_read_b64 v[18:19], v235 offset:26112
	ds_read_b64 v[20:21], v176 offset:34816
	ds_read_b64 v[22:23], v235 offset:34816
	ds_read_b64 v[24:25], v176 offset:43520
	ds_read_b64 v[26:27], v235 offset:43520
	ds_read_b64 v[28:29], v176 offset:52224
	ds_read_b64 v[30:31], v235 offset:52224
	ds_read_b64 v[32:33], v176 offset:60928
	ds_read_b64 v[34:35], v235 offset:60928
	s_cmp_eq_u32 s0, 0
	s_movk_i32 s0, 0x200
	s_mov_b64 s[8:9], 0
	s_waitcnt lgkmcnt(15)
	v_pk_mul_f32 v[38:39], v[0:1], v[2:3] op_sel:[0,1] op_sel_hi:[1,1]
	s_nop 0
	v_pk_fma_f32 v[0:1], v[0:1], v[2:3], v[38:39] op_sel:[0,0,1] op_sel_hi:[1,0,0] neg_lo:[0,0,1]
	s_nop 0
	v_pk_mul_f32 v[38:39], v[0:1], v[0:1] op_sel:[0,1] op_sel_hi:[1,1]
	s_nop 0
	v_pk_fma_f32 v[38:39], v[0:1], v[0:1], v[38:39] op_sel:[0,0,1] op_sel_hi:[1,0,0] neg_lo:[0,0,1]
	s_nop 0
	v_pk_mul_f32 v[2:3], v[38:39], v[0:1] op_sel:[0,1] op_sel_hi:[1,1]
	v_pk_mul_f32 v[40:41], v[38:39], v[38:39] op_sel:[0,1] op_sel_hi:[1,1]
	v_pk_fma_f32 v[2:3], v[38:39], v[0:1], v[2:3] op_sel:[0,0,1] op_sel_hi:[1,0,0] neg_lo:[0,0,1]
	v_pk_fma_f32 v[40:41], v[38:39], v[38:39], v[40:41] op_sel:[0,0,1] op_sel_hi:[1,0,0] neg_lo:[0,0,1]
	s_nop 0
	v_pk_mul_f32 v[42:43], v[40:41], v[0:1] op_sel:[0,1] op_sel_hi:[1,1]
	v_pk_mul_f32 v[44:45], v[40:41], v[38:39] op_sel:[0,1] op_sel_hi:[1,1]
	v_pk_mul_f32 v[46:47], v[40:41], v[2:3] op_sel:[0,1] op_sel_hi:[1,1]
	v_pk_fma_f32 v[42:43], v[40:41], v[0:1], v[42:43] op_sel:[0,0,1] op_sel_hi:[1,0,0] neg_lo:[0,0,1]
	v_pk_fma_f32 v[44:45], v[40:41], v[38:39], v[44:45] op_sel:[0,0,1] op_sel_hi:[1,0,0] neg_lo:[0,0,1]
	v_pk_fma_f32 v[46:47], v[40:41], v[2:3], v[46:47] op_sel:[0,0,1] op_sel_hi:[1,0,0] neg_lo:[0,0,1]
	v_pk_mul_f32 v[48:49], v[40:41], v[40:41] op_sel:[0,1] op_sel_hi:[1,1]
	s_nop 0
	v_pk_fma_f32 v[48:49], v[40:41], v[40:41], v[48:49] op_sel:[0,0,1] op_sel_hi:[1,0,0] neg_lo:[0,0,1]
	s_nop 0
	v_pk_mul_f32 v[50:51], v[48:49], v[0:1] op_sel:[0,1] op_sel_hi:[1,1]
	v_pk_mul_f32 v[52:53], v[48:49], v[38:39] op_sel:[0,1] op_sel_hi:[1,1]
	v_pk_mul_f32 v[54:55], v[48:49], v[2:3] op_sel:[0,1] op_sel_hi:[1,1]
	v_pk_fma_f32 v[50:51], v[48:49], v[0:1], v[50:51] op_sel:[0,0,1] op_sel_hi:[1,0,0] neg_lo:[0,0,1]
	v_pk_fma_f32 v[52:53], v[48:49], v[38:39], v[52:53] op_sel:[0,0,1] op_sel_hi:[1,0,0] neg_lo:[0,0,1]
	v_pk_fma_f32 v[54:55], v[48:49], v[2:3], v[54:55] op_sel:[0,0,1] op_sel_hi:[1,0,0] neg_lo:[0,0,1]
	v_pk_mul_f32 v[56:57], v[48:49], v[40:41] op_sel:[0,1] op_sel_hi:[1,1]
	v_pk_mul_f32 v[58:59], v[48:49], v[42:43] op_sel:[0,1] op_sel_hi:[1,1]
	v_pk_mul_f32 v[60:61], v[48:49], v[44:45] op_sel:[0,1] op_sel_hi:[1,1]
	v_pk_fma_f32 v[56:57], v[48:49], v[40:41], v[56:57] op_sel:[0,0,1] op_sel_hi:[1,0,0] neg_lo:[0,0,1]
	v_pk_fma_f32 v[58:59], v[48:49], v[42:43], v[58:59] op_sel:[0,0,1] op_sel_hi:[1,0,0] neg_lo:[0,0,1]
	v_pk_fma_f32 v[60:61], v[48:49], v[44:45], v[60:61] op_sel:[0,0,1] op_sel_hi:[1,0,0] neg_lo:[0,0,1]
	v_pk_mul_f32 v[62:63], v[48:49], v[46:47] op_sel:[0,1] op_sel_hi:[1,1]
	s_nop 0
	v_pk_fma_f32 v[62:63], v[48:49], v[46:47], v[62:63] op_sel:[0,0,1] op_sel_hi:[1,0,0] neg_lo:[0,0,1]
	s_waitcnt lgkmcnt(14)
	v_pk_add_f32 v[64:65], v[4:5], v[6:7]
	s_waitcnt lgkmcnt(12)
	v_pk_add_f32 v[66:67], v[8:9], v[10:11]
	s_waitcnt lgkmcnt(10)
	v_pk_add_f32 v[68:69], v[12:13], v[14:15]
	s_waitcnt lgkmcnt(8)
	v_pk_add_f32 v[70:71], v[16:17], v[18:19]
	v_pk_add_f32 v[4:5], v[4:5], v[6:7] neg_lo:[0,1] neg_hi:[0,1]
	v_pk_add_f32 v[10:11], v[8:9], v[10:11] neg_lo:[0,1] neg_hi:[0,1]
	v_pk_add_f32 v[14:15], v[12:13], v[14:15] neg_lo:[0,1] neg_hi:[0,1]
	v_pk_add_f32 v[18:19], v[16:17], v[18:19] neg_lo:[0,1] neg_hi:[0,1]
	s_waitcnt lgkmcnt(6)
	v_pk_add_f32 v[16:17], v[20:21], v[22:23]
	s_waitcnt lgkmcnt(4)
	v_pk_add_f32 v[12:13], v[24:25], v[26:27]
	s_waitcnt lgkmcnt(2)
	v_pk_add_f32 v[8:9], v[28:29], v[30:31]
	s_waitcnt lgkmcnt(0)
; #define LAS __attribute__((address_space(3)))
; __device__ __forceinline__ f32x2 cmul(f32x2 a, f32x2 b) { return (f32x2){a.x * b.x - a.y * b.y, a.x * b.y + a.y * b.x}; }
; __device__ __forceinline__ f32x2 tw32k(const LAS f32x2* TH, const LAS f32x2* TL, int n) { return cmul(TH[n >> 7], TL[n & 127]); }
; template <bool INV> __device__ __forceinline__ void dft16(f32x2 (&x)[16]) {
; #pragma unroll
;     for (int b = 0; b < 4; ++b) r4<INV>(x[b], x[4 + b], x[8 + b], x[12 + b]);
;     const float sg = INV ? -1.f : 1.f;
;     const f32x2 W1 = {0.92387953251f, -0.38268343236f * sg}, W2 = {0.70710678118f, -0.70710678118f * sg}, W3 = {0.38268343236f, -0.92387953251f * sg},
;                 W4 = {0.f, -1.f * sg}, W6 = {-0.70710678118f, -0.70710678118f * sg}, W9 = {-0.92387953251f, 0.38268343236f * sg};
;     x[5] = cmul(x[5], W1); x[9] = cmul(x[9], W2); x[13] = cmul(x[13], W3);
;     x[6] = cmul(x[6], W2); x[10] = cmul(x[10], W4); x[14] = cmul(x[14], W6);
;     x[7] = cmul(x[7], W3); x[11] = cmul(x[11], W6); x[15] = cmul(x[15], W9);
; #pragma unroll
;     for (int c = 0; c < 4; ++c) r4<INV>(x[4 * c], x[4 * c + 1], x[4 * c + 2], x[4 * c + 3]);
; }
; template <bool INV> __device__ __forceinline__ void bfly16(f32x2 (&x)[16], const LAS f32x2* TH, const LAS f32x2* TL, int tw) {
;     f32x2 W = tw32k(TH, TL, tw); if (INV) W.y = -W.y;
;     if (INV) { f32x2 p = W;
; #pragma unroll
;         for (int q = 1; q < 16; ++q) { x[q] = cmul(x[q], p); if (q < 15) p = cmul(p, W); } }
;     dft16<INV>(x);
;     if (!INV) { f32x2 p = W;
; #pragma unroll
;         for (int r = 1; r < 16; ++r) { x[4 * (r & 3) + (r >> 2)] = cmul(x[4 * (r & 3) + (r >> 2)], p); if (r < 15) p = cmul(p, W); } }
; }
	v_pk_add_f32 v[6:7], v[32:33], v[34:35]
	v_pk_add_f32 v[22:23], v[20:21], v[22:23] neg_lo:[0,1] neg_hi:[0,1]
	v_pk_add_f32 v[24:25], v[24:25], v[26:27] neg_lo:[0,1] neg_hi:[0,1]
	v_pk_add_f32 v[28:29], v[28:29], v[30:31] neg_lo:[0,1] neg_hi:[0,1]
	v_pk_add_f32 v[34:35], v[32:33], v[34:35] neg_lo:[0,1] neg_hi:[0,1]
	v_pk_add_f32 v[32:33], v[64:65], v[16:17]
	v_pk_add_f32 v[30:31], v[66:67], v[12:13]
	v_pk_add_f32 v[26:27], v[68:69], v[8:9]
	v_pk_add_f32 v[20:21], v[70:71], v[6:7]
	v_pk_add_f32 v[16:17], v[64:65], v[16:17] neg_lo:[0,1] neg_hi:[0,1]
	v_pk_add_f32 v[66:67], v[66:67], v[12:13] neg_lo:[0,1] neg_hi:[0,1]
	v_pk_add_f32 v[8:9], v[68:69], v[8:9] neg_lo:[0,1] neg_hi:[0,1]
	v_pk_add_f32 v[6:7], v[70:71], v[6:7] neg_lo:[0,1] neg_hi:[0,1]
	v_pk_add_f32 v[70:71], v[4:5], v[22:23] op_sel:[0,1] op_sel_hi:[1,0] neg_hi:[0,1]
	v_pk_add_f32 v[68:69], v[10:11], v[24:25] op_sel:[0,1] op_sel_hi:[1,0] neg_hi:[0,1]
	v_pk_add_f32 v[12:13], v[14:15], v[28:29] op_sel:[0,1] op_sel_hi:[1,0] neg_hi:[0,1]
	v_pk_add_f32 v[64:65], v[18:19], v[34:35] op_sel:[0,1] op_sel_hi:[1,0] neg_hi:[0,1]
	v_pk_add_f32 v[22:23], v[4:5], v[22:23] op_sel:[0,1] op_sel_hi:[1,0] neg_lo:[0,1]
	v_pk_add_f32 v[24:25], v[10:11], v[24:25] op_sel:[0,1] op_sel_hi:[1,0] neg_lo:[0,1]
	v_pk_add_f32 v[14:15], v[14:15], v[28:29] op_sel:[0,1] op_sel_hi:[1,0] neg_lo:[0,1]
	v_pk_add_f32 v[18:19], v[18:19], v[34:35] op_sel:[0,1] op_sel_hi:[1,0] neg_lo:[0,1]
	v_pk_add_f32 v[34:35], v[32:33], v[26:27]
	v_pk_mul_f32 v[28:29], v[68:69], s[70:71] op_sel_hi:[1,0]
	v_pk_mul_f32 v[10:11], v[66:67], s[72:73] op_sel_hi:[1,0]
	v_pk_mul_f32 v[4:5], v[24:25], s[64:65] op_sel_hi:[1,0]
	v_pk_add_f32 v[26:27], v[32:33], v[26:27] neg_lo:[0,1] neg_hi:[0,1]
	v_pk_fma_f32 v[68:69], v[68:69], s[44:45], v[28:29] op_sel:[0,0,1] op_sel_hi:[1,0,0] neg_lo:[0,0,1]
	v_pk_fma_f32 v[66:67], v[66:67], s[76:77], v[10:11] op_sel:[0,0,1] op_sel_hi:[1,0,0] neg_lo:[0,0,1]
	v_pk_fma_f32 v[24:25], v[24:25], s[82:83], v[4:5] op_sel:[0,0,1] op_sel_hi:[1,0,0] neg_lo:[0,0,1]
	v_pk_add_f32 v[4:5], v[30:31], v[20:21]
	v_pk_fma_f32 v[10:11], v[12:13], s[72:73], v[70:71] op_sel:[0,0,1] op_sel_hi:[1,0,0] neg_hi:[0,0,1]
	v_pk_add_f32 v[28:29], v[16:17], v[8:9] op_sel:[0,1] op_sel_hi:[1,0] neg_hi:[0,1]
	v_pk_fma_f32 v[32:33], v[14:15], s[72:73], v[22:23] op_sel:[0,0,1] op_sel_hi:[1,0,0] neg_hi:[0,0,1]
	v_pk_add_f32 v[30:31], v[30:31], v[20:21] neg_lo:[0,1] neg_hi:[0,1]
	v_pk_fma_f32 v[10:11], v[12:13], s[76:77], v[10:11] op_sel:[0,0,1] op_sel_hi:[1,0,0] neg_lo:[0,0,1]
	v_pk_add_f32 v[16:17], v[16:17], v[8:9] op_sel:[0,1] op_sel_hi:[1,0] neg_lo:[0,1]
	v_pk_fma_f32 v[14:15], v[14:15], s[72:73], v[32:33] op_sel:[0,0,1] op_sel_hi:[1,0,0] neg_lo:[0,0,1]
	v_pk_add_f32 v[32:33], v[34:35], v[4:5]
	v_pk_fma_f32 v[70:71], v[70:71], s[100:101], v[10:11] op_sel_hi:[1,0,1] neg_lo:[0,0,1] neg_hi:[0,0,1]
	v_pk_fma_f32 v[8:9], v[6:7], s[72:73], v[66:67] op_sel:[0,0,1] op_sel_hi:[1,0,0] neg_hi:[0,0,1]
	v_pk_fma_f32 v[22:23], v[22:23], s[100:101], v[14:15] op_sel_hi:[1,0,1] neg_lo:[0,0,1] neg_hi:[0,0,1]
	v_pk_add_f32 v[4:5], v[34:35], v[4:5] neg_lo:[0,1] neg_hi:[0,1]
	v_pk_fma_f32 v[34:35], v[64:65], s[64:65], v[68:69] op_sel:[0,0,1] op_sel_hi:[1,0,0] neg_hi:[0,0,1]
	v_pk_fma_f32 v[6:7], v[6:7], s[72:73], v[8:9] op_sel:[0,0,1] op_sel_hi:[1,0,0] neg_lo:[0,0,1]
	v_pk_fma_f32 v[8:9], v[18:19], s[82:83], v[24:25] op_sel:[0,0,1] op_sel_hi:[1,0,0] neg_hi:[0,0,1]
	v_pk_add_f32 v[12:13], v[26:27], v[30:31] op_sel:[0,1] op_sel_hi:[1,0] neg_hi:[0,1]
	v_pk_fma_f32 v[64:65], v[64:65], s[82:83], v[34:35] op_sel:[0,0,1] op_sel_hi:[1,0,0] neg_lo:[0,0,1]
	v_pk_fma_f32 v[66:67], v[66:67], s[100:101], v[6:7] op_sel_hi:[1,0,1] neg_lo:[0,0,1] neg_hi:[0,0,1]
	v_pk_fma_f32 v[18:19], v[18:19], s[64:65], v[8:9] op_sel:[0,0,1] op_sel_hi:[1,0,0] neg_lo:[0,0,1]
	v_pk_add_f32 v[30:31], v[26:27], v[30:31] op_sel:[0,1] op_sel_hi:[1,0] neg_lo:[0,1]
	v_pk_fma_f32 v[68:69], v[68:69], s[100:101], v[64:65] op_sel_hi:[1,0,1] neg_lo:[0,0,1] neg_hi:[0,0,1]
	v_pk_add_f32 v[26:27], v[28:29], v[6:7]
	v_pk_fma_f32 v[24:25], v[24:25], s[100:101], v[18:19] op_sel_hi:[1,0,1] neg_lo:[0,0,1] neg_hi:[0,0,1]
	v_pk_add_f32 v[8:9], v[10:11], v[64:65]
	v_pk_add_f32 v[6:7], v[28:29], v[6:7] neg_lo:[0,1] neg_hi:[0,1]
	v_pk_add_f32 v[28:29], v[14:15], v[18:19]
	v_pk_add_f32 v[64:65], v[10:11], v[64:65] neg_lo:[0,1] neg_hi:[0,1]
	v_pk_add_f32 v[10:11], v[16:17], v[66:67] op_sel:[0,1] op_sel_hi:[1,0] neg_hi:[0,1]
	v_pk_add_f32 v[18:19], v[14:15], v[18:19] neg_lo:[0,1] neg_hi:[0,1]
	v_pk_add_f32 v[14:15], v[70:71], v[68:69] op_sel:[0,1] op_sel_hi:[1,0] neg_hi:[0,1]
	v_pk_add_f32 v[16:17], v[16:17], v[66:67] op_sel:[0,1] op_sel_hi:[1,0] neg_lo:[0,1]
	v_pk_add_f32 v[66:67], v[22:23], v[24:25] op_sel:[0,1] op_sel_hi:[1,0] neg_hi:[0,1]
	v_pk_add_f32 v[70:71], v[70:71], v[68:69] op_sel:[0,1] op_sel_hi:[1,0] neg_lo:[0,1]
	v_pk_add_f32 v[22:23], v[22:23], v[24:25] op_sel:[0,1] op_sel_hi:[1,0] neg_lo:[0,1]
	v_pk_mul_f32 v[24:25], v[8:9], v[0:1] op_sel:[0,1] op_sel_hi:[1,1]
	v_pk_mul_f32 v[68:69], v[26:27], v[38:39] op_sel:[0,1] op_sel_hi:[1,1]
	v_pk_fma_f32 v[24:25], v[8:9], v[0:1], v[24:25] op_sel:[0,0,1] op_sel_hi:[1,0,0] neg_lo:[0,0,1]
	v_pk_mul_f32 v[0:1], v[28:29], v[2:3] op_sel:[0,1] op_sel_hi:[1,1]
	v_pk_fma_f32 v[38:39], v[26:27], v[38:39], v[68:69] op_sel:[0,0,1] op_sel_hi:[1,0,0] neg_lo:[0,0,1]
	v_pk_mul_f32 v[68:69], v[12:13], v[40:41] op_sel:[0,1] op_sel_hi:[1,1]
	v_pk_fma_f32 v[28:29], v[28:29], v[2:3], v[0:1] op_sel:[0,0,1] op_sel_hi:[1,0,0] neg_lo:[0,0,1]
	v_pk_mul_f32 v[2:3], v[14:15], v[42:43] op_sel:[0,1] op_sel_hi:[1,1]
	v_pk_fma_f32 v[68:69], v[12:13], v[40:41], v[68:69] op_sel:[0,0,1] op_sel_hi:[1,0,0] neg_lo:[0,0,1]
; #define LAS __attribute__((address_space(3)))
; template <bool INV> __device__ __forceinline__ void pass16_s64(LAS f32x2* X, const LAS f32x2* TH, int base, int j) {
;     f32x2 x[16];
; #pragma unroll
;     for (int q = 0; q < 16; ++q) x[q] = X[base + q * 68];
;     bfly16_tab<INV>(x, TH - 2048, 64, j);
; #pragma unroll
;     for (int c = 0; c < 4; ++c)
; #pragma unroll
;         for (int d = 0; d < 4; ++d) X[base + (c + 4 * d) * 68] = x[4 * c + d];
; }
; template <bool INV> __device__ __forceinline__ void pass16(LAS f32x2* X, const LAS f32x2* TH, const LAS f32x2* TL, int base, int stride, int tw) {
;     f32x2 x[16];
; #pragma unroll
;     for (int q = 0; q < 16; ++q) x[q] = X[base + q * stride];
;     bfly16<INV>(x, TH, TL, tw);
; #pragma unroll
;     for (int c = 0; c < 4; ++c)
; #pragma unroll
;         for (int d = 0; d < 4; ++d) X[base + (c + 4 * d) * stride] = x[4 * c + d];
; }
	v_pk_mul_f32 v[12:13], v[10:11], v[44:45] op_sel:[0,1] op_sel_hi:[1,1]
	v_pk_fma_f32 v[42:43], v[14:15], v[42:43], v[2:3] op_sel:[0,0,1] op_sel_hi:[1,0,0] neg_lo:[0,0,1]
	v_pk_mul_f32 v[2:3], v[66:67], v[46:47] op_sel:[0,1] op_sel_hi:[1,1]
	v_pk_fma_f32 v[12:13], v[10:11], v[44:45], v[12:13] op_sel:[0,0,1] op_sel_hi:[1,0,0] neg_lo:[0,0,1]
	v_pk_mul_f32 v[10:11], v[4:5], v[48:49] op_sel:[0,1] op_sel_hi:[1,1]
	v_pk_fma_f32 v[2:3], v[66:67], v[46:47], v[2:3] op_sel:[0,0,1] op_sel_hi:[1,0,0] neg_lo:[0,0,1]
	v_pk_mul_f32 v[46:47], v[64:65], v[50:51] op_sel:[0,1] op_sel_hi:[1,1]
	v_pk_fma_f32 v[4:5], v[4:5], v[48:49], v[10:11] op_sel:[0,0,1] op_sel_hi:[1,0,0] neg_lo:[0,0,1]
	v_pk_mul_f32 v[10:11], v[6:7], v[52:53] op_sel:[0,1] op_sel_hi:[1,1]
	v_pk_fma_f32 v[46:47], v[64:65], v[50:51], v[46:47] op_sel:[0,0,1] op_sel_hi:[1,0,0] neg_lo:[0,0,1]
	v_pk_mul_f32 v[64:65], v[18:19], v[54:55] op_sel:[0,1] op_sel_hi:[1,1]
	v_pk_fma_f32 v[10:11], v[6:7], v[52:53], v[10:11] op_sel:[0,0,1] op_sel_hi:[1,0,0] neg_lo:[0,0,1]
	v_pk_mul_f32 v[52:53], v[30:31], v[56:57] op_sel:[0,1] op_sel_hi:[1,1]
	v_pk_fma_f32 v[54:55], v[18:19], v[54:55], v[64:65] op_sel:[0,0,1] op_sel_hi:[1,0,0] neg_lo:[0,0,1]
	v_pk_mul_f32 v[64:65], v[70:71], v[58:59] op_sel:[0,1] op_sel_hi:[1,1]
	v_pk_fma_f32 v[52:53], v[30:31], v[56:57], v[52:53] op_sel:[0,0,1] op_sel_hi:[1,0,0] neg_lo:[0,0,1]
	v_pk_mul_f32 v[30:31], v[16:17], v[60:61] op_sel:[0,1] op_sel_hi:[1,1]
	v_pk_fma_f32 v[64:65], v[70:71], v[58:59], v[64:65] op_sel:[0,0,1] op_sel_hi:[1,0,0] neg_lo:[0,0,1]
	v_pk_mul_f32 v[58:59], v[22:23], v[62:63] op_sel:[0,1] op_sel_hi:[1,1]
	v_pk_fma_f32 v[60:61], v[16:17], v[60:61], v[30:31] op_sel:[0,0,1] op_sel_hi:[1,0,0] neg_lo:[0,0,1]
	v_pk_fma_f32 v[58:59], v[22:23], v[62:63], v[58:59] op_sel:[0,0,1] op_sel_hi:[1,0,0] neg_lo:[0,0,1]
	ds_write_b64 v176, v[32:33] offset:0
	ds_write_b64 v176, v[24:25] offset:8704
	ds_write_b64 v176, v[38:39] offset:17408
	ds_write_b64 v176, v[28:29] offset:26112
	ds_write_b64 v176, v[68:69] offset:34816
	ds_write_b64 v176, v[42:43] offset:43520
	ds_write_b64 v176, v[12:13] offset:52224
	ds_write_b64 v176, v[2:3] offset:60928
	ds_write_b64 v235, v[4:5] offset:0
	ds_write_b64 v235, v[46:47] offset:8704
	ds_write_b64 v235, v[10:11] offset:17408
	ds_write_b64 v235, v[54:55] offset:26112
	ds_write_b64 v235, v[52:53] offset:34816
	ds_write_b64 v235, v[64:65] offset:43520
	ds_write_b64 v235, v[60:61] offset:52224
	ds_write_b64 v235, v[58:59] offset:60928
	s_cbranch_scc1 .LBB0_944
	s_waitcnt lgkmcnt(0)
	s_barrier
	s_mov_b32 s0, 0
	s_mov_b64 s[8:9], -1
	ds_read2st64_b64 v[208:211], v139 offset0:1 offset1:2
	ds_read2st64_b64 v[204:207], v139 offset0:3 offset1:4
	ds_read2st64_b64 v[200:203], v139 offset0:5 offset1:6
	ds_read2st64_b64 v[196:199], v139 offset0:7 offset1:8
	ds_read2st64_b64 v[192:195], v139 offset0:9 offset1:10
	ds_read2st64_b64 v[188:191], v139 offset0:11 offset1:12
	ds_read2st64_b64 v[184:187], v139 offset0:13 offset1:14
	ds_read_b64 v[232:233], v139 offset:7680
.LBB0_946:
	v_add_u32_e32 v37, s0, v140
	v_lshrrev_b32_e32 v138, 6, v37
	v_mad_u32_u24 v176, v138, s77, v142
	ds_read_b64 v[0:1], v176 offset:0
	ds_read_b64 v[2:3], v176 offset:4352
	ds_read_b64 v[4:5], v176 offset:544
	ds_read_b64 v[6:7], v176 offset:4896
	ds_read_b64 v[8:9], v176 offset:1088
	ds_read_b64 v[10:11], v176 offset:5440
	ds_read_b64 v[12:13], v176 offset:1632
	ds_read_b64 v[14:15], v176 offset:5984
	ds_read_b64 v[16:17], v176 offset:2176
	ds_read_b64 v[18:19], v176 offset:6528
	ds_read_b64 v[20:21], v176 offset:2720
	ds_read_b64 v[22:23], v176 offset:7072
	ds_read_b64 v[24:25], v176 offset:3264
	ds_read_b64 v[26:27], v176 offset:7616
	ds_read_b64 v[28:29], v176 offset:3808
	ds_read_b64 v[30:31], v176 offset:8160
	s_cmp_eq_u32 s0, 0
	s_movk_i32 s0, 0x200
	s_mov_b64 s[8:9], 0
	s_waitcnt lgkmcnt(14)
	v_pk_add_f32 v[32:33], v[0:1], v[2:3]
	s_waitcnt lgkmcnt(12)
	v_pk_add_f32 v[34:35], v[4:5], v[6:7]
	s_waitcnt lgkmcnt(10)
	v_pk_add_f32 v[38:39], v[8:9], v[10:11]
	s_waitcnt lgkmcnt(8)
	v_pk_add_f32 v[40:41], v[12:13], v[14:15]
	v_pk_add_f32 v[0:1], v[0:1], v[2:3] neg_lo:[0,1] neg_hi:[0,1]
	v_pk_add_f32 v[6:7], v[4:5], v[6:7] neg_lo:[0,1] neg_hi:[0,1]
	v_pk_add_f32 v[8:9], v[8:9], v[10:11] neg_lo:[0,1] neg_hi:[0,1]
	v_pk_add_f32 v[14:15], v[12:13], v[14:15] neg_lo:[0,1] neg_hi:[0,1]
	s_waitcnt lgkmcnt(6)
	v_pk_add_f32 v[12:13], v[16:17], v[18:19]
	s_waitcnt lgkmcnt(4)
	v_pk_add_f32 v[10:11], v[20:21], v[22:23]
	s_waitcnt lgkmcnt(2)
	v_pk_add_f32 v[4:5], v[24:25], v[26:27]
	s_waitcnt lgkmcnt(0)
; #define LAS __attribute__((address_space(3)))
; template <bool INV> __device__ __forceinline__ void dft16(f32x2 (&x)[16]) {
; #pragma unroll
;     for (int b = 0; b < 4; ++b) r4<INV>(x[b], x[4 + b], x[8 + b], x[12 + b]);
;     const float sg = INV ? -1.f : 1.f;
;     const f32x2 W1 = {0.92387953251f, -0.38268343236f * sg}, W2 = {0.70710678118f, -0.70710678118f * sg}, W3 = {0.38268343236f, -0.92387953251f * sg},
;                 W4 = {0.f, -1.f * sg}, W6 = {-0.70710678118f, -0.70710678118f * sg}, W9 = {-0.92387953251f, 0.38268343236f * sg};
;     x[5] = cmul(x[5], W1); x[9] = cmul(x[9], W2); x[13] = cmul(x[13], W3);
;     x[6] = cmul(x[6], W2); x[10] = cmul(x[10], W4); x[14] = cmul(x[14], W6);
;     x[7] = cmul(x[7], W3); x[11] = cmul(x[11], W6); x[15] = cmul(x[15], W9);
; #pragma unroll
;     for (int c = 0; c < 4; ++c) r4<INV>(x[4 * c], x[4 * c + 1], x[4 * c + 2], x[4 * c + 3]);
; }
; template <bool INV> __device__ __forceinline__ void bfly16(f32x2 (&x)[16], const LAS f32x2* TH, const LAS f32x2* TL, int tw) {
;     f32x2 W = tw32k(TH, TL, tw); if (INV) W.y = -W.y;
;     if (INV) { f32x2 p = W;
; #pragma unroll
;         for (int q = 1; q < 16; ++q) { x[q] = cmul(x[q], p); if (q < 15) p = cmul(p, W); } }
;     dft16<INV>(x);
;     if (!INV) { f32x2 p = W;
; #pragma unroll
;         for (int r = 1; r < 16; ++r) { x[4 * (r & 3) + (r >> 2)] = cmul(x[4 * (r & 3) + (r >> 2)], p); if (r < 15) p = cmul(p, W); } }
; }
; template <bool INV> __device__ __forceinline__ void bfly16_tab(f32x2 (&x)[16], const LAS f32x2* T, int tstride, int j) {
;     if (INV) {
; #pragma unroll
;         for (int q = 1; q < 16; ++q) { f32x2 p = T[q * tstride + j]; p.y = -p.y; x[q] = cmul(x[q], p); } }
;     dft16<INV>(x);
;     if (!INV) {
; #pragma unroll
;         for (int r = 1; r < 16; ++r) { const f32x2 p = T[r * tstride + j]; x[4 * (r & 3) + (r >> 2)] = cmul(x[4 * (r & 3) + (r >> 2)], p); } }
; }
; template <bool INV> __device__ __forceinline__ void pass16_s64(LAS f32x2* X, const LAS f32x2* TH, int base, int j) {
;     f32x2 x[16];
; #pragma unroll
;     for (int q = 0; q < 16; ++q) x[q] = X[base + q * 68];
;     bfly16_tab<INV>(x, TH - 2048, 64, j);
; #pragma unroll
;     for (int c = 0; c < 4; ++c)
; #pragma unroll
;         for (int d = 0; d < 4; ++d) X[base + (c + 4 * d) * 68] = x[4 * c + d];
; }
	v_pk_add_f32 v[2:3], v[28:29], v[30:31]
	v_pk_add_f32 v[18:19], v[16:17], v[18:19] neg_lo:[0,1] neg_hi:[0,1]
	v_pk_add_f32 v[22:23], v[20:21], v[22:23] neg_lo:[0,1] neg_hi:[0,1]
	v_pk_add_f32 v[24:25], v[24:25], v[26:27] neg_lo:[0,1] neg_hi:[0,1]
	v_pk_add_f32 v[28:29], v[28:29], v[30:31] neg_lo:[0,1] neg_hi:[0,1]
	v_pk_add_f32 v[30:31], v[32:33], v[12:13]
	v_pk_add_f32 v[26:27], v[34:35], v[10:11]
	v_pk_add_f32 v[20:21], v[38:39], v[4:5]
	v_pk_add_f32 v[16:17], v[40:41], v[2:3]
	v_pk_add_f32 v[32:33], v[32:33], v[12:13] neg_lo:[0,1] neg_hi:[0,1]
	v_pk_add_f32 v[10:11], v[34:35], v[10:11] neg_lo:[0,1] neg_hi:[0,1]
	v_pk_add_f32 v[38:39], v[38:39], v[4:5] neg_lo:[0,1] neg_hi:[0,1]
	v_pk_add_f32 v[40:41], v[40:41], v[2:3] neg_lo:[0,1] neg_hi:[0,1]
	v_pk_add_f32 v[2:3], v[0:1], v[18:19] op_sel:[0,1] op_sel_hi:[1,0] neg_hi:[0,1]
	v_pk_add_f32 v[4:5], v[6:7], v[22:23] op_sel:[0,1] op_sel_hi:[1,0] neg_hi:[0,1]
	v_pk_add_f32 v[34:35], v[8:9], v[24:25] op_sel:[0,1] op_sel_hi:[1,0] neg_hi:[0,1]
	v_pk_add_f32 v[12:13], v[14:15], v[28:29] op_sel:[0,1] op_sel_hi:[1,0] neg_hi:[0,1]
	v_pk_add_f32 v[0:1], v[0:1], v[18:19] op_sel:[0,1] op_sel_hi:[1,0] neg_lo:[0,1]
	v_pk_add_f32 v[22:23], v[6:7], v[22:23] op_sel:[0,1] op_sel_hi:[1,0] neg_lo:[0,1]
	v_pk_add_f32 v[24:25], v[8:9], v[24:25] op_sel:[0,1] op_sel_hi:[1,0] neg_lo:[0,1]
	v_pk_add_f32 v[14:15], v[14:15], v[28:29] op_sel:[0,1] op_sel_hi:[1,0] neg_lo:[0,1]
	v_pk_add_f32 v[28:29], v[30:31], v[20:21]
	v_pk_mul_f32 v[8:9], v[4:5], s[70:71] op_sel_hi:[1,0]
	v_pk_mul_f32 v[6:7], v[10:11], s[72:73] op_sel_hi:[1,0]
	v_pk_mul_f32 v[18:19], v[22:23], s[64:65] op_sel_hi:[1,0]
	v_pk_add_f32 v[30:31], v[30:31], v[20:21] neg_lo:[0,1] neg_hi:[0,1]
	v_pk_fma_f32 v[4:5], v[4:5], s[44:45], v[8:9] op_sel:[0,0,1] op_sel_hi:[1,0,0] neg_lo:[0,0,1]
	v_pk_fma_f32 v[10:11], v[10:11], s[76:77], v[6:7] op_sel:[0,0,1] op_sel_hi:[1,0,0] neg_lo:[0,0,1]
	v_pk_fma_f32 v[18:19], v[22:23], s[82:83], v[18:19] op_sel:[0,0,1] op_sel_hi:[1,0,0] neg_lo:[0,0,1]
	v_pk_add_f32 v[22:23], v[26:27], v[16:17]
	v_pk_fma_f32 v[6:7], v[34:35], s[72:73], v[2:3] op_sel:[0,0,1] op_sel_hi:[1,0,0] neg_hi:[0,0,1]
	v_pk_add_f32 v[8:9], v[32:33], v[38:39] op_sel:[0,1] op_sel_hi:[1,0] neg_hi:[0,1]
	v_pk_fma_f32 v[20:21], v[24:25], s[72:73], v[0:1] op_sel:[0,0,1] op_sel_hi:[1,0,0] neg_hi:[0,0,1]
	v_pk_add_f32 v[26:27], v[26:27], v[16:17] neg_lo:[0,1] neg_hi:[0,1]
	v_pk_fma_f32 v[6:7], v[34:35], s[76:77], v[6:7] op_sel:[0,0,1] op_sel_hi:[1,0,0] neg_lo:[0,0,1]
	v_pk_add_f32 v[32:33], v[32:33], v[38:39] op_sel:[0,1] op_sel_hi:[1,0] neg_lo:[0,1]
	v_pk_fma_f32 v[24:25], v[24:25], s[72:73], v[20:21] op_sel:[0,0,1] op_sel_hi:[1,0,0] neg_lo:[0,0,1]
	v_pk_add_f32 v[20:21], v[28:29], v[22:23]
	v_pk_fma_f32 v[2:3], v[2:3], s[100:101], v[6:7] op_sel_hi:[1,0,1] neg_lo:[0,0,1] neg_hi:[0,0,1]
	v_pk_fma_f32 v[38:39], v[40:41], s[72:73], v[10:11] op_sel:[0,0,1] op_sel_hi:[1,0,0] neg_hi:[0,0,1]
	v_pk_fma_f32 v[0:1], v[0:1], s[100:101], v[24:25] op_sel_hi:[1,0,1] neg_lo:[0,0,1] neg_hi:[0,0,1]
	v_pk_add_f32 v[22:23], v[28:29], v[22:23] neg_lo:[0,1] neg_hi:[0,1]
	v_pk_fma_f32 v[28:29], v[12:13], s[64:65], v[4:5] op_sel:[0,0,1] op_sel_hi:[1,0,0] neg_hi:[0,0,1]
	v_pk_fma_f32 v[40:41], v[40:41], s[72:73], v[38:39] op_sel:[0,0,1] op_sel_hi:[1,0,0] neg_lo:[0,0,1]
	v_pk_fma_f32 v[38:39], v[14:15], s[82:83], v[18:19] op_sel:[0,0,1] op_sel_hi:[1,0,0] neg_hi:[0,0,1]
	v_pk_add_f32 v[34:35], v[30:31], v[26:27] op_sel:[0,1] op_sel_hi:[1,0] neg_hi:[0,1]
	v_pk_fma_f32 v[12:13], v[12:13], s[82:83], v[28:29] op_sel:[0,0,1] op_sel_hi:[1,0,0] neg_lo:[0,0,1]
	v_pk_fma_f32 v[10:11], v[10:11], s[100:101], v[40:41] op_sel_hi:[1,0,1] neg_lo:[0,0,1] neg_hi:[0,0,1]
	v_pk_fma_f32 v[38:39], v[14:15], s[64:65], v[38:39] op_sel:[0,0,1] op_sel_hi:[1,0,0] neg_lo:[0,0,1]
	v_pk_add_f32 v[30:31], v[30:31], v[26:27] op_sel:[0,1] op_sel_hi:[1,0] neg_lo:[0,1]
	v_pk_fma_f32 v[4:5], v[4:5], s[100:101], v[12:13] op_sel_hi:[1,0,1] neg_lo:[0,0,1] neg_hi:[0,0,1]
	v_pk_add_f32 v[26:27], v[8:9], v[40:41]
	v_pk_fma_f32 v[18:19], v[18:19], s[100:101], v[38:39] op_sel_hi:[1,0,1] neg_lo:[0,0,1] neg_hi:[0,0,1]
	v_pk_add_f32 v[14:15], v[6:7], v[12:13]
	v_pk_add_f32 v[8:9], v[8:9], v[40:41] neg_lo:[0,1] neg_hi:[0,1]
	v_pk_add_f32 v[40:41], v[24:25], v[38:39]
	v_pk_add_f32 v[12:13], v[6:7], v[12:13] neg_lo:[0,1] neg_hi:[0,1]
	v_pk_add_f32 v[6:7], v[32:33], v[10:11] op_sel:[0,1] op_sel_hi:[1,0] neg_hi:[0,1]
	v_pk_add_f32 v[38:39], v[24:25], v[38:39] neg_lo:[0,1] neg_hi:[0,1]
	v_pk_add_f32 v[24:25], v[2:3], v[4:5] op_sel:[0,1] op_sel_hi:[1,0] neg_hi:[0,1]
	v_pk_add_f32 v[10:11], v[32:33], v[10:11] op_sel:[0,1] op_sel_hi:[1,0] neg_lo:[0,1]
	v_pk_add_f32 v[32:33], v[0:1], v[18:19] op_sel:[0,1] op_sel_hi:[1,0] neg_hi:[0,1]
	v_pk_add_f32 v[4:5], v[2:3], v[4:5] op_sel:[0,1] op_sel_hi:[1,0] neg_lo:[0,1]
	v_pk_add_f32 v[18:19], v[0:1], v[18:19] op_sel:[0,1] op_sel_hi:[1,0] neg_lo:[0,1]
	v_pk_mul_f32 v[0:1], v[14:15], v[208:209] op_sel:[0,1] op_sel_hi:[1,1]
	v_pk_mul_f32 v[2:3], v[26:27], v[210:211] op_sel:[0,1] op_sel_hi:[1,1]
	v_pk_fma_f32 v[14:15], v[14:15], v[208:209], v[0:1] op_sel:[0,0,1] op_sel_hi:[1,0,0] neg_lo:[0,0,1]
	v_pk_mul_f32 v[0:1], v[40:41], v[204:205] op_sel:[0,1] op_sel_hi:[1,1]
	v_pk_fma_f32 v[2:3], v[26:27], v[210:211], v[2:3] op_sel:[0,0,1] op_sel_hi:[1,0,0] neg_lo:[0,0,1]
	v_pk_mul_f32 v[26:27], v[34:35], v[206:207] op_sel:[0,1] op_sel_hi:[1,1]
	v_pk_fma_f32 v[40:41], v[40:41], v[204:205], v[0:1] op_sel:[0,0,1] op_sel_hi:[1,0,0] neg_lo:[0,0,1]
	v_pk_mul_f32 v[0:1], v[24:25], v[200:201] op_sel:[0,1] op_sel_hi:[1,1]
	v_pk_fma_f32 v[34:35], v[34:35], v[206:207], v[26:27] op_sel:[0,0,1] op_sel_hi:[1,0,0] neg_lo:[0,0,1]
; #define LAS __attribute__((address_space(3)))
; __device__ __forceinline__ f32x2 cmul(f32x2 a, f32x2 b) { return (f32x2){a.x * b.x - a.y * b.y, a.x * b.y + a.y * b.x}; }
; template <bool INV> __device__ __forceinline__ void bfly16_tab(f32x2 (&x)[16], const LAS f32x2* T, int tstride, int j) {
;     if (INV) {
; #pragma unroll
;         for (int q = 1; q < 16; ++q) { f32x2 p = T[q * tstride + j]; p.y = -p.y; x[q] = cmul(x[q], p); } }
;     dft16<INV>(x);
;     if (!INV) {
; #pragma unroll
;         for (int r = 1; r < 16; ++r) { const f32x2 p = T[r * tstride + j]; x[4 * (r & 3) + (r >> 2)] = cmul(x[4 * (r & 3) + (r >> 2)], p); } }
; }
; template <bool INV> __device__ __forceinline__ void pass16_s4(LAS f32x2* X, const LAS f32x2* TH, const LAS f32x2* TL, int tid) {
; #pragma unroll 1
;     for (int s = 0; s < 2; ++s) {
;         const int b = tid + NTHR * s, blk = b >> 2, jj = b & 3;
;         LAS f32x2* P = X + blk * 68 + jj;
;         f32x2 x[16];
; #pragma unroll
;         for (int q = 0; q < 16; ++q) x[q] = P[4 * q];
;         bfly16_tab<INV>(x, TH - 1024, 4, jj);
; #pragma unroll
;         for (int c = 0; c < 4; ++c)
; #pragma unroll
;             for (int d = 0; d < 4; ++d) P[4 * (c + 4 * d)] = x[4 * c + d];
;     }
; }
	v_pk_mul_f32 v[26:27], v[6:7], v[202:203] op_sel:[0,1] op_sel_hi:[1,1]
	v_pk_fma_f32 v[0:1], v[24:25], v[200:201], v[0:1] op_sel:[0,0,1] op_sel_hi:[1,0,0] neg_lo:[0,0,1]
	v_pk_mul_f32 v[24:25], v[32:33], v[196:197] op_sel:[0,1] op_sel_hi:[1,1]
	v_pk_fma_f32 v[6:7], v[6:7], v[202:203], v[26:27] op_sel:[0,0,1] op_sel_hi:[1,0,0] neg_lo:[0,0,1]
	v_pk_mul_f32 v[26:27], v[22:23], v[198:199] op_sel:[0,1] op_sel_hi:[1,1]
	v_pk_fma_f32 v[24:25], v[32:33], v[196:197], v[24:25] op_sel:[0,0,1] op_sel_hi:[1,0,0] neg_lo:[0,0,1]
	v_pk_mul_f32 v[32:33], v[12:13], v[192:193] op_sel:[0,1] op_sel_hi:[1,1]
	v_pk_fma_f32 v[26:27], v[22:23], v[198:199], v[26:27] op_sel:[0,0,1] op_sel_hi:[1,0,0] neg_lo:[0,0,1]
	v_pk_mul_f32 v[22:23], v[8:9], v[194:195] op_sel:[0,1] op_sel_hi:[1,1]
	v_pk_fma_f32 v[12:13], v[12:13], v[192:193], v[32:33] op_sel:[0,0,1] op_sel_hi:[1,0,0] neg_lo:[0,0,1]
	v_pk_mul_f32 v[32:33], v[38:39], v[188:189] op_sel:[0,1] op_sel_hi:[1,1]
	v_pk_fma_f32 v[22:23], v[8:9], v[194:195], v[22:23] op_sel:[0,0,1] op_sel_hi:[1,0,0] neg_lo:[0,0,1]
	v_pk_mul_f32 v[8:9], v[30:31], v[190:191] op_sel:[0,1] op_sel_hi:[1,1]
	v_pk_fma_f32 v[32:33], v[38:39], v[188:189], v[32:33] op_sel:[0,0,1] op_sel_hi:[1,0,0] neg_lo:[0,0,1]
	v_pk_mul_f32 v[38:39], v[4:5], v[184:185] op_sel:[0,1] op_sel_hi:[1,1]
	v_pk_fma_f32 v[30:31], v[30:31], v[190:191], v[8:9] op_sel:[0,0,1] op_sel_hi:[1,0,0] neg_lo:[0,0,1]
	v_pk_mul_f32 v[8:9], v[10:11], v[186:187] op_sel:[0,1] op_sel_hi:[1,1]
	v_pk_fma_f32 v[38:39], v[4:5], v[184:185], v[38:39] op_sel:[0,0,1] op_sel_hi:[1,0,0] neg_lo:[0,0,1]
	v_pk_mul_f32 v[4:5], v[18:19], v[232:233] op_sel:[0,1] op_sel_hi:[1,1]
	v_pk_fma_f32 v[8:9], v[10:11], v[186:187], v[8:9] op_sel:[0,0,1] op_sel_hi:[1,0,0] neg_lo:[0,0,1]
	v_pk_fma_f32 v[18:19], v[18:19], v[232:233], v[4:5] op_sel:[0,0,1] op_sel_hi:[1,0,0] neg_lo:[0,0,1]
	ds_write_b64 v176, v[20:21] offset:0
	ds_write_b64 v176, v[14:15] offset:544
	ds_write_b64 v176, v[2:3] offset:1088
	ds_write_b64 v176, v[40:41] offset:1632
	ds_write_b64 v176, v[34:35] offset:2176
	ds_write_b64 v176, v[0:1] offset:2720
	ds_write_b64 v176, v[6:7] offset:3264
	ds_write_b64 v176, v[24:25] offset:3808
	ds_write_b64 v176, v[26:27] offset:4352
	ds_write_b64 v176, v[12:13] offset:4896
	ds_write_b64 v176, v[22:23] offset:5440
	ds_write_b64 v176, v[32:33] offset:5984
	ds_write_b64 v176, v[30:31] offset:6528
	ds_write_b64 v176, v[38:39] offset:7072
	ds_write_b64 v176, v[8:9] offset:7616
	ds_write_b64 v176, v[18:19] offset:8160
	s_cbranch_scc1 .LBB0_946
	s_waitcnt lgkmcnt(0)
	s_barrier
	s_mov_b32 s0, 0
	s_mov_b64 s[8:9], -1
	ds_read2_b64 v[232:235], v141 offset0:4 offset1:8
	ds_read2_b64 v[208:211], v141 offset0:12 offset1:16
	ds_read2_b64 v[204:207], v141 offset0:20 offset1:24
	ds_read2_b64 v[200:203], v141 offset0:28 offset1:32
	ds_read2_b64 v[196:199], v141 offset0:36 offset1:40
	ds_read2_b64 v[192:195], v141 offset0:44 offset1:48
	ds_read2_b64 v[188:191], v141 offset0:52 offset1:56
	ds_read_b64 v[186:187], v141 offset:480
.LBB0_948:
	v_add_u32_e32 v37, s0, v140
	v_lshrrev_b32_e32 v138, 2, v37
	v_mad_u32_u24 v176, v138, s43, v144
	ds_read_b64 v[0:1], v176 offset:0
	ds_read_b64 v[2:3], v176 offset:256
	ds_read_b64 v[4:5], v176 offset:32
	ds_read_b64 v[6:7], v176 offset:288
	ds_read_b64 v[8:9], v176 offset:64
	ds_read_b64 v[10:11], v176 offset:320
	ds_read_b64 v[12:13], v176 offset:96
	ds_read_b64 v[14:15], v176 offset:352
	ds_read_b64 v[16:17], v176 offset:128
	ds_read_b64 v[18:19], v176 offset:384
	ds_read_b64 v[20:21], v176 offset:160
	ds_read_b64 v[22:23], v176 offset:416
	ds_read_b64 v[24:25], v176 offset:192
	ds_read_b64 v[26:27], v176 offset:448
	ds_read_b64 v[28:29], v176 offset:224
	ds_read_b64 v[30:31], v176 offset:480
	s_cmp_eq_u32 s0, 0
	s_movk_i32 s0, 0x200
	s_mov_b64 s[8:9], 0
	s_waitcnt lgkmcnt(14)
	v_pk_add_f32 v[32:33], v[0:1], v[2:3]
	s_waitcnt lgkmcnt(12)
	v_pk_add_f32 v[34:35], v[4:5], v[6:7]
	s_waitcnt lgkmcnt(10)
	v_pk_add_f32 v[38:39], v[8:9], v[10:11]
	s_waitcnt lgkmcnt(8)
	v_pk_add_f32 v[40:41], v[12:13], v[14:15]
	v_pk_add_f32 v[0:1], v[0:1], v[2:3] neg_lo:[0,1] neg_hi:[0,1]
	v_pk_add_f32 v[4:5], v[4:5], v[6:7] neg_lo:[0,1] neg_hi:[0,1]
	v_pk_add_f32 v[10:11], v[8:9], v[10:11] neg_lo:[0,1] neg_hi:[0,1]
	v_pk_add_f32 v[12:13], v[12:13], v[14:15] neg_lo:[0,1] neg_hi:[0,1]
	s_waitcnt lgkmcnt(6)
	v_pk_add_f32 v[14:15], v[16:17], v[18:19]
	s_waitcnt lgkmcnt(4)
	v_pk_add_f32 v[8:9], v[20:21], v[22:23]
	s_waitcnt lgkmcnt(2)
	v_pk_add_f32 v[6:7], v[24:25], v[26:27]
	s_waitcnt lgkmcnt(0)
; template <bool INV> __device__ __forceinline__ void dft16(f32x2 (&x)[16]) {
; #pragma unroll
;     for (int b = 0; b < 4; ++b) r4<INV>(x[b], x[4 + b], x[8 + b], x[12 + b]);
;     const float sg = INV ? -1.f : 1.f;
;     const f32x2 W1 = {0.92387953251f, -0.38268343236f * sg}, W2 = {0.70710678118f, -0.70710678118f * sg}, W3 = {0.38268343236f, -0.92387953251f * sg},
;                 W4 = {0.f, -1.f * sg}, W6 = {-0.70710678118f, -0.70710678118f * sg}, W9 = {-0.92387953251f, 0.38268343236f * sg};
;     x[5] = cmul(x[5], W1); x[9] = cmul(x[9], W2); x[13] = cmul(x[13], W3);
;     x[6] = cmul(x[6], W2); x[10] = cmul(x[10], W4); x[14] = cmul(x[14], W6);
;     x[7] = cmul(x[7], W3); x[11] = cmul(x[11], W6); x[15] = cmul(x[15], W9);
; #pragma unroll
;     for (int c = 0; c < 4; ++c) r4<INV>(x[4 * c], x[4 * c + 1], x[4 * c + 2], x[4 * c + 3]);
; }
; template <bool INV> __device__ __forceinline__ void bfly16(f32x2 (&x)[16], const LAS f32x2* TH, const LAS f32x2* TL, int tw) {
;     f32x2 W = tw32k(TH, TL, tw); if (INV) W.y = -W.y;
;     if (INV) { f32x2 p = W;
; #pragma unroll
;         for (int q = 1; q < 16; ++q) { x[q] = cmul(x[q], p); if (q < 15) p = cmul(p, W); } }
;     dft16<INV>(x);
;     if (!INV) { f32x2 p = W;
; #pragma unroll
;         for (int r = 1; r < 16; ++r) { x[4 * (r & 3) + (r >> 2)] = cmul(x[4 * (r & 3) + (r >> 2)], p); if (r < 15) p = cmul(p, W); } }
; }
; template <bool INV> __device__ __forceinline__ void bfly16_tab(f32x2 (&x)[16], const LAS f32x2* T, int tstride, int j) {
;     if (INV) {
; #pragma unroll
;         for (int q = 1; q < 16; ++q) { f32x2 p = T[q * tstride + j]; p.y = -p.y; x[q] = cmul(x[q], p); } }
;     dft16<INV>(x);
;     if (!INV) {
; #pragma unroll
;         for (int r = 1; r < 16; ++r) { const f32x2 p = T[r * tstride + j]; x[4 * (r & 3) + (r >> 2)] = cmul(x[4 * (r & 3) + (r >> 2)], p); } }
; }
; template <bool INV> __device__ __forceinline__ void pass16_s4(LAS f32x2* X, const LAS f32x2* TH, const LAS f32x2* TL, int tid) {
; #pragma unroll 1
;     for (int s = 0; s < 2; ++s) {
;         const int b = tid + NTHR * s, blk = b >> 2, jj = b & 3;
;         LAS f32x2* P = X + blk * 68 + jj;
;         f32x2 x[16];
; #pragma unroll
;         for (int q = 0; q < 16; ++q) x[q] = P[4 * q];
;         bfly16_tab<INV>(x, TH - 1024, 4, jj);
; #pragma unroll
;         for (int c = 0; c < 4; ++c)
; #pragma unroll
	v_pk_add_f32 v[2:3], v[28:29], v[30:31]
	v_pk_add_f32 v[18:19], v[16:17], v[18:19] neg_lo:[0,1] neg_hi:[0,1]
	v_pk_add_f32 v[20:21], v[20:21], v[22:23] neg_lo:[0,1] neg_hi:[0,1]
	v_pk_add_f32 v[26:27], v[24:25], v[26:27] neg_lo:[0,1] neg_hi:[0,1]
	v_pk_add_f32 v[28:29], v[28:29], v[30:31] neg_lo:[0,1] neg_hi:[0,1]
	v_pk_add_f32 v[30:31], v[32:33], v[14:15]
	v_pk_add_f32 v[24:25], v[34:35], v[8:9]
	v_pk_add_f32 v[22:23], v[38:39], v[6:7]
	v_pk_add_f32 v[16:17], v[40:41], v[2:3]
	v_pk_add_f32 v[14:15], v[32:33], v[14:15] neg_lo:[0,1] neg_hi:[0,1]
	v_pk_add_f32 v[34:35], v[34:35], v[8:9] neg_lo:[0,1] neg_hi:[0,1]
	v_pk_add_f32 v[6:7], v[38:39], v[6:7] neg_lo:[0,1] neg_hi:[0,1]
	v_pk_add_f32 v[40:41], v[40:41], v[2:3] neg_lo:[0,1] neg_hi:[0,1]
	v_pk_add_f32 v[2:3], v[0:1], v[18:19] op_sel:[0,1] op_sel_hi:[1,0] neg_hi:[0,1]
	v_pk_add_f32 v[38:39], v[4:5], v[20:21] op_sel:[0,1] op_sel_hi:[1,0] neg_hi:[0,1]
	v_pk_add_f32 v[8:9], v[10:11], v[26:27] op_sel:[0,1] op_sel_hi:[1,0] neg_hi:[0,1]
	v_pk_add_f32 v[32:33], v[12:13], v[28:29] op_sel:[0,1] op_sel_hi:[1,0] neg_hi:[0,1]
	v_pk_add_f32 v[18:19], v[0:1], v[18:19] op_sel:[0,1] op_sel_hi:[1,0] neg_lo:[0,1]
	v_pk_add_f32 v[4:5], v[4:5], v[20:21] op_sel:[0,1] op_sel_hi:[1,0] neg_lo:[0,1]
	v_pk_add_f32 v[26:27], v[10:11], v[26:27] op_sel:[0,1] op_sel_hi:[1,0] neg_lo:[0,1]
	v_pk_add_f32 v[28:29], v[12:13], v[28:29] op_sel:[0,1] op_sel_hi:[1,0] neg_lo:[0,1]
	v_pk_add_f32 v[12:13], v[30:31], v[22:23]
	v_pk_mul_f32 v[10:11], v[38:39], s[70:71] op_sel_hi:[1,0]
	v_pk_mul_f32 v[20:21], v[34:35], s[72:73] op_sel_hi:[1,0]
	v_pk_mul_f32 v[0:1], v[4:5], s[64:65] op_sel_hi:[1,0]
	v_pk_add_f32 v[22:23], v[30:31], v[22:23] neg_lo:[0,1] neg_hi:[0,1]
	v_pk_fma_f32 v[10:11], v[38:39], s[44:45], v[10:11] op_sel:[0,0,1] op_sel_hi:[1,0,0] neg_lo:[0,0,1]
	v_pk_fma_f32 v[20:21], v[34:35], s[76:77], v[20:21] op_sel:[0,0,1] op_sel_hi:[1,0,0] neg_lo:[0,0,1]
	v_pk_fma_f32 v[4:5], v[4:5], s[82:83], v[0:1] op_sel:[0,0,1] op_sel_hi:[1,0,0] neg_lo:[0,0,1]
	v_pk_add_f32 v[0:1], v[24:25], v[16:17]
	v_pk_fma_f32 v[34:35], v[8:9], s[72:73], v[2:3] op_sel:[0,0,1] op_sel_hi:[1,0,0] neg_hi:[0,0,1]
	v_pk_add_f32 v[38:39], v[14:15], v[6:7] op_sel:[0,1] op_sel_hi:[1,0] neg_hi:[0,1]
	v_pk_fma_f32 v[30:31], v[26:27], s[72:73], v[18:19] op_sel:[0,0,1] op_sel_hi:[1,0,0] neg_hi:[0,0,1]
	v_pk_add_f32 v[24:25], v[24:25], v[16:17] neg_lo:[0,1] neg_hi:[0,1]
	v_pk_fma_f32 v[8:9], v[8:9], s[76:77], v[34:35] op_sel:[0,0,1] op_sel_hi:[1,0,0] neg_lo:[0,0,1]
	v_pk_add_f32 v[14:15], v[14:15], v[6:7] op_sel:[0,1] op_sel_hi:[1,0] neg_lo:[0,1]
	v_pk_fma_f32 v[26:27], v[26:27], s[72:73], v[30:31] op_sel:[0,0,1] op_sel_hi:[1,0,0] neg_lo:[0,0,1]
	v_pk_add_f32 v[30:31], v[12:13], v[0:1]
	v_pk_fma_f32 v[2:3], v[2:3], s[100:101], v[8:9] op_sel_hi:[1,0,1] neg_lo:[0,0,1] neg_hi:[0,0,1]
	v_pk_fma_f32 v[6:7], v[40:41], s[72:73], v[20:21] op_sel:[0,0,1] op_sel_hi:[1,0,0] neg_hi:[0,0,1]
	v_pk_fma_f32 v[18:19], v[18:19], s[100:101], v[26:27] op_sel_hi:[1,0,1] neg_lo:[0,0,1] neg_hi:[0,0,1]
	v_pk_add_f32 v[12:13], v[12:13], v[0:1] neg_lo:[0,1] neg_hi:[0,1]
	v_pk_fma_f32 v[0:1], v[32:33], s[64:65], v[10:11] op_sel:[0,0,1] op_sel_hi:[1,0,0] neg_hi:[0,0,1]
	v_pk_fma_f32 v[40:41], v[40:41], s[72:73], v[6:7] op_sel:[0,0,1] op_sel_hi:[1,0,0] neg_lo:[0,0,1]
	v_pk_fma_f32 v[6:7], v[28:29], s[82:83], v[4:5] op_sel:[0,0,1] op_sel_hi:[1,0,0] neg_hi:[0,0,1]
	v_pk_add_f32 v[34:35], v[22:23], v[24:25] op_sel:[0,1] op_sel_hi:[1,0] neg_hi:[0,1]
	v_pk_fma_f32 v[32:33], v[32:33], s[82:83], v[0:1] op_sel:[0,0,1] op_sel_hi:[1,0,0] neg_lo:[0,0,1]
	v_pk_fma_f32 v[20:21], v[20:21], s[100:101], v[40:41] op_sel_hi:[1,0,1] neg_lo:[0,0,1] neg_hi:[0,0,1]
	v_pk_fma_f32 v[28:29], v[28:29], s[64:65], v[6:7] op_sel:[0,0,1] op_sel_hi:[1,0,0] neg_lo:[0,0,1]
	v_pk_add_f32 v[24:25], v[22:23], v[24:25] op_sel:[0,1] op_sel_hi:[1,0] neg_lo:[0,1]
	v_pk_fma_f32 v[10:11], v[10:11], s[100:101], v[32:33] op_sel_hi:[1,0,1] neg_lo:[0,0,1] neg_hi:[0,0,1]
	v_pk_add_f32 v[22:23], v[38:39], v[40:41]
	v_pk_fma_f32 v[4:5], v[4:5], s[100:101], v[28:29] op_sel_hi:[1,0,1] neg_lo:[0,0,1] neg_hi:[0,0,1]
; #define LAS __attribute__((address_space(3)))
; __device__ __forceinline__ f32x2 cmul(f32x2 a, f32x2 b) { return (f32x2){a.x * b.x - a.y * b.y, a.x * b.y + a.y * b.x}; }
; template <bool INV> __device__ __forceinline__ void bfly16_tab(f32x2 (&x)[16], const LAS f32x2* T, int tstride, int j) {
;     if (INV) {
; #pragma unroll
;         for (int q = 1; q < 16; ++q) { f32x2 p = T[q * tstride + j]; p.y = -p.y; x[q] = cmul(x[q], p); } }
;     dft16<INV>(x);
;     if (!INV) {
; #pragma unroll
;         for (int r = 1; r < 16; ++r) { const f32x2 p = T[r * tstride + j]; x[4 * (r & 3) + (r >> 2)] = cmul(x[4 * (r & 3) + (r >> 2)], p); } }
; }
; template <bool INV> __device__ __forceinline__ void pass16_s4(LAS f32x2* X, const LAS f32x2* TH, const LAS f32x2* TL, int tid) {
; #pragma unroll 1
;     for (int s = 0; s < 2; ++s) {
;         const int b = tid + NTHR * s, blk = b >> 2, jj = b & 3;
;         LAS f32x2* P = X + blk * 68 + jj;
;         f32x2 x[16];
; #pragma unroll
;         for (int q = 0; q < 16; ++q) x[q] = P[4 * q];
;         bfly16_tab<INV>(x, TH - 1024, 4, jj);
; #pragma unroll
;         for (int c = 0; c < 4; ++c)
; #pragma unroll
;             for (int d = 0; d < 4; ++d) P[4 * (c + 4 * d)] = x[4 * c + d];
;     }
; }
	v_pk_add_f32 v[6:7], v[8:9], v[32:33]
	v_pk_add_f32 v[40:41], v[38:39], v[40:41] neg_lo:[0,1] neg_hi:[0,1]
	v_pk_add_f32 v[38:39], v[26:27], v[28:29]
	v_pk_add_f32 v[32:33], v[8:9], v[32:33] neg_lo:[0,1] neg_hi:[0,1]
	v_pk_add_f32 v[8:9], v[14:15], v[20:21] op_sel:[0,1] op_sel_hi:[1,0] neg_hi:[0,1]
	v_pk_add_f32 v[26:27], v[26:27], v[28:29] neg_lo:[0,1] neg_hi:[0,1]
	v_pk_add_f32 v[28:29], v[2:3], v[10:11] op_sel:[0,1] op_sel_hi:[1,0] neg_hi:[0,1]
	v_pk_add_f32 v[20:21], v[14:15], v[20:21] op_sel:[0,1] op_sel_hi:[1,0] neg_lo:[0,1]
	v_pk_add_f32 v[14:15], v[18:19], v[4:5] op_sel:[0,1] op_sel_hi:[1,0] neg_hi:[0,1]
	v_pk_add_f32 v[10:11], v[2:3], v[10:11] op_sel:[0,1] op_sel_hi:[1,0] neg_lo:[0,1]
	v_pk_add_f32 v[18:19], v[18:19], v[4:5] op_sel:[0,1] op_sel_hi:[1,0] neg_lo:[0,1]
	v_pk_mul_f32 v[4:5], v[6:7], v[232:233] op_sel:[0,1] op_sel_hi:[1,1]
	v_pk_mul_f32 v[2:3], v[22:23], v[234:235] op_sel:[0,1] op_sel_hi:[1,1]
	v_pk_fma_f32 v[6:7], v[6:7], v[232:233], v[4:5] op_sel:[0,0,1] op_sel_hi:[1,0,0] neg_lo:[0,0,1]
	v_pk_mul_f32 v[4:5], v[38:39], v[208:209] op_sel:[0,1] op_sel_hi:[1,1]
	v_pk_fma_f32 v[22:23], v[22:23], v[234:235], v[2:3] op_sel:[0,0,1] op_sel_hi:[1,0,0] neg_lo:[0,0,1]
	v_pk_mul_f32 v[2:3], v[34:35], v[210:211] op_sel:[0,1] op_sel_hi:[1,1]
	v_pk_fma_f32 v[4:5], v[38:39], v[208:209], v[4:5] op_sel:[0,0,1] op_sel_hi:[1,0,0] neg_lo:[0,0,1]
	v_pk_mul_f32 v[38:39], v[28:29], v[204:205] op_sel:[0,1] op_sel_hi:[1,1]
	v_pk_fma_f32 v[34:35], v[34:35], v[210:211], v[2:3] op_sel:[0,0,1] op_sel_hi:[1,0,0] neg_lo:[0,0,1]
	v_pk_mul_f32 v[2:3], v[8:9], v[206:207] op_sel:[0,1] op_sel_hi:[1,1]
	v_pk_fma_f32 v[28:29], v[28:29], v[204:205], v[38:39] op_sel:[0,0,1] op_sel_hi:[1,0,0] neg_lo:[0,0,1]
	v_pk_mul_f32 v[38:39], v[14:15], v[200:201] op_sel:[0,1] op_sel_hi:[1,1]
	v_pk_fma_f32 v[2:3], v[8:9], v[206:207], v[2:3] op_sel:[0,0,1] op_sel_hi:[1,0,0] neg_lo:[0,0,1]
	v_pk_mul_f32 v[8:9], v[12:13], v[202:203] op_sel:[0,1] op_sel_hi:[1,1]
	v_pk_fma_f32 v[14:15], v[14:15], v[200:201], v[38:39] op_sel:[0,0,1] op_sel_hi:[1,0,0] neg_lo:[0,0,1]
	v_pk_mul_f32 v[38:39], v[32:33], v[196:197] op_sel:[0,1] op_sel_hi:[1,1]
	v_pk_fma_f32 v[8:9], v[12:13], v[202:203], v[8:9] op_sel:[0,0,1] op_sel_hi:[1,0,0] neg_lo:[0,0,1]
	v_pk_mul_f32 v[12:13], v[40:41], v[198:199] op_sel:[0,1] op_sel_hi:[1,1]
	v_pk_fma_f32 v[38:39], v[32:33], v[196:197], v[38:39] op_sel:[0,0,1] op_sel_hi:[1,0,0] neg_lo:[0,0,1]
	v_pk_mul_f32 v[32:33], v[26:27], v[192:193] op_sel:[0,1] op_sel_hi:[1,1]
	v_pk_fma_f32 v[40:41], v[40:41], v[198:199], v[12:13] op_sel:[0,0,1] op_sel_hi:[1,0,0] neg_lo:[0,0,1]
	v_pk_mul_f32 v[12:13], v[24:25], v[194:195] op_sel:[0,1] op_sel_hi:[1,1]
	v_pk_fma_f32 v[32:33], v[26:27], v[192:193], v[32:33] op_sel:[0,0,1] op_sel_hi:[1,0,0] neg_lo:[0,0,1]
	v_pk_mul_f32 v[26:27], v[10:11], v[188:189] op_sel:[0,1] op_sel_hi:[1,1]
	v_pk_fma_f32 v[24:25], v[24:25], v[194:195], v[12:13] op_sel:[0,0,1] op_sel_hi:[1,0,0] neg_lo:[0,0,1]
	v_pk_mul_f32 v[12:13], v[20:21], v[190:191] op_sel:[0,1] op_sel_hi:[1,1]
	v_pk_fma_f32 v[26:27], v[10:11], v[188:189], v[26:27] op_sel:[0,0,1] op_sel_hi:[1,0,0] neg_lo:[0,0,1]
	v_pk_mul_f32 v[10:11], v[18:19], v[186:187] op_sel:[0,1] op_sel_hi:[1,1]
	v_pk_fma_f32 v[20:21], v[20:21], v[190:191], v[12:13] op_sel:[0,0,1] op_sel_hi:[1,0,0] neg_lo:[0,0,1]
	v_pk_fma_f32 v[18:19], v[18:19], v[186:187], v[10:11] op_sel:[0,0,1] op_sel_hi:[1,0,0] neg_lo:[0,0,1]
	ds_write_b64 v176, v[30:31] offset:0
	ds_write_b64 v176, v[6:7] offset:32
	ds_write_b64 v176, v[22:23] offset:64
	ds_write_b64 v176, v[4:5] offset:96
	ds_write_b64 v176, v[34:35] offset:128
	ds_write_b64 v176, v[28:29] offset:160
	ds_write_b64 v176, v[2:3] offset:192
	ds_write_b64 v176, v[14:15] offset:224
	ds_write_b64 v176, v[8:9] offset:256
	ds_write_b64 v176, v[38:39] offset:288
	ds_write_b64 v176, v[40:41] offset:320
	ds_write_b64 v176, v[32:33] offset:352
	ds_write_b64 v176, v[24:25] offset:384
	ds_write_b64 v176, v[26:27] offset:416
	ds_write_b64 v176, v[20:21] offset:448
	ds_write_b64 v176, v[18:19] offset:480
	s_cbranch_scc1 .LBB0_948
	s_waitcnt lgkmcnt(0)
	s_barrier
	s_mov_b32 s0, 0
	v_mov_b32_e32 v0, v36

; __global__ void __launch_bounds__(NTHR, 2) fwd_kernel(Args args) {
;     extern __shared__ __attribute__((aligned(16))) unsigned char lds[];
	.amdhsa_kernel _Z10fwd_kernel4Args
		.amdhsa_group_segment_fixed_size 0
		.amdhsa_private_segment_fixed_size 0
		.amdhsa_kernarg_size 480
		.amdhsa_user_sgpr_count 2
		.amdhsa_user_sgpr_dispatch_ptr 0
		.amdhsa_user_sgpr_queue_ptr 0
		.amdhsa_user_sgpr_kernarg_segment_ptr 1
		.amdhsa_user_sgpr_dispatch_id 0
		.amdhsa_user_sgpr_kernarg_preload_length 0
		.amdhsa_user_sgpr_kernarg_preload_offset 0
		.amdhsa_user_sgpr_private_segment_size 0
		.amdhsa_uses_dynamic_stack 0
		.amdhsa_enable_private_segment 0
		.amdhsa_system_sgpr_workgroup_id_x 1
		.amdhsa_system_sgpr_workgroup_id_y 0
		.amdhsa_system_sgpr_workgroup_id_z 0
		.amdhsa_system_sgpr_workgroup_info 0
		.amdhsa_system_vgpr_workitem_id 0
		.amdhsa_next_free_vgpr 256
		.amdhsa_next_free_sgpr 102
		.amdhsa_accum_offset 256
		.amdhsa_reserve_vcc 1
		.amdhsa_float_round_mode_32 0
		.amdhsa_float_round_mode_16_64 0
		.amdhsa_float_denorm_mode_32 3
		.amdhsa_float_denorm_mode_16_64 3
		.amdhsa_dx10_clamp 1
		.amdhsa_ieee_mode 1
		.amdhsa_fp16_overflow 0
		.amdhsa_tg_split 0
		.amdhsa_exception_fp_ieee_invalid_op 0
		.amdhsa_exception_fp_denorm_src 0
		.amdhsa_exception_fp_ieee_div_zero 0
		.amdhsa_exception_fp_ieee_overflow 0
		.amdhsa_exception_fp_ieee_underflow 0
		.amdhsa_exception_fp_ieee_inexact 0
		.amdhsa_exception_int_div_zero 0
	.end_amdhsa_kernel

; __global__ void __launch_bounds__(NTHR, 2) fwd_kernel(Args args) {
;     extern __shared__ __attribute__((aligned(16))) unsigned char lds[];
amdhsa.kernels:
  - .agpr_count:     0
    .args:
      - .offset:         0
        .size:           224
        .value_kind:     by_value
      - .offset:         224
        .size:           4
        .value_kind:     hidden_block_count_x
      - .offset:         228
        .size:           4
        .value_kind:     hidden_block_count_y
      - .offset:         232
        .size:           4
        .value_kind:     hidden_block_count_z
      - .offset:         236
        .size:           2
        .value_kind:     hidden_group_size_x
      - .offset:         238
        .size:           2
        .value_kind:     hidden_group_size_y
      - .offset:         240
        .size:           2
        .value_kind:     hidden_group_size_z
      - .offset:         242
        .size:           2
        .value_kind:     hidden_remainder_x
      - .offset:         244
        .size:           2
        .value_kind:     hidden_remainder_y
      - .offset:         246
        .size:           2
        .value_kind:     hidden_remainder_z
      - .offset:         264
        .size:           8
        .value_kind:     hidden_global_offset_x
      - .offset:         272
        .size:           8
        .value_kind:     hidden_global_offset_y
      - .offset:         280
        .size:           8
        .value_kind:     hidden_global_offset_z
      - .offset:         288
        .size:           2
        .value_kind:     hidden_grid_dims
      - .offset:         344
        .size:           4
        .value_kind:     hidden_dynamic_lds_size
    .group_segment_fixed_size: 0
    .kernarg_segment_align: 8
    .kernarg_segment_size: 480
    .language:       OpenCL C
    .language_version:
      - 2
      - 0
    .max_flat_workgroup_size: 512
    .name:           _Z10fwd_kernel4Args
    .private_segment_fixed_size: 0
    .sgpr_count:     108
    .sgpr_spill_count: 154
    .symbol:         _Z10fwd_kernel4Args.kd
    .uniform_work_group_size: 1
    .uses_dynamic_stack: false
    .vgpr_count:     256
    .vgpr_spill_count: 0
    .wavefront_size: 64
